# row/wave sums in phases 1,3,5,7,10: xor-1/2/4/8 butterfly steps via DPP moves instead of ds_bpermute round trips
# speedup vs baseline: 1.0051x; 1.0051x over previous
; DI unsigned pk2(float a, float b) { f32x2 v = {a, b}; bf16x2_t r = __builtin_convertvector(v, bf16x2_t); return __builtin_bit_cast(unsigned, r); }
; template <int MODE>
; DI void norm_rows(const Params& p) {
;     ...
;         for (int u = 0; u < 2; ++u) {
;             const int row = row0 + u * NGW < nrows ? row0 + u * NGW : row0;
;             if (MODE == 0) { if (row < NLAT) { src[u] = p.x + (size_t)row * DM; mb[u] = row >> 12; } else { src[u] = p.ctx + (size_t)(row - NLAT) * DM; mb[u] = 16; } }
;             else { src[u] = p.out + (size_t)row * DM; mb[u] = row >> 12; }
; #pragma unroll
;             for (int j = 0; j < 4; ++j) v[u][j] = *(const f32x4*)(src[u] + 4 * lane + 256 * j);
;         }
; #pragma unroll
;         for (int u = 0; u < 2; ++u) {
;             const int row = row0 + u * NGW;
;             if (row >= nrows) break;
;             s[u] = 0.f;
; #pragma unroll
;             for (int j = 0; j < 4; ++j) s[u] += (v[u][j].x * v[u][j].x + v[u][j].y * v[u][j].y) + (v[u][j].z * v[u][j].z + v[u][j].w * v[u][j].w);
;             const float rstd = rsqrtf(wave_sum(s[u]) * (1.f / DM) + EPS);
;             if (MODE == 2) {
;                 float* dst = p.out + (size_t)row * DM;
; #pragma unroll
;                 for (int j = 0; j < 4; ++j) *(f32x4*)(dst + 4 * lane + 256 * j) = v[u][j] * rstd * gn[j];
;             } else {
;                 const float* mrow = modp + (size_t)mb[u] * NMODC + (MODE == 0 ? 0 : 3072);
;                 bf16_t* dst = (bf16_t*)(p.ws + OFF_A) + (MODE == 0 ? (size_t)0 : (size_t)NLAT * 1024) + (size_t)row * DM;
; #pragma unroll
;                 for (int j = 0; j < 4; ++j) {
;                     const f32x4 sh = *(const f32x4*)(mrow + 4 * lane + 256 * j), scl = *(const f32x4*)(mrow + 1024 + 4 * lane + 256 * j);
;                     const f32x4 y = (v[u][j] * rstd * gn[j]) * (scl + 1.f) + sh;
;                     u32x2 o; o.x = pk2(y.x, y.y); o.y = pk2(y.z, y.w);
;                     *(u32x2*)(dst + 4 * lane + 256 * j) = o;
.LBB0_139:
	v_cmp_lt_i32_e32 vcc, s22, v16
	s_and_saveexec_b64 s[4:5], vcc
	s_xor_b64 s[4:5], exec, s[4:5]
	v_add_u32_e32 v18, 0xffff0000, v16
	v_mov_b32_e32 v19, v49
	v_lshlrev_b64 v[18:19], 12, v[18:19]
	v_lshl_add_u64 v[18:19], s[40:41], 0, v[18:19]
	s_or_saveexec_b64 s[4:5], s[4:5]
	v_mov_b64_e32 v[20:21], 0x60000
	v_ashrrev_i32_e32 v17, 31, v16
	s_xor_b64 exec, exec, s[4:5]
	v_lshlrev_b64 v[18:19], 12, v[16:17]
	v_ashrrev_i32_e32 v20, 12, v16
	v_lshl_add_u64 v[18:19], s[36:37], 0, v[18:19]
	v_mul_hi_i32_i24_e32 v21, 0x6000, v20
	v_mul_i32_i24_e32 v20, 0x6000, v20
	s_or_b64 exec, exec, s[4:5]
	v_lshl_add_u64 v[18:19], v[18:19], 0, v[48:49]
	global_load_dwordx4 v[44:47], v[18:19], off
	global_load_dwordx4 v[40:43], v[18:19], off offset:1024
	global_load_dwordx4 v[36:39], v[18:19], off offset:2048
	global_load_dwordx4 v[24:27], v[18:19], off offset:3072
	v_add_u32_e32 v52, s19, v16
	v_cmp_gt_i32_e32 vcc, s18, v52
	s_nop 1
	v_cndmask_b32_e32 v22, v16, v52, vcc
	v_cmp_lt_i32_e64 s[4:5], s22, v22
	s_and_saveexec_b64 s[38:39], s[4:5]
	s_xor_b64 s[4:5], exec, s[38:39]
	v_add_u32_e32 v18, 0xffff0000, v22
	v_mov_b32_e32 v19, v49
	v_lshlrev_b64 v[18:19], 12, v[18:19]
	v_lshl_add_u64 v[18:19], s[40:41], 0, v[18:19]
	s_or_saveexec_b64 s[4:5], s[4:5]
	v_mov_b64_e32 v[54:55], 0x60000
	s_xor_b64 exec, exec, s[4:5]
	v_ashrrev_i32_e32 v23, 31, v22
	v_lshlrev_b64 v[18:19], 12, v[22:23]
	v_ashrrev_i32_e32 v22, 12, v22
	v_lshl_add_u64 v[18:19], s[36:37], 0, v[18:19]
	v_mul_hi_i32_i24_e32 v55, 0x6000, v22
	v_mul_i32_i24_e32 v54, 0x6000, v22
	s_or_b64 exec, exec, s[4:5]
	v_lshl_add_u64 v[20:21], s[12:13], 0, v[20:21]
	v_lshl_add_u64 v[72:73], v[20:21], 0, v[48:49]
	v_add_co_u32_e64 v20, s[4:5], s24, v72
	s_waitcnt vmcnt(3)
	v_pk_mul_f32 v[22:23], v[44:45], v[44:45]
	v_addc_co_u32_e64 v21, s[4:5], 0, v73, s[4:5]
	global_load_dwordx4 v[64:67], v[72:73], off
	global_load_dwordx4 v[68:71], v[20:21], off
	v_pk_mul_f32 v[20:21], v[46:47], v[46:47]
	v_lshlrev_b64 v[74:75], 11, v[16:17]
	v_pk_mov_b32 v[28:29], v[22:23], v[20:21] op_sel:[1,0]
	v_mov_b32_e32 v23, v21
	v_pk_add_f32 v[20:21], v[28:29], v[22:23]
	s_waitcnt vmcnt(4)
	v_pk_mul_f32 v[22:23], v[42:43], v[42:43]
	v_pk_mul_f32 v[28:29], v[40:41], v[40:41]
	v_pk_add_f32 v[20:21], v[20:21], v[20:21] op_sel:[0,1] op_sel_hi:[1,0]
	v_pk_mov_b32 v[30:31], v[28:29], v[22:23] op_sel:[1,0]
	v_mov_b32_e32 v29, v23
	v_pk_add_f32 v[22:23], v[30:31], v[28:29]
	s_waitcnt vmcnt(2)
	v_mul_f32_e32 v28, v24, v24
	v_mul_f32_e32 v29, v25, v25
	v_pk_add_f32 v[22:23], v[22:23], v[22:23] op_sel:[0,1] op_sel_hi:[1,0]
	v_mov_b32_e32 v21, v28
	v_mov_b32_e32 v23, v29
	v_pk_add_f32 v[20:21], v[20:21], v[22:23]
	v_mul_f32_e32 v22, v37, v37
	v_mul_f32_e32 v28, v39, v39
	v_mul_f32_e32 v30, v26, v26
	v_mul_f32_e32 v31, v27, v27
	v_pk_fma_f32 v[22:23], v[36:37], v[36:37], v[22:23] op_sel_hi:[1,1,0]
	v_pk_fma_f32 v[28:29], v[38:39], v[38:39], v[28:29] op_sel_hi:[1,1,0]
	v_mov_b32_e32 v23, v30
	v_mov_b32_e32 v29, v31
	v_pk_add_f32 v[22:23], v[22:23], v[28:29]
	v_lshl_add_u64 v[18:19], v[18:19], 0, v[48:49]
	v_pk_add_f32 v[20:21], v[20:21], v[22:23]
	v_lshl_add_u64 v[74:75], v[50:51], 0, v[74:75]
	v_add_f32_e32 v20, v20, v21
	s_nop 1
	v_mov_b32_dpp v21, v20 quad_perm:[1,0,3,2] row_mask:0xf bank_mask:0xf
	global_load_dwordx4 v[32:35], v[18:19], off
	global_load_dwordx4 v[28:31], v[18:19], off offset:1024
	v_lshl_add_u64 v[76:77], v[72:73], 0, s[16:17]
	s_waitcnt lgkmcnt(0)
	v_add_f32_e32 v20, v20, v21
	s_nop 1
	v_mov_b32_dpp v21, v20 quad_perm:[2,3,0,1] row_mask:0xf bank_mask:0xf
	s_waitcnt lgkmcnt(0)
	v_add_f32_e32 v20, v20, v21
	s_nop 1
	v_mov_b32_dpp v21, v20 row_half_mirror row_mask:0xf bank_mask:0xf
	s_waitcnt lgkmcnt(0)
	v_add_f32_e32 v20, v20, v21
	s_nop 1
	v_mov_b32_dpp v21, v20 row_ror:8 row_mask:0xf bank_mask:0xf
	s_waitcnt lgkmcnt(0)
	v_add_f32_e32 v20, v20, v21
	ds_bpermute_b32 v21, v60, v20
	s_waitcnt lgkmcnt(0)
	v_add_f32_e32 v20, v20, v21
	ds_bpermute_b32 v21, v61, v20
	s_waitcnt lgkmcnt(0)
	v_add_f32_e32 v16, v20, v21
	v_fmamk_f32 v16, v16, 0x3a800000, v62
	v_mul_f32_e32 v17, 0x4b800000, v16
	v_cmp_gt_f32_e64 s[4:5], s23, v16
	s_waitcnt vmcnt(2)
	v_pk_add_f32 v[70:71], v[70:71], 1.0 op_sel_hi:[1,0]
	v_cndmask_b32_e64 v16, v16, v17, s[4:5]
	v_rsq_f32_e32 v53, v16
	v_pk_add_f32 v[68:69], v[68:69], 1.0 op_sel_hi:[1,0]
	global_load_dwordx4 v[20:23], v[18:19], off offset:2048
	s_nop 0
	global_load_dwordx4 v[16:19], v[18:19], off offset:3072
	v_mul_f32_e32 v63, 0x45800000, v53
	v_cndmask_b32_e64 v78, v53, v63, s[4:5]
	v_pk_mul_f32 v[46:47], v[46:47], v[78:79] op_sel_hi:[1,0]
	v_pk_mul_f32 v[44:45], v[44:45], v[78:79] op_sel_hi:[1,0]
	v_pk_mul_f32 v[46:47], v[2:3], v[46:47]
	v_pk_mul_f32 v[44:45], v[0:1], v[44:45]
	v_pk_fma_f32 v[46:47], v[70:71], v[46:47], v[66:67]
	v_pk_fma_f32 v[44:45], v[68:69], v[44:45], v[64:65]
	v_pk_mul_f32 v[42:43], v[42:43], v[78:79] op_sel_hi:[1,0]
	v_cvt_pk_bf16_f32 v44, v44, v45
	v_cvt_pk_bf16_f32 v45, v46, v47
	global_store_dwordx2 v[74:75], v[44:45], off
	global_load_dwordx4 v[44:47], v[76:77], off offset:1024
	s_nop 0
	global_load_dwordx4 v[64:67], v[72:73], off offset:1024
	v_pk_mul_f32 v[40:41], v[40:41], v[78:79] op_sel_hi:[1,0]
	v_pk_mul_f32 v[42:43], v[6:7], v[42:43]
	v_pk_mul_f32 v[40:41], v[4:5], v[40:41]
	v_pk_mul_f32 v[38:39], v[38:39], v[78:79] op_sel_hi:[1,0]
	v_pk_mul_f32 v[36:37], v[36:37], v[78:79] op_sel_hi:[1,0]
	v_pk_mul_f32 v[38:39], v[10:11], v[38:39]
	v_pk_mul_f32 v[36:37], v[8:9], v[36:37]
	v_pk_mul_f32 v[26:27], v[26:27], v[78:79] op_sel_hi:[1,0]
	v_pk_mul_f32 v[24:25], v[24:25], v[78:79] op_sel_hi:[1,0]
	v_pk_mul_f32 v[26:27], v[14:15], v[26:27]
	v_pk_mul_f32 v[24:25], v[12:13], v[24:25]
	s_waitcnt vmcnt(1)
; DI unsigned pk2(float a, float b) { f32x2 v = {a, b}; bf16x2_t r = __builtin_convertvector(v, bf16x2_t); return __builtin_bit_cast(unsigned, r); }
; template <int MODE>
; DI void norm_rows(const Params& p) {
;     ...
;         for (int u = 0; u < 2; ++u) {
;             const int row = row0 + u * NGW;
;             if (row >= nrows) break;
;             s[u] = 0.f;
; #pragma unroll
;             for (int j = 0; j < 4; ++j) s[u] += (v[u][j].x * v[u][j].x + v[u][j].y * v[u][j].y) + (v[u][j].z * v[u][j].z + v[u][j].w * v[u][j].w);
;             const float rstd = rsqrtf(wave_sum(s[u]) * (1.f / DM) + EPS);
;             if (MODE == 2) {
;                 float* dst = p.out + (size_t)row * DM;
; #pragma unroll
;                 for (int j = 0; j < 4; ++j) *(f32x4*)(dst + 4 * lane + 256 * j) = v[u][j] * rstd * gn[j];
;             } else {
;                 const float* mrow = modp + (size_t)mb[u] * NMODC + (MODE == 0 ? 0 : 3072);
;                 bf16_t* dst = (bf16_t*)(p.ws + OFF_A) + (MODE == 0 ? (size_t)0 : (size_t)NLAT * 1024) + (size_t)row * DM;
; #pragma unroll
;                 for (int j = 0; j < 4; ++j) {
;                     const f32x4 sh = *(const f32x4*)(mrow + 4 * lane + 256 * j), scl = *(const f32x4*)(mrow + 1024 + 4 * lane + 256 * j);
;                     const f32x4 y = (v[u][j] * rstd * gn[j]) * (scl + 1.f) + sh;
;                     u32x2 o; o.x = pk2(y.x, y.y); o.y = pk2(y.z, y.w);
;                     *(u32x2*)(dst + 4 * lane + 256 * j) = o;
;                 }
	v_pk_add_f32 v[46:47], v[46:47], 1.0 op_sel_hi:[1,0]
	v_pk_add_f32 v[44:45], v[44:45], 1.0 op_sel_hi:[1,0]
	s_waitcnt vmcnt(0)
	v_pk_fma_f32 v[42:43], v[46:47], v[42:43], v[66:67]
	v_pk_fma_f32 v[40:41], v[44:45], v[40:41], v[64:65]
	s_nop 0
	v_cvt_pk_bf16_f32 v40, v40, v41
	v_cvt_pk_bf16_f32 v41, v42, v43
	global_store_dwordx2 v[74:75], v[40:41], off offset:512
	global_load_dwordx4 v[40:43], v[76:77], off offset:2048
	s_nop 0
	global_load_dwordx4 v[44:47], v[72:73], off offset:2048
	s_waitcnt vmcnt(1)
	v_pk_add_f32 v[42:43], v[42:43], 1.0 op_sel_hi:[1,0]
	v_pk_add_f32 v[40:41], v[40:41], 1.0 op_sel_hi:[1,0]
	s_waitcnt vmcnt(0)
	v_pk_fma_f32 v[38:39], v[42:43], v[38:39], v[46:47]
	v_pk_fma_f32 v[36:37], v[40:41], v[36:37], v[44:45]
	s_nop 0
	v_cvt_pk_bf16_f32 v36, v36, v37
	v_cvt_pk_bf16_f32 v37, v38, v39
	global_store_dwordx2 v[74:75], v[36:37], off offset:1024
	global_load_dwordx4 v[36:39], v[76:77], off offset:3072
	s_nop 0
	global_load_dwordx4 v[40:43], v[72:73], off offset:3072
	s_waitcnt vmcnt(1)
	v_pk_add_f32 v[38:39], v[38:39], 1.0 op_sel_hi:[1,0]
	v_pk_add_f32 v[36:37], v[36:37], 1.0 op_sel_hi:[1,0]
	s_waitcnt vmcnt(0)
	v_pk_fma_f32 v[26:27], v[38:39], v[26:27], v[42:43]
	v_pk_fma_f32 v[24:25], v[36:37], v[24:25], v[40:41]
	s_nop 0
	v_cvt_pk_bf16_f32 v24, v24, v25
	v_cvt_pk_bf16_f32 v25, v26, v27
	global_store_dwordx2 v[74:75], v[24:25], off offset:1536
	s_and_saveexec_b64 s[4:5], vcc
	s_cbranch_execz .LBB0_138
	v_lshl_add_u64 v[24:25], s[12:13], 0, v[54:55]
	v_lshl_add_u64 v[40:41], v[24:25], 0, v[48:49]
	v_add_co_u32_e32 v24, vcc, s24, v40
	v_pk_mul_f32 v[42:43], v[34:35], v[34:35]
	s_nop 0
	v_addc_co_u32_e32 v25, vcc, 0, v41, vcc
	global_load_dwordx4 v[24:27], v[24:25], off
	s_nop 0
	global_load_dwordx4 v[36:39], v[40:41], off
	v_pk_mul_f32 v[44:45], v[32:33], v[32:33]
	v_mul_f32_e32 v53, v18, v18
	v_pk_mov_b32 v[46:47], v[44:45], v[42:43] op_sel:[1,0]
	v_mov_b32_e32 v45, v43
	v_pk_add_f32 v[42:43], v[46:47], v[44:45]
	v_pk_mul_f32 v[44:45], v[30:31], v[30:31]
	v_pk_mul_f32 v[46:47], v[28:29], v[28:29]
	v_pk_add_f32 v[42:43], v[42:43], v[42:43] op_sel:[0,1] op_sel_hi:[1,0]
	v_pk_mov_b32 v[54:55], v[46:47], v[44:45] op_sel:[1,0]
	v_mov_b32_e32 v47, v45
	v_pk_add_f32 v[44:45], v[54:55], v[46:47]
	v_mul_f32_e32 v46, v16, v16
	v_mul_f32_e32 v47, v17, v17
	v_pk_add_f32 v[44:45], v[44:45], v[44:45] op_sel:[0,1] op_sel_hi:[1,0]
	v_mov_b32_e32 v43, v46
	v_mov_b32_e32 v45, v47
	v_pk_add_f32 v[42:43], v[42:43], v[44:45]
	v_mul_f32_e32 v44, v21, v21
	v_mul_f32_e32 v46, v23, v23
	v_mul_f32_e32 v54, v19, v19
	v_pk_fma_f32 v[44:45], v[20:21], v[20:21], v[44:45] op_sel_hi:[1,1,0]
	v_pk_fma_f32 v[46:47], v[22:23], v[22:23], v[46:47] op_sel_hi:[1,1,0]
	v_mov_b32_e32 v45, v53
	v_mov_b32_e32 v47, v54
	v_pk_add_f32 v[44:45], v[44:45], v[46:47]
	v_ashrrev_i32_e32 v53, 31, v52
	v_pk_add_f32 v[42:43], v[42:43], v[44:45]
	v_lshl_add_u64 v[44:45], v[40:41], 0, s[16:17]
	v_add_f32_e32 v42, v42, v43
	s_nop 1
	v_mov_b32_dpp v43, v42 quad_perm:[1,0,3,2] row_mask:0xf bank_mask:0xf
	s_waitcnt lgkmcnt(0)
	v_add_f32_e32 v42, v42, v43
	s_nop 1
	v_mov_b32_dpp v43, v42 quad_perm:[2,3,0,1] row_mask:0xf bank_mask:0xf
	s_waitcnt lgkmcnt(0)
	v_add_f32_e32 v42, v42, v43
	s_nop 1
	v_mov_b32_dpp v43, v42 row_half_mirror row_mask:0xf bank_mask:0xf
	s_waitcnt lgkmcnt(0)
	v_add_f32_e32 v42, v42, v43
	s_nop 1
	v_mov_b32_dpp v43, v42 row_ror:8 row_mask:0xf bank_mask:0xf
	s_waitcnt lgkmcnt(0)
	v_add_f32_e32 v42, v42, v43
	ds_bpermute_b32 v43, v60, v42
	s_waitcnt lgkmcnt(0)
	v_add_f32_e32 v42, v42, v43
	ds_bpermute_b32 v43, v61, v42
	s_waitcnt lgkmcnt(0)
	v_add_f32_e32 v42, v42, v43
	v_fmamk_f32 v42, v42, 0x3a800000, v62
	v_mul_f32_e32 v43, 0x4b800000, v42
	v_cmp_gt_f32_e32 vcc, s23, v42
	s_waitcnt vmcnt(1)
	v_pk_add_f32 v[26:27], v[26:27], 1.0 op_sel_hi:[1,0]
	v_cndmask_b32_e32 v42, v42, v43, vcc
	v_rsq_f32_e32 v46, v42
	v_pk_add_f32 v[24:25], v[24:25], 1.0 op_sel_hi:[1,0]
	v_lshlrev_b64 v[42:43], 11, v[52:53]
	v_lshl_add_u64 v[42:43], v[50:51], 0, v[42:43]
	v_mul_f32_e32 v47, 0x45800000, v46
	v_cndmask_b32_e32 v46, v46, v47, vcc
	v_pk_mul_f32 v[34:35], v[34:35], v[46:47] op_sel_hi:[1,0]
	v_pk_mul_f32 v[32:33], v[32:33], v[46:47] op_sel_hi:[1,0]
	v_pk_mul_f32 v[34:35], v[2:3], v[34:35]
	v_pk_mul_f32 v[32:33], v[0:1], v[32:33]
	s_waitcnt vmcnt(0)
	v_pk_fma_f32 v[26:27], v[26:27], v[34:35], v[38:39]
	v_pk_fma_f32 v[24:25], v[24:25], v[32:33], v[36:37]
	v_pk_mul_f32 v[30:31], v[30:31], v[46:47] op_sel_hi:[1,0]
	v_cvt_pk_bf16_f32 v24, v24, v25
	v_cvt_pk_bf16_f32 v25, v26, v27
	global_store_dwordx2 v[42:43], v[24:25], off
	global_load_dwordx4 v[24:27], v[44:45], off offset:1024
	s_nop 0
	global_load_dwordx4 v[32:35], v[40:41], off offset:1024
	v_pk_mul_f32 v[28:29], v[28:29], v[46:47] op_sel_hi:[1,0]
	v_pk_mul_f32 v[30:31], v[6:7], v[30:31]
	v_pk_mul_f32 v[28:29], v[4:5], v[28:29]
	v_pk_mul_f32 v[22:23], v[22:23], v[46:47] op_sel_hi:[1,0]
	v_pk_mul_f32 v[20:21], v[20:21], v[46:47] op_sel_hi:[1,0]
	v_pk_mul_f32 v[22:23], v[10:11], v[22:23]
	v_pk_mul_f32 v[20:21], v[8:9], v[20:21]
	v_pk_mul_f32 v[18:19], v[18:19], v[46:47] op_sel_hi:[1,0]
	v_pk_mul_f32 v[16:17], v[16:17], v[46:47] op_sel_hi:[1,0]
	v_pk_mul_f32 v[18:19], v[14:15], v[18:19]
	v_pk_mul_f32 v[16:17], v[12:13], v[16:17]
	s_waitcnt vmcnt(1)
	v_pk_add_f32 v[26:27], v[26:27], 1.0 op_sel_hi:[1,0]
	v_pk_add_f32 v[24:25], v[24:25], 1.0 op_sel_hi:[1,0]
	s_waitcnt vmcnt(0)
	v_pk_fma_f32 v[26:27], v[26:27], v[30:31], v[34:35]
	v_pk_fma_f32 v[24:25], v[24:25], v[28:29], v[32:33]
	s_nop 0
	v_cvt_pk_bf16_f32 v24, v24, v25
	v_cvt_pk_bf16_f32 v25, v26, v27
	global_store_dwordx2 v[42:43], v[24:25], off offset:512
	global_load_dwordx4 v[24:27], v[44:45], off offset:2048
	s_nop 0
	global_load_dwordx4 v[28:31], v[40:41], off offset:2048
	s_waitcnt vmcnt(1)
	v_pk_add_f32 v[26:27], v[26:27], 1.0 op_sel_hi:[1,0]
	v_pk_add_f32 v[24:25], v[24:25], 1.0 op_sel_hi:[1,0]
	s_waitcnt vmcnt(0)
	v_pk_fma_f32 v[22:23], v[26:27], v[22:23], v[30:31]
	v_pk_fma_f32 v[20:21], v[24:25], v[20:21], v[28:29]
	s_nop 0
	v_cvt_pk_bf16_f32 v20, v20, v21
	v_cvt_pk_bf16_f32 v21, v22, v23
	global_store_dwordx2 v[42:43], v[20:21], off offset:1024
	global_load_dwordx4 v[20:23], v[44:45], off offset:3072
	s_nop 0
	global_load_dwordx4 v[24:27], v[40:41], off offset:3072
	s_waitcnt vmcnt(1)
	v_pk_add_f32 v[22:23], v[22:23], 1.0 op_sel_hi:[1,0]
	v_pk_add_f32 v[20:21], v[20:21], 1.0 op_sel_hi:[1,0]
	s_waitcnt vmcnt(0)
	v_pk_fma_f32 v[18:19], v[22:23], v[18:19], v[26:27]
	v_pk_fma_f32 v[16:17], v[20:21], v[16:17], v[24:25]
	s_nop 0
	v_cvt_pk_bf16_f32 v16, v16, v17
	v_cvt_pk_bf16_f32 v17, v18, v19
	global_store_dwordx2 v[42:43], v[16:17], off offset:1536
	s_branch .LBB0_138

; DI float bflo(unsigned u) { return __uint_as_float(u << 16); }
; DI float bfhi(unsigned u) { return __uint_as_float(u & 0xffff0000u); }
; DI float siluf_(float x) { return x * __builtin_amdgcn_rcpf(1.f + __expf(-x)); }
; DI void dn_conv_phase(const Params& p) {
;     ...
;         for (int q = 0; q < 4; ++q) { const u32x4 u = rows[q];
;             ring[q][0] = (f32x2){bflo(u.x), bfhi(u.x)}; ring[q][1] = (f32x2){bflo(u.y), bfhi(u.y)}; ring[q][2] = (f32x2){bflo(u.z), bfhi(u.z)}; ring[q][3] = (f32x2){bflo(u.w), bfhi(u.w)}; }
; #pragma unroll
;         for (int tt = 0; tt < SEG; ++tt) {
;             { const u32x4 u = rows[tt + 4]; const int sl = (tt + 4) % 5;
;               ring[sl][0] = (f32x2){bflo(u.x), bfhi(u.x)}; ring[sl][1] = (f32x2){bflo(u.y), bfhi(u.y)}; ring[sl][2] = (f32x2){bflo(u.z), bfhi(u.z)}; ring[sl][3] = (f32x2){bflo(u.w), bfhi(u.w)}; }
;             f32x2 o2[4];
; #pragma unroll
;             for (int e = 0; e < 4; ++e) o2[e] = w[0][e] * ring[tt % 5][e];
; #pragma unroll
;             for (int j = 1; j < 5; ++j)
; #pragma unroll
;                 for (int e = 0; e < 4; ++e) o2[e] += w[j][e] * ring[(tt + j) % 5][e];
;             float o[8];
; #pragma unroll
;             for (int e = 0; e < 4; ++e) { o[2 * e] = siluf_(o2[e].x); o[2 * e + 1] = siluf_(o2[e].y); }
;             if (part < 2) {
;                 float ss = 0.f;
; #pragma unroll
;                 for (int e = 0; e < 8; ++e) ss += o[e] * o[e];
;                 ss += __shfl_xor(ss, 1); ss += __shfl_xor(ss, 2); ss += __shfl_xor(ss, 4); ss += __shfl_xor(ss, 8);
;                 const float sc = rsqrtf(ss + EPS) * (part == 0 ? 0.08838834764831845f : 1.f);
; #pragma unroll
;                 for (int e = 0; e < 8; ++e) o[e] *= sc;
;             }
.LBB0_311:
	s_or_b64 exec, exec, s[4:5]
	s_waitcnt vmcnt(0)
	v_lshlrev_b32_e32 v152, 16, v100
	v_and_b32_e32 v153, 0xffff0000, v100
	v_lshlrev_b32_e32 v150, 16, v101
	v_and_b32_e32 v151, 0xffff0000, v101
	v_lshlrev_b32_e32 v138, 16, v102
	v_and_b32_e32 v139, 0xffff0000, v102
	v_lshlrev_b32_e32 v136, 16, v103
	v_and_b32_e32 v137, 0xffff0000, v103
	v_mad_u64_u32 v[140:141], s[4:5], v130, -3, v[120:121]
	v_lshlrev_b32_e32 v142, 16, v104
	v_and_b32_e32 v143, 0xffff0000, v104
	v_lshlrev_b32_e32 v144, 16, v105
	v_and_b32_e32 v145, 0xffff0000, v105
	v_lshlrev_b32_e32 v158, 16, v106
	v_and_b32_e32 v159, 0xffff0000, v106
	v_lshlrev_b32_e32 v160, 16, v107
	v_and_b32_e32 v161, 0xffff0000, v107
	v_lshlrev_b32_e32 v148, 16, v108
	v_and_b32_e32 v149, 0xffff0000, v108
	v_lshlrev_b32_e32 v134, 16, v109
	v_and_b32_e32 v135, 0xffff0000, v109
	v_lshlrev_b32_e32 v132, 16, v110
	v_and_b32_e32 v133, 0xffff0000, v110
	v_lshlrev_b32_e32 v130, 16, v111
	v_and_b32_e32 v131, 0xffff0000, v111
	v_lshlrev_b32_e32 v146, 16, v112
	v_and_b32_e32 v147, 0xffff0000, v112
	v_lshlrev_b32_e32 v128, 16, v113
	v_and_b32_e32 v129, 0xffff0000, v113
	v_lshlrev_b32_e32 v112, 16, v114
	v_and_b32_e32 v113, 0xffff0000, v114
	v_lshlrev_b32_e32 v110, 16, v115
	v_and_b32_e32 v111, 0xffff0000, v115
	v_lshlrev_b32_e32 v108, 16, v116
	v_and_b32_e32 v109, 0xffff0000, v116
	v_lshlrev_b32_e32 v106, 16, v117
	v_and_b32_e32 v107, 0xffff0000, v117
	v_lshlrev_b32_e32 v104, 16, v118
	v_and_b32_e32 v105, 0xffff0000, v118
	v_lshlrev_b32_e32 v102, 16, v119
	v_and_b32_e32 v103, 0xffff0000, v119
	v_pk_mul_f32 v[100:101], v[20:21], v[152:153]
	v_pk_mul_f32 v[114:115], v[22:23], v[150:151]
	v_pk_mul_f32 v[116:117], v[12:13], v[138:139]
	v_pk_mul_f32 v[118:119], v[14:15], v[136:137]
	v_pk_fma_f32 v[100:101], v[4:5], v[142:143], v[100:101]
	v_pk_fma_f32 v[114:115], v[6:7], v[144:145], v[114:115]
	v_pk_fma_f32 v[116:117], v[0:1], v[158:159], v[116:117]
	v_pk_fma_f32 v[118:119], v[2:3], v[160:161], v[118:119]
	v_pk_fma_f32 v[100:101], v[24:25], v[148:149], v[100:101]
	v_pk_fma_f32 v[114:115], v[26:27], v[134:135], v[114:115]
	v_pk_fma_f32 v[116:117], v[16:17], v[132:133], v[116:117]
	v_pk_fma_f32 v[118:119], v[18:19], v[130:131], v[118:119]
	v_pk_fma_f32 v[100:101], v[36:37], v[146:147], v[100:101]
	v_pk_fma_f32 v[114:115], v[38:39], v[128:129], v[114:115]
	v_pk_fma_f32 v[116:117], v[28:29], v[112:113], v[116:117]
	v_pk_fma_f32 v[118:119], v[30:31], v[110:111], v[118:119]
	v_cmp_gt_i32_e32 vcc, 2, v140
	v_cmp_eq_u32_e64 s[4:5], 0, v140
	v_pk_fma_f32 v[100:101], v[32:33], v[108:109], v[100:101]
	v_pk_fma_f32 v[140:141], v[34:35], v[106:107], v[114:115]
	v_pk_fma_f32 v[142:143], v[8:9], v[104:105], v[116:117]
	v_pk_fma_f32 v[144:145], v[10:11], v[102:103], v[118:119]
	v_mul_f32_e32 v114, 0xbfb8aa3b, v100
	v_mul_f32_e32 v115, 0xbfb8aa3b, v101
	v_mul_f32_e32 v116, 0xbfb8aa3b, v140
	v_mul_f32_e32 v117, 0xbfb8aa3b, v141
	v_mul_f32_e32 v118, 0xbfb8aa3b, v142
	v_mul_f32_e32 v119, 0xbfb8aa3b, v143
	v_mul_f32_e32 v158, 0xbfb8aa3b, v144
	v_mul_f32_e32 v159, 0xbfb8aa3b, v145
	v_exp_f32_e32 v114, v114
	v_exp_f32_e32 v115, v115
	v_exp_f32_e32 v116, v116
	v_exp_f32_e32 v117, v117
	v_exp_f32_e32 v118, v118
	v_exp_f32_e32 v119, v119
	v_exp_f32_e32 v158, v158
	v_exp_f32_e32 v159, v159
	v_add_f32_e32 v114, 1.0, v114
	v_add_f32_e32 v115, 1.0, v115
	v_add_f32_e32 v116, 1.0, v116
	v_add_f32_e32 v117, 1.0, v117
	v_add_f32_e32 v118, 1.0, v118
	v_add_f32_e32 v119, 1.0, v119
	v_add_f32_e32 v158, 1.0, v158
	v_add_f32_e32 v159, 1.0, v159
	v_rcp_f32_e32 v114, v114
	v_rcp_f32_e32 v115, v115
	v_rcp_f32_e32 v116, v116
	v_rcp_f32_e32 v117, v117
	v_rcp_f32_e32 v118, v118
	v_rcp_f32_e32 v119, v119
	v_rcp_f32_e32 v158, v158
	v_rcp_f32_e32 v159, v159
	v_cndmask_b32_e64 v157, 1.0, v154, s[4:5]
	v_pk_mul_f32 v[114:115], v[100:101], v[114:115]
	v_pk_mul_f32 v[116:117], v[140:141], v[116:117]
	v_pk_mul_f32 v[118:119], v[142:143], v[118:119]
	v_pk_mul_f32 v[140:141], v[144:145], v[158:159]
	v_mbcnt_hi_u32_b32 v158, -1, v155
	s_and_saveexec_b64 s[24:25], vcc
	s_cbranch_execz .LBB0_313
	v_pk_mul_f32 v[100:101], v[114:115], v[114:115]
	v_pk_mul_f32 v[142:143], v[116:117], v[116:117]
	v_add_f32_e32 v100, v100, v101
	v_add_f32_e32 v100, v142, v100
	v_pk_mul_f32 v[144:145], v[118:119], v[118:119]
	v_add_f32_e32 v100, v143, v100
	v_and_b32_e32 v142, 64, v158
	v_add_f32_e32 v100, v144, v100
	v_xor_b32_e32 v101, 1, v158
	v_add_u32_e32 v142, 64, v142
	v_pk_mul_f32 v[160:161], v[140:141], v[140:141]
	v_add_f32_e32 v100, v145, v100
	v_cmp_lt_i32_e64 s[4:5], v101, v142
	v_add_f32_e32 v100, v160, v100
	v_add_f32_e32 v100, v161, v100
	v_cndmask_b32_e64 v101, v158, v101, s[4:5]
	v_lshlrev_b32_e32 v101, 2, v101
	s_nop 1
	v_mov_b32_dpp v101, v100 quad_perm:[1,0,3,2] row_mask:0xf bank_mask:0xf
	s_waitcnt lgkmcnt(0)
	v_add_f32_e32 v100, v100, v101
	v_xor_b32_e32 v101, 2, v158
	v_cmp_lt_i32_e64 s[4:5], v101, v142
	s_nop 1
	v_cndmask_b32_e64 v101, v158, v101, s[4:5]
	v_lshlrev_b32_e32 v101, 2, v101
	s_nop 1
	v_mov_b32_dpp v101, v100 quad_perm:[2,3,0,1] row_mask:0xf bank_mask:0xf
	s_waitcnt lgkmcnt(0)
	v_add_f32_e32 v100, v100, v101
	v_xor_b32_e32 v101, 4, v158
	v_cmp_lt_i32_e64 s[4:5], v101, v142
	s_nop 1
	v_cndmask_b32_e64 v101, v158, v101, s[4:5]
	v_lshlrev_b32_e32 v101, 2, v101
	s_nop 1
	v_mov_b32_dpp v101, v100 row_half_mirror row_mask:0xf bank_mask:0xf
	s_waitcnt lgkmcnt(0)
	v_add_f32_e32 v100, v100, v101
	v_xor_b32_e32 v101, 8, v158
	v_cmp_lt_i32_e64 s[4:5], v101, v142
	s_nop 1
	v_cndmask_b32_e64 v101, v158, v101, s[4:5]
	v_lshlrev_b32_e32 v101, 2, v101
	s_nop 1
	v_mov_b32_dpp v101, v100 row_ror:8 row_mask:0xf bank_mask:0xf
	s_waitcnt lgkmcnt(0)
	v_add_f32_e32 v100, v100, v101
	v_add_f32_e32 v100, 0x358637bd, v100
	v_mul_f32_e32 v101, 0x4b800000, v100
	v_cmp_gt_f32_e64 s[4:5], s46, v100
	s_nop 1
	v_cndmask_b32_e64 v100, v100, v101, s[4:5]
	v_rsq_f32_e32 v100, v100
	s_nop 0
	v_mul_f32_e32 v101, 0x45800000, v100
	v_cndmask_b32_e64 v100, v100, v101, s[4:5]
	v_mul_f32_e32 v100, v157, v100
	v_pk_mul_f32 v[140:141], v[140:141], v[100:101] op_sel_hi:[1,0]
	v_pk_mul_f32 v[118:119], v[118:119], v[100:101] op_sel_hi:[1,0]
	v_pk_mul_f32 v[116:117], v[116:117], v[100:101] op_sel_hi:[1,0]
	v_pk_mul_f32 v[114:115], v[114:115], v[100:101] op_sel_hi:[1,0]
; DI unsigned pk2(float a, float b) { f32x2 v = {a, b}; bf16x2_t r = __builtin_convertvector(v, bf16x2_t); return __builtin_bit_cast(unsigned, r); }
; DI float bflo(unsigned u) { return __uint_as_float(u << 16); }
; DI float bfhi(unsigned u) { return __uint_as_float(u & 0xffff0000u); }
; DI float siluf_(float x) { return x * __builtin_amdgcn_rcpf(1.f + __expf(-x)); }
; DI void dn_conv_phase(const Params& p) {
;     ...
;         for (int tt = 0; tt < SEG; ++tt) {
;             { const u32x4 u = rows[tt + 4]; const int sl = (tt + 4) % 5;
;               ring[sl][0] = (f32x2){bflo(u.x), bfhi(u.x)}; ring[sl][1] = (f32x2){bflo(u.y), bfhi(u.y)}; ring[sl][2] = (f32x2){bflo(u.z), bfhi(u.z)}; ring[sl][3] = (f32x2){bflo(u.w), bfhi(u.w)}; }
;             f32x2 o2[4];
; #pragma unroll
;             for (int e = 0; e < 4; ++e) o2[e] = w[0][e] * ring[tt % 5][e];
; #pragma unroll
;             for (int j = 1; j < 5; ++j)
; #pragma unroll
;                 for (int e = 0; e < 4; ++e) o2[e] += w[j][e] * ring[(tt + j) % 5][e];
;             float o[8];
; #pragma unroll
;             for (int e = 0; e < 4; ++e) { o[2 * e] = siluf_(o2[e].x); o[2 * e + 1] = siluf_(o2[e].y); }
;             if (part < 2) {
;                 float ss = 0.f;
; #pragma unroll
;                 for (int e = 0; e < 8; ++e) ss += o[e] * o[e];
;                 ss += __shfl_xor(ss, 1); ss += __shfl_xor(ss, 2); ss += __shfl_xor(ss, 4); ss += __shfl_xor(ss, 8);
;                 const float sc = rsqrtf(ss + EPS) * (part == 0 ? 0.08838834764831845f : 1.f);
; #pragma unroll
;                 for (int e = 0; e < 8; ++e) o[e] *= sc;
;             }
;             u32x4 ov; ov.x = pk2(o[0], o[1]); ov.y = pk2(o[2], o[3]); ov.z = pk2(o[4], o[5]); ov.w = pk2(o[6], o[7]);
;             *(u32x4*)(QKV + (size_t)(row0 + tt) * 1536 + ch) = ov;
.LBB0_313:
	s_or_b64 exec, exec, s[24:25]
	v_mad_i64_i32 v[142:143], s[4:5], v156, s45, 0
	v_lshl_add_u64 v[100:101], v[126:127], 1, s[28:29]
	v_cvt_pk_bf16_f32 v114, v114, v115
	v_cvt_pk_bf16_f32 v115, v116, v117
	v_cvt_pk_bf16_f32 v116, v118, v119
	v_cvt_pk_bf16_f32 v117, v140, v141
	v_lshl_add_u64 v[118:119], v[100:101], 0, v[142:143]
	global_store_dwordx4 v[118:119], v[114:117], off
	v_lshlrev_b32_e32 v144, 16, v96
	v_and_b32_e32 v145, 0xffff0000, v96
	v_lshlrev_b32_e32 v142, 16, v97
	v_and_b32_e32 v143, 0xffff0000, v97
	v_pk_mul_f32 v[96:97], v[20:21], v[148:149]
	v_pk_mul_f32 v[114:115], v[22:23], v[134:135]
	v_pk_mul_f32 v[116:117], v[12:13], v[132:133]
	v_pk_mul_f32 v[118:119], v[14:15], v[130:131]
	v_pk_fma_f32 v[96:97], v[4:5], v[152:153], v[96:97]
	v_pk_fma_f32 v[114:115], v[6:7], v[150:151], v[114:115]
	v_pk_fma_f32 v[116:117], v[0:1], v[138:139], v[116:117]
	v_pk_fma_f32 v[118:119], v[2:3], v[136:137], v[118:119]
	v_pk_fma_f32 v[96:97], v[24:25], v[146:147], v[96:97]
	v_pk_fma_f32 v[114:115], v[26:27], v[128:129], v[114:115]
	v_pk_fma_f32 v[116:117], v[16:17], v[112:113], v[116:117]
	v_pk_fma_f32 v[118:119], v[18:19], v[110:111], v[118:119]
	v_lshlrev_b32_e32 v140, 16, v98
	v_and_b32_e32 v141, 0xffff0000, v98
	v_lshlrev_b32_e32 v98, 16, v99
	v_and_b32_e32 v99, 0xffff0000, v99
	v_pk_fma_f32 v[96:97], v[36:37], v[108:109], v[96:97]
	v_pk_fma_f32 v[114:115], v[38:39], v[106:107], v[114:115]
	v_pk_fma_f32 v[116:117], v[28:29], v[104:105], v[116:117]
	v_pk_fma_f32 v[118:119], v[30:31], v[102:103], v[118:119]
	v_pk_fma_f32 v[96:97], v[32:33], v[144:145], v[96:97]
	v_pk_fma_f32 v[114:115], v[34:35], v[142:143], v[114:115]
	v_pk_fma_f32 v[116:117], v[8:9], v[140:141], v[116:117]
	v_pk_fma_f32 v[118:119], v[10:11], v[98:99], v[118:119]
	v_mul_f32_e32 v126, 0xbfb8aa3b, v96
	v_mul_f32_e32 v127, 0xbfb8aa3b, v97
	v_mul_f32_e32 v136, 0xbfb8aa3b, v114
	v_mul_f32_e32 v137, 0xbfb8aa3b, v115
	v_mul_f32_e32 v138, 0xbfb8aa3b, v116
	v_mul_f32_e32 v139, 0xbfb8aa3b, v117
	v_mul_f32_e32 v150, 0xbfb8aa3b, v118
	v_mul_f32_e32 v151, 0xbfb8aa3b, v119
	v_exp_f32_e32 v126, v126
	v_exp_f32_e32 v127, v127
	v_exp_f32_e32 v136, v136
	v_exp_f32_e32 v137, v137
	v_exp_f32_e32 v138, v138
	v_exp_f32_e32 v139, v139
	v_exp_f32_e32 v150, v150
	v_exp_f32_e32 v151, v151
	v_add_f32_e32 v126, 1.0, v126
	v_add_f32_e32 v127, 1.0, v127
	v_add_f32_e32 v136, 1.0, v136
	v_add_f32_e32 v137, 1.0, v137
	v_add_f32_e32 v138, 1.0, v138
	v_add_f32_e32 v139, 1.0, v139
	v_add_f32_e32 v150, 1.0, v150
	v_add_f32_e32 v151, 1.0, v151
	v_rcp_f32_e32 v126, v126
	v_rcp_f32_e32 v127, v127
	v_rcp_f32_e32 v136, v136
	v_rcp_f32_e32 v137, v137
	v_rcp_f32_e32 v138, v138
	v_rcp_f32_e32 v139, v139
	v_rcp_f32_e32 v150, v150
	v_rcp_f32_e32 v151, v151
	v_pk_mul_f32 v[96:97], v[96:97], v[126:127]
	v_pk_mul_f32 v[114:115], v[114:115], v[136:137]
	v_pk_mul_f32 v[116:117], v[116:117], v[138:139]
	v_pk_mul_f32 v[118:119], v[118:119], v[150:151]
	s_and_saveexec_b64 s[24:25], vcc
	s_cbranch_execz .LBB0_315
	v_pk_mul_f32 v[126:127], v[96:97], v[96:97]
	v_pk_mul_f32 v[136:137], v[114:115], v[114:115]
	v_add_f32_e32 v126, v126, v127
	v_add_f32_e32 v126, v136, v126
	v_pk_mul_f32 v[138:139], v[116:117], v[116:117]
	v_add_f32_e32 v126, v137, v126
	v_and_b32_e32 v136, 64, v158
	v_add_f32_e32 v126, v138, v126
	v_xor_b32_e32 v127, 1, v158
	v_add_u32_e32 v136, 64, v136
	v_pk_mul_f32 v[150:151], v[118:119], v[118:119]
	v_add_f32_e32 v126, v139, v126
	v_cmp_lt_i32_e64 s[4:5], v127, v136
	v_add_f32_e32 v126, v150, v126
	v_add_f32_e32 v126, v151, v126
	v_cndmask_b32_e64 v127, v158, v127, s[4:5]
	v_lshlrev_b32_e32 v127, 2, v127
	s_nop 1
	v_mov_b32_dpp v127, v126 quad_perm:[1,0,3,2] row_mask:0xf bank_mask:0xf
	s_waitcnt lgkmcnt(0)
	v_add_f32_e32 v126, v126, v127
	v_xor_b32_e32 v127, 2, v158
	v_cmp_lt_i32_e64 s[4:5], v127, v136
	s_nop 1
	v_cndmask_b32_e64 v127, v158, v127, s[4:5]
	v_lshlrev_b32_e32 v127, 2, v127
	s_nop 1
	v_mov_b32_dpp v127, v126 quad_perm:[2,3,0,1] row_mask:0xf bank_mask:0xf
	s_waitcnt lgkmcnt(0)
	v_add_f32_e32 v126, v126, v127
	v_xor_b32_e32 v127, 4, v158
	v_cmp_lt_i32_e64 s[4:5], v127, v136
	s_nop 1
	v_cndmask_b32_e64 v127, v158, v127, s[4:5]
	v_lshlrev_b32_e32 v127, 2, v127
	s_nop 1
	v_mov_b32_dpp v127, v126 row_half_mirror row_mask:0xf bank_mask:0xf
	s_waitcnt lgkmcnt(0)
	v_add_f32_e32 v126, v126, v127
	v_xor_b32_e32 v127, 8, v158
	v_cmp_lt_i32_e64 s[4:5], v127, v136
	s_nop 1
	v_cndmask_b32_e64 v127, v158, v127, s[4:5]
	v_lshlrev_b32_e32 v127, 2, v127
	s_nop 1
	v_mov_b32_dpp v127, v126 row_ror:8 row_mask:0xf bank_mask:0xf
	s_waitcnt lgkmcnt(0)
	v_add_f32_e32 v126, v126, v127
	v_add_f32_e32 v126, 0x358637bd, v126
	v_mul_f32_e32 v127, 0x4b800000, v126
	v_cmp_gt_f32_e64 s[4:5], s46, v126
	s_nop 1
	v_cndmask_b32_e64 v126, v126, v127, s[4:5]
	v_rsq_f32_e32 v126, v126
	s_nop 0
	v_mul_f32_e32 v127, 0x45800000, v126
	v_cndmask_b32_e64 v126, v126, v127, s[4:5]
	v_mul_f32_e32 v126, v157, v126
	v_pk_mul_f32 v[118:119], v[118:119], v[126:127] op_sel_hi:[1,0]
	v_pk_mul_f32 v[116:117], v[116:117], v[126:127] op_sel_hi:[1,0]
	v_pk_mul_f32 v[114:115], v[114:115], v[126:127] op_sel_hi:[1,0]
	v_pk_mul_f32 v[96:97], v[96:97], v[126:127] op_sel_hi:[1,0]
; DI unsigned pk2(float a, float b) { f32x2 v = {a, b}; bf16x2_t r = __builtin_convertvector(v, bf16x2_t); return __builtin_bit_cast(unsigned, r); }
; DI float bflo(unsigned u) { return __uint_as_float(u << 16); }
; DI float bfhi(unsigned u) { return __uint_as_float(u & 0xffff0000u); }
; DI float siluf_(float x) { return x * __builtin_amdgcn_rcpf(1.f + __expf(-x)); }
; DI void dn_conv_phase(const Params& p) {
;     ...
;         for (int tt = 0; tt < SEG; ++tt) {
;             { const u32x4 u = rows[tt + 4]; const int sl = (tt + 4) % 5;
;               ring[sl][0] = (f32x2){bflo(u.x), bfhi(u.x)}; ring[sl][1] = (f32x2){bflo(u.y), bfhi(u.y)}; ring[sl][2] = (f32x2){bflo(u.z), bfhi(u.z)}; ring[sl][3] = (f32x2){bflo(u.w), bfhi(u.w)}; }
;             f32x2 o2[4];
; #pragma unroll
;             for (int e = 0; e < 4; ++e) o2[e] = w[0][e] * ring[tt % 5][e];
; #pragma unroll
;             for (int j = 1; j < 5; ++j)
; #pragma unroll
;                 for (int e = 0; e < 4; ++e) o2[e] += w[j][e] * ring[(tt + j) % 5][e];
;             float o[8];
; #pragma unroll
;             for (int e = 0; e < 4; ++e) { o[2 * e] = siluf_(o2[e].x); o[2 * e + 1] = siluf_(o2[e].y); }
;             if (part < 2) {
;                 float ss = 0.f;
; #pragma unroll
;                 for (int e = 0; e < 8; ++e) ss += o[e] * o[e];
;                 ss += __shfl_xor(ss, 1); ss += __shfl_xor(ss, 2); ss += __shfl_xor(ss, 4); ss += __shfl_xor(ss, 8);
;                 const float sc = rsqrtf(ss + EPS) * (part == 0 ? 0.08838834764831845f : 1.f);
; #pragma unroll
;                 for (int e = 0; e < 8; ++e) o[e] *= sc;
;             }
;             u32x4 ov; ov.x = pk2(o[0], o[1]); ov.y = pk2(o[2], o[3]); ov.z = pk2(o[4], o[5]); ov.w = pk2(o[6], o[7]);
;             *(u32x4*)(QKV + (size_t)(row0 + tt) * 1536 + ch) = ov;
.LBB0_315:
	s_or_b64 exec, exec, s[24:25]
	v_cvt_pk_bf16_f32 v136, v96, v97
	v_or_b32_e32 v96, 1, v156
	v_cvt_pk_bf16_f32 v137, v114, v115
	v_cvt_pk_bf16_f32 v138, v116, v117
	v_cvt_pk_bf16_f32 v139, v118, v119
	v_mad_i64_i32 v[96:97], s[4:5], v96, s45, v[100:101]
	global_store_dwordx4 v[96:97], v[136:139], off
	v_lshlrev_b32_e32 v96, 16, v94
	v_and_b32_e32 v97, 0xffff0000, v94
	v_lshlrev_b32_e32 v138, 16, v92
	v_and_b32_e32 v139, 0xffff0000, v92
	v_lshlrev_b32_e32 v136, 16, v93
	v_and_b32_e32 v137, 0xffff0000, v93
	v_lshlrev_b32_e32 v92, 16, v95
	v_and_b32_e32 v93, 0xffff0000, v95
	v_pk_mul_f32 v[94:95], v[20:21], v[146:147]
	v_pk_mul_f32 v[114:115], v[22:23], v[128:129]
	v_pk_mul_f32 v[116:117], v[12:13], v[112:113]
	v_pk_mul_f32 v[118:119], v[14:15], v[110:111]
	v_pk_fma_f32 v[94:95], v[4:5], v[148:149], v[94:95]
	v_pk_fma_f32 v[114:115], v[6:7], v[134:135], v[114:115]
	v_pk_fma_f32 v[116:117], v[0:1], v[132:133], v[116:117]
	v_pk_fma_f32 v[118:119], v[2:3], v[130:131], v[118:119]
	v_pk_fma_f32 v[94:95], v[24:25], v[108:109], v[94:95]
	v_pk_fma_f32 v[114:115], v[26:27], v[106:107], v[114:115]
	v_pk_fma_f32 v[116:117], v[16:17], v[104:105], v[116:117]
	v_pk_fma_f32 v[118:119], v[18:19], v[102:103], v[118:119]
	v_pk_fma_f32 v[94:95], v[36:37], v[144:145], v[94:95]
	v_pk_fma_f32 v[114:115], v[38:39], v[142:143], v[114:115]
	v_pk_fma_f32 v[116:117], v[28:29], v[140:141], v[116:117]
	v_pk_fma_f32 v[118:119], v[30:31], v[98:99], v[118:119]
	v_pk_fma_f32 v[94:95], v[32:33], v[138:139], v[94:95]
	v_pk_fma_f32 v[114:115], v[34:35], v[136:137], v[114:115]
	v_pk_fma_f32 v[116:117], v[8:9], v[96:97], v[116:117]
	v_pk_fma_f32 v[118:119], v[10:11], v[92:93], v[118:119]
	v_mul_f32_e32 v126, 0xbfb8aa3b, v94
	v_mul_f32_e32 v127, 0xbfb8aa3b, v95
	v_mul_f32_e32 v130, 0xbfb8aa3b, v114
	v_mul_f32_e32 v131, 0xbfb8aa3b, v115
	v_mul_f32_e32 v132, 0xbfb8aa3b, v116
	v_mul_f32_e32 v133, 0xbfb8aa3b, v117
	v_mul_f32_e32 v134, 0xbfb8aa3b, v118
	v_mul_f32_e32 v135, 0xbfb8aa3b, v119
	v_exp_f32_e32 v126, v126
	v_exp_f32_e32 v127, v127
	v_exp_f32_e32 v130, v130
	v_exp_f32_e32 v131, v131
	v_exp_f32_e32 v132, v132
	v_exp_f32_e32 v133, v133
	v_exp_f32_e32 v134, v134
	v_exp_f32_e32 v135, v135
	v_add_f32_e32 v126, 1.0, v126
	v_add_f32_e32 v127, 1.0, v127
	v_add_f32_e32 v130, 1.0, v130
	v_add_f32_e32 v131, 1.0, v131
	v_add_f32_e32 v132, 1.0, v132
	v_add_f32_e32 v133, 1.0, v133
	v_add_f32_e32 v134, 1.0, v134
	v_add_f32_e32 v135, 1.0, v135
	v_rcp_f32_e32 v126, v126
	v_rcp_f32_e32 v127, v127
	v_rcp_f32_e32 v130, v130
	v_rcp_f32_e32 v131, v131
	v_rcp_f32_e32 v132, v132
	v_rcp_f32_e32 v133, v133
	v_rcp_f32_e32 v134, v134
	v_rcp_f32_e32 v135, v135
	v_pk_mul_f32 v[94:95], v[94:95], v[126:127]
	v_pk_mul_f32 v[114:115], v[114:115], v[130:131]
	v_pk_mul_f32 v[116:117], v[116:117], v[132:133]
	v_pk_mul_f32 v[118:119], v[118:119], v[134:135]
	s_and_saveexec_b64 s[24:25], vcc
	s_cbranch_execz .LBB0_317
	v_pk_mul_f32 v[126:127], v[94:95], v[94:95]
	v_pk_mul_f32 v[130:131], v[114:115], v[114:115]
	v_add_f32_e32 v126, v126, v127
	v_add_f32_e32 v126, v130, v126
	v_pk_mul_f32 v[132:133], v[116:117], v[116:117]
	v_add_f32_e32 v126, v131, v126
	v_and_b32_e32 v130, 64, v158
	v_add_f32_e32 v126, v132, v126
	v_xor_b32_e32 v127, 1, v158
	v_add_u32_e32 v130, 64, v130
	v_pk_mul_f32 v[134:135], v[118:119], v[118:119]
	v_add_f32_e32 v126, v133, v126
	v_cmp_lt_i32_e64 s[4:5], v127, v130
	v_add_f32_e32 v126, v134, v126
	v_add_f32_e32 v126, v135, v126
	v_cndmask_b32_e64 v127, v158, v127, s[4:5]
	v_lshlrev_b32_e32 v127, 2, v127
	s_nop 1
	v_mov_b32_dpp v127, v126 quad_perm:[1,0,3,2] row_mask:0xf bank_mask:0xf
	s_waitcnt lgkmcnt(0)
	v_add_f32_e32 v126, v126, v127
	v_xor_b32_e32 v127, 2, v158
	v_cmp_lt_i32_e64 s[4:5], v127, v130
	s_nop 1
	v_cndmask_b32_e64 v127, v158, v127, s[4:5]
	v_lshlrev_b32_e32 v127, 2, v127
	s_nop 1
	v_mov_b32_dpp v127, v126 quad_perm:[2,3,0,1] row_mask:0xf bank_mask:0xf
	s_waitcnt lgkmcnt(0)
	v_add_f32_e32 v126, v126, v127
	v_xor_b32_e32 v127, 4, v158
	v_cmp_lt_i32_e64 s[4:5], v127, v130
	s_nop 1
	v_cndmask_b32_e64 v127, v158, v127, s[4:5]
	v_lshlrev_b32_e32 v127, 2, v127
	s_nop 1
	v_mov_b32_dpp v127, v126 row_half_mirror row_mask:0xf bank_mask:0xf
	s_waitcnt lgkmcnt(0)
	v_add_f32_e32 v126, v126, v127
	v_xor_b32_e32 v127, 8, v158
	v_cmp_lt_i32_e64 s[4:5], v127, v130
	s_nop 1
	v_cndmask_b32_e64 v127, v158, v127, s[4:5]
	v_lshlrev_b32_e32 v127, 2, v127
	s_nop 1
	v_mov_b32_dpp v127, v126 row_ror:8 row_mask:0xf bank_mask:0xf
	s_waitcnt lgkmcnt(0)
	v_add_f32_e32 v126, v126, v127
	v_add_f32_e32 v126, 0x358637bd, v126
	v_mul_f32_e32 v127, 0x4b800000, v126
	v_cmp_gt_f32_e64 s[4:5], s46, v126
	s_nop 1
	v_cndmask_b32_e64 v126, v126, v127, s[4:5]
	v_rsq_f32_e32 v126, v126
	s_nop 0
	v_mul_f32_e32 v127, 0x45800000, v126
	v_cndmask_b32_e64 v126, v126, v127, s[4:5]
	v_mul_f32_e32 v126, v157, v126
	v_pk_mul_f32 v[118:119], v[118:119], v[126:127] op_sel_hi:[1,0]
	v_pk_mul_f32 v[116:117], v[116:117], v[126:127] op_sel_hi:[1,0]
	v_pk_mul_f32 v[114:115], v[114:115], v[126:127] op_sel_hi:[1,0]
	v_pk_mul_f32 v[94:95], v[94:95], v[126:127] op_sel_hi:[1,0]
; DI unsigned pk2(float a, float b) { f32x2 v = {a, b}; bf16x2_t r = __builtin_convertvector(v, bf16x2_t); return __builtin_bit_cast(unsigned, r); }
; DI float bflo(unsigned u) { return __uint_as_float(u << 16); }
; DI float bfhi(unsigned u) { return __uint_as_float(u & 0xffff0000u); }
; DI float siluf_(float x) { return x * __builtin_amdgcn_rcpf(1.f + __expf(-x)); }
; DI void dn_conv_phase(const Params& p) {
;     ...
;         for (int tt = 0; tt < SEG; ++tt) {
;             { const u32x4 u = rows[tt + 4]; const int sl = (tt + 4) % 5;
;               ring[sl][0] = (f32x2){bflo(u.x), bfhi(u.x)}; ring[sl][1] = (f32x2){bflo(u.y), bfhi(u.y)}; ring[sl][2] = (f32x2){bflo(u.z), bfhi(u.z)}; ring[sl][3] = (f32x2){bflo(u.w), bfhi(u.w)}; }
;             f32x2 o2[4];
; #pragma unroll
;             for (int e = 0; e < 4; ++e) o2[e] = w[0][e] * ring[tt % 5][e];
; #pragma unroll
;             for (int j = 1; j < 5; ++j)
; #pragma unroll
;                 for (int e = 0; e < 4; ++e) o2[e] += w[j][e] * ring[(tt + j) % 5][e];
;             float o[8];
; #pragma unroll
;             for (int e = 0; e < 4; ++e) { o[2 * e] = siluf_(o2[e].x); o[2 * e + 1] = siluf_(o2[e].y); }
;             if (part < 2) {
;                 float ss = 0.f;
; #pragma unroll
;                 for (int e = 0; e < 8; ++e) ss += o[e] * o[e];
;                 ss += __shfl_xor(ss, 1); ss += __shfl_xor(ss, 2); ss += __shfl_xor(ss, 4); ss += __shfl_xor(ss, 8);
;                 const float sc = rsqrtf(ss + EPS) * (part == 0 ? 0.08838834764831845f : 1.f);
; #pragma unroll
;                 for (int e = 0; e < 8; ++e) o[e] *= sc;
;             }
;             u32x4 ov; ov.x = pk2(o[0], o[1]); ov.y = pk2(o[2], o[3]); ov.z = pk2(o[4], o[5]); ov.w = pk2(o[6], o[7]);
;             *(u32x4*)(QKV + (size_t)(row0 + tt) * 1536 + ch) = ov;
.LBB0_317:
	s_or_b64 exec, exec, s[24:25]
	v_cvt_pk_bf16_f32 v130, v94, v95
	v_or_b32_e32 v94, 2, v156
	v_cvt_pk_bf16_f32 v131, v114, v115
	v_cvt_pk_bf16_f32 v132, v116, v117
	v_cvt_pk_bf16_f32 v133, v118, v119
	v_mad_i64_i32 v[94:95], s[4:5], v94, s45, v[100:101]
	global_store_dwordx4 v[94:95], v[130:133], off
	v_lshlrev_b32_e32 v134, 16, v88
	v_and_b32_e32 v135, 0xffff0000, v88
	v_lshlrev_b32_e32 v132, 16, v89
	v_and_b32_e32 v133, 0xffff0000, v89
	v_lshlrev_b32_e32 v130, 16, v90
	v_and_b32_e32 v131, 0xffff0000, v90
	v_lshlrev_b32_e32 v88, 16, v91
	v_and_b32_e32 v89, 0xffff0000, v91
	v_pk_mul_f32 v[90:91], v[20:21], v[108:109]
	v_pk_mul_f32 v[114:115], v[12:13], v[104:105]
	v_pk_fma_f32 v[90:91], v[4:5], v[146:147], v[90:91]
	v_pk_fma_f32 v[112:113], v[0:1], v[112:113], v[114:115]
	v_pk_fma_f32 v[90:91], v[24:25], v[144:145], v[90:91]
	v_pk_mul_f32 v[114:115], v[14:15], v[102:103]
	v_pk_fma_f32 v[90:91], v[36:37], v[138:139], v[90:91]
	v_pk_fma_f32 v[110:111], v[2:3], v[110:111], v[114:115]
	v_pk_fma_f32 v[90:91], v[32:33], v[134:135], v[90:91]
	v_pk_mul_f32 v[94:95], v[22:23], v[106:107]
	v_mul_f32_e32 v114, 0xbfb8aa3b, v90
	v_exp_f32_e32 v116, v114
	v_mul_f32_e32 v114, 0xbfb8aa3b, v91
	v_pk_fma_f32 v[94:95], v[6:7], v[128:129], v[94:95]
	v_exp_f32_e32 v117, v114
	v_pk_fma_f32 v[94:95], v[26:27], v[142:143], v[94:95]
	v_pk_fma_f32 v[112:113], v[16:17], v[140:141], v[112:113]
	v_pk_fma_f32 v[110:111], v[18:19], v[98:99], v[110:111]
	v_pk_fma_f32 v[94:95], v[38:39], v[136:137], v[94:95]
	v_pk_fma_f32 v[112:113], v[28:29], v[96:97], v[112:113]
	v_pk_fma_f32 v[110:111], v[30:31], v[92:93], v[110:111]
	v_pk_fma_f32 v[94:95], v[34:35], v[132:133], v[94:95]
	v_pk_fma_f32 v[112:113], v[8:9], v[130:131], v[112:113]
	v_pk_fma_f32 v[114:115], v[10:11], v[88:89], v[110:111]
	v_add_f32_e32 v110, 1.0, v116
	v_add_f32_e32 v111, 1.0, v117
	v_mul_f32_e32 v116, 0xbfb8aa3b, v94
	v_mul_f32_e32 v117, 0xbfb8aa3b, v95
	v_mul_f32_e32 v118, 0xbfb8aa3b, v112
	v_mul_f32_e32 v119, 0xbfb8aa3b, v113
	v_mul_f32_e32 v126, 0xbfb8aa3b, v114
	v_mul_f32_e32 v127, 0xbfb8aa3b, v115
	v_exp_f32_e32 v116, v116
	v_exp_f32_e32 v117, v117
	v_exp_f32_e32 v118, v118
	v_exp_f32_e32 v119, v119
	v_exp_f32_e32 v126, v126
	v_exp_f32_e32 v127, v127
	v_add_f32_e32 v116, 1.0, v116
	v_add_f32_e32 v117, 1.0, v117
	v_add_f32_e32 v118, 1.0, v118
	v_add_f32_e32 v119, 1.0, v119
	v_add_f32_e32 v126, 1.0, v126
	v_add_f32_e32 v127, 1.0, v127
	v_rcp_f32_e32 v110, v110
	v_rcp_f32_e32 v111, v111
	v_rcp_f32_e32 v116, v116
	v_rcp_f32_e32 v117, v117
	v_rcp_f32_e32 v118, v118
	v_rcp_f32_e32 v119, v119
	v_rcp_f32_e32 v126, v126
	v_rcp_f32_e32 v127, v127
	v_pk_mul_f32 v[90:91], v[90:91], v[110:111]
	v_pk_mul_f32 v[94:95], v[94:95], v[116:117]
	v_pk_mul_f32 v[110:111], v[112:113], v[118:119]
	v_pk_mul_f32 v[112:113], v[114:115], v[126:127]
	s_and_saveexec_b64 s[24:25], vcc
	s_cbranch_execz .LBB0_319
	v_pk_mul_f32 v[114:115], v[90:91], v[90:91]
	v_pk_mul_f32 v[116:117], v[94:95], v[94:95]
	v_add_f32_e32 v114, v114, v115
	v_add_f32_e32 v114, v116, v114
	v_pk_mul_f32 v[118:119], v[110:111], v[110:111]
	v_add_f32_e32 v114, v117, v114
	v_and_b32_e32 v116, 64, v158
	v_add_f32_e32 v114, v118, v114
	v_xor_b32_e32 v115, 1, v158
	v_add_u32_e32 v116, 64, v116
	v_pk_mul_f32 v[126:127], v[112:113], v[112:113]
	v_add_f32_e32 v114, v119, v114
	v_cmp_lt_i32_e64 s[4:5], v115, v116
	v_add_f32_e32 v114, v126, v114
	v_add_f32_e32 v114, v127, v114
	v_cndmask_b32_e64 v115, v158, v115, s[4:5]
	v_lshlrev_b32_e32 v115, 2, v115
	s_nop 1
	v_mov_b32_dpp v115, v114 quad_perm:[1,0,3,2] row_mask:0xf bank_mask:0xf
	s_waitcnt lgkmcnt(0)
	v_add_f32_e32 v114, v114, v115
	v_xor_b32_e32 v115, 2, v158
	v_cmp_lt_i32_e64 s[4:5], v115, v116
	s_nop 1
	v_cndmask_b32_e64 v115, v158, v115, s[4:5]
	v_lshlrev_b32_e32 v115, 2, v115
	s_nop 1
	v_mov_b32_dpp v115, v114 quad_perm:[2,3,0,1] row_mask:0xf bank_mask:0xf
	s_waitcnt lgkmcnt(0)
	v_add_f32_e32 v114, v114, v115
	v_xor_b32_e32 v115, 4, v158
	v_cmp_lt_i32_e64 s[4:5], v115, v116
	s_nop 1
	v_cndmask_b32_e64 v115, v158, v115, s[4:5]
	v_lshlrev_b32_e32 v115, 2, v115
	s_nop 1
	v_mov_b32_dpp v115, v114 row_half_mirror row_mask:0xf bank_mask:0xf
	s_waitcnt lgkmcnt(0)
	v_add_f32_e32 v114, v114, v115
	v_xor_b32_e32 v115, 8, v158
	v_cmp_lt_i32_e64 s[4:5], v115, v116
	s_nop 1
	v_cndmask_b32_e64 v115, v158, v115, s[4:5]
	v_lshlrev_b32_e32 v115, 2, v115
	s_nop 1
	v_mov_b32_dpp v115, v114 row_ror:8 row_mask:0xf bank_mask:0xf
	s_waitcnt lgkmcnt(0)
	v_add_f32_e32 v114, v114, v115
	v_add_f32_e32 v114, 0x358637bd, v114
	v_mul_f32_e32 v115, 0x4b800000, v114
	v_cmp_gt_f32_e64 s[4:5], s46, v114
	s_nop 1
	v_cndmask_b32_e64 v114, v114, v115, s[4:5]
	v_rsq_f32_e32 v114, v114
	s_nop 0
	v_mul_f32_e32 v115, 0x45800000, v114
	v_cndmask_b32_e64 v114, v114, v115, s[4:5]
	v_mul_f32_e32 v114, v157, v114
	v_pk_mul_f32 v[112:113], v[112:113], v[114:115] op_sel_hi:[1,0]
	v_pk_mul_f32 v[110:111], v[110:111], v[114:115] op_sel_hi:[1,0]
	v_pk_mul_f32 v[94:95], v[94:95], v[114:115] op_sel_hi:[1,0]
	v_pk_mul_f32 v[90:91], v[90:91], v[114:115] op_sel_hi:[1,0]
; DI unsigned pk2(float a, float b) { f32x2 v = {a, b}; bf16x2_t r = __builtin_convertvector(v, bf16x2_t); return __builtin_bit_cast(unsigned, r); }
; DI float bflo(unsigned u) { return __uint_as_float(u << 16); }
; DI float bfhi(unsigned u) { return __uint_as_float(u & 0xffff0000u); }
; DI float siluf_(float x) { return x * __builtin_amdgcn_rcpf(1.f + __expf(-x)); }
; DI void dn_conv_phase(const Params& p) {
;     ...
;         for (int tt = 0; tt < SEG; ++tt) {
;             { const u32x4 u = rows[tt + 4]; const int sl = (tt + 4) % 5;
;               ring[sl][0] = (f32x2){bflo(u.x), bfhi(u.x)}; ring[sl][1] = (f32x2){bflo(u.y), bfhi(u.y)}; ring[sl][2] = (f32x2){bflo(u.z), bfhi(u.z)}; ring[sl][3] = (f32x2){bflo(u.w), bfhi(u.w)}; }
;             f32x2 o2[4];
; #pragma unroll
;             for (int e = 0; e < 4; ++e) o2[e] = w[0][e] * ring[tt % 5][e];
; #pragma unroll
;             for (int j = 1; j < 5; ++j)
; #pragma unroll
;                 for (int e = 0; e < 4; ++e) o2[e] += w[j][e] * ring[(tt + j) % 5][e];
;             float o[8];
; #pragma unroll
;             for (int e = 0; e < 4; ++e) { o[2 * e] = siluf_(o2[e].x); o[2 * e + 1] = siluf_(o2[e].y); }
;             if (part < 2) {
;                 float ss = 0.f;
; #pragma unroll
;                 for (int e = 0; e < 8; ++e) ss += o[e] * o[e];
;                 ss += __shfl_xor(ss, 1); ss += __shfl_xor(ss, 2); ss += __shfl_xor(ss, 4); ss += __shfl_xor(ss, 8);
;                 const float sc = rsqrtf(ss + EPS) * (part == 0 ? 0.08838834764831845f : 1.f);
; #pragma unroll
;                 for (int e = 0; e < 8; ++e) o[e] *= sc;
;             }
;             u32x4 ov; ov.x = pk2(o[0], o[1]); ov.y = pk2(o[2], o[3]); ov.z = pk2(o[4], o[5]); ov.w = pk2(o[6], o[7]);
;             *(u32x4*)(QKV + (size_t)(row0 + tt) * 1536 + ch) = ov;
.LBB0_319:
	s_or_b64 exec, exec, s[24:25]
	v_cvt_pk_bf16_f32 v114, v90, v91
	v_or_b32_e32 v90, 3, v156
	v_cvt_pk_bf16_f32 v115, v94, v95
	v_cvt_pk_bf16_f32 v116, v110, v111
	v_cvt_pk_bf16_f32 v117, v112, v113
	v_mad_i64_i32 v[90:91], s[4:5], v90, s45, v[100:101]
	global_store_dwordx4 v[90:91], v[114:117], off
	v_lshlrev_b32_e32 v128, 16, v84
	v_and_b32_e32 v129, 0xffff0000, v84
	v_lshlrev_b32_e32 v126, 16, v85
	v_and_b32_e32 v127, 0xffff0000, v85
	v_lshlrev_b32_e32 v118, 16, v86
	v_and_b32_e32 v119, 0xffff0000, v86
	v_lshlrev_b32_e32 v116, 16, v87
	v_and_b32_e32 v117, 0xffff0000, v87
	v_pk_mul_f32 v[84:85], v[20:21], v[144:145]
	v_pk_mul_f32 v[86:87], v[22:23], v[142:143]
	v_pk_mul_f32 v[90:91], v[12:13], v[140:141]
	v_pk_mul_f32 v[94:95], v[14:15], v[98:99]
	v_pk_fma_f32 v[84:85], v[4:5], v[108:109], v[84:85]
	v_pk_fma_f32 v[86:87], v[6:7], v[106:107], v[86:87]
	v_pk_fma_f32 v[90:91], v[0:1], v[104:105], v[90:91]
	v_pk_fma_f32 v[94:95], v[2:3], v[102:103], v[94:95]
	v_pk_fma_f32 v[84:85], v[24:25], v[138:139], v[84:85]
	v_pk_fma_f32 v[86:87], v[26:27], v[136:137], v[86:87]
	v_pk_fma_f32 v[90:91], v[16:17], v[96:97], v[90:91]
	v_pk_fma_f32 v[94:95], v[18:19], v[92:93], v[94:95]
	v_pk_fma_f32 v[84:85], v[36:37], v[134:135], v[84:85]
	v_pk_fma_f32 v[86:87], v[38:39], v[132:133], v[86:87]
	v_pk_fma_f32 v[90:91], v[28:29], v[130:131], v[90:91]
	v_pk_fma_f32 v[94:95], v[30:31], v[88:89], v[94:95]
	v_pk_fma_f32 v[84:85], v[32:33], v[128:129], v[84:85]
	v_pk_fma_f32 v[86:87], v[34:35], v[126:127], v[86:87]
	v_pk_fma_f32 v[90:91], v[8:9], v[118:119], v[90:91]
	v_pk_fma_f32 v[94:95], v[10:11], v[116:117], v[94:95]
	v_mul_f32_e32 v102, 0xbfb8aa3b, v84
	v_mul_f32_e32 v103, 0xbfb8aa3b, v85
	v_mul_f32_e32 v104, 0xbfb8aa3b, v86
	v_mul_f32_e32 v105, 0xbfb8aa3b, v87
	v_mul_f32_e32 v106, 0xbfb8aa3b, v90
	v_mul_f32_e32 v107, 0xbfb8aa3b, v91
	v_mul_f32_e32 v108, 0xbfb8aa3b, v94
	v_mul_f32_e32 v109, 0xbfb8aa3b, v95
	v_exp_f32_e32 v102, v102
	v_exp_f32_e32 v103, v103
	v_exp_f32_e32 v104, v104
	v_exp_f32_e32 v105, v105
	v_exp_f32_e32 v106, v106
	v_exp_f32_e32 v107, v107
	v_exp_f32_e32 v108, v108
	v_exp_f32_e32 v109, v109
	v_add_f32_e32 v102, 1.0, v102
	v_add_f32_e32 v103, 1.0, v103
	v_add_f32_e32 v104, 1.0, v104
	v_add_f32_e32 v105, 1.0, v105
	v_add_f32_e32 v106, 1.0, v106
	v_add_f32_e32 v107, 1.0, v107
	v_add_f32_e32 v108, 1.0, v108
	v_add_f32_e32 v109, 1.0, v109
	v_rcp_f32_e32 v102, v102
	v_rcp_f32_e32 v103, v103
	v_rcp_f32_e32 v104, v104
	v_rcp_f32_e32 v105, v105
	v_rcp_f32_e32 v106, v106
	v_rcp_f32_e32 v107, v107
	v_rcp_f32_e32 v108, v108
	v_rcp_f32_e32 v109, v109
	v_pk_mul_f32 v[84:85], v[84:85], v[102:103]
	v_pk_mul_f32 v[86:87], v[86:87], v[104:105]
	v_pk_mul_f32 v[90:91], v[90:91], v[106:107]
	v_pk_mul_f32 v[94:95], v[94:95], v[108:109]
	s_and_saveexec_b64 s[24:25], vcc
	s_cbranch_execz .LBB0_321
	v_pk_mul_f32 v[102:103], v[84:85], v[84:85]
	v_pk_mul_f32 v[104:105], v[86:87], v[86:87]
	v_add_f32_e32 v102, v102, v103
	v_add_f32_e32 v102, v104, v102
	v_pk_mul_f32 v[106:107], v[90:91], v[90:91]
	v_add_f32_e32 v102, v105, v102
	v_and_b32_e32 v104, 64, v158
	v_add_f32_e32 v102, v106, v102
	v_xor_b32_e32 v103, 1, v158
	v_add_u32_e32 v104, 64, v104
	v_pk_mul_f32 v[108:109], v[94:95], v[94:95]
	v_add_f32_e32 v102, v107, v102
	v_cmp_lt_i32_e64 s[4:5], v103, v104
	v_add_f32_e32 v102, v108, v102
	v_add_f32_e32 v102, v109, v102
	v_cndmask_b32_e64 v103, v158, v103, s[4:5]
	v_lshlrev_b32_e32 v103, 2, v103
	s_nop 1
	v_mov_b32_dpp v103, v102 quad_perm:[1,0,3,2] row_mask:0xf bank_mask:0xf
	s_waitcnt lgkmcnt(0)
	v_add_f32_e32 v102, v102, v103
	v_xor_b32_e32 v103, 2, v158
	v_cmp_lt_i32_e64 s[4:5], v103, v104
	s_nop 1
	v_cndmask_b32_e64 v103, v158, v103, s[4:5]
	v_lshlrev_b32_e32 v103, 2, v103
	s_nop 1
	v_mov_b32_dpp v103, v102 quad_perm:[2,3,0,1] row_mask:0xf bank_mask:0xf
	s_waitcnt lgkmcnt(0)
	v_add_f32_e32 v102, v102, v103
	v_xor_b32_e32 v103, 4, v158
	v_cmp_lt_i32_e64 s[4:5], v103, v104
	s_nop 1
	v_cndmask_b32_e64 v103, v158, v103, s[4:5]
	v_lshlrev_b32_e32 v103, 2, v103
	s_nop 1
	v_mov_b32_dpp v103, v102 row_half_mirror row_mask:0xf bank_mask:0xf
	s_waitcnt lgkmcnt(0)
	v_add_f32_e32 v102, v102, v103
	v_xor_b32_e32 v103, 8, v158
	v_cmp_lt_i32_e64 s[4:5], v103, v104
	s_nop 1
	v_cndmask_b32_e64 v103, v158, v103, s[4:5]
	v_lshlrev_b32_e32 v103, 2, v103
	s_nop 1
	v_mov_b32_dpp v103, v102 row_ror:8 row_mask:0xf bank_mask:0xf
	s_waitcnt lgkmcnt(0)
	v_add_f32_e32 v102, v102, v103
	v_add_f32_e32 v102, 0x358637bd, v102
	v_mul_f32_e32 v103, 0x4b800000, v102
	v_cmp_gt_f32_e64 s[4:5], s46, v102
	s_nop 1
	v_cndmask_b32_e64 v102, v102, v103, s[4:5]
	v_rsq_f32_e32 v102, v102
	s_nop 0
	v_mul_f32_e32 v103, 0x45800000, v102
	v_cndmask_b32_e64 v102, v102, v103, s[4:5]
	v_mul_f32_e32 v102, v157, v102
	v_pk_mul_f32 v[94:95], v[94:95], v[102:103] op_sel_hi:[1,0]
	v_pk_mul_f32 v[90:91], v[90:91], v[102:103] op_sel_hi:[1,0]
	v_pk_mul_f32 v[86:87], v[86:87], v[102:103] op_sel_hi:[1,0]
	v_pk_mul_f32 v[84:85], v[84:85], v[102:103] op_sel_hi:[1,0]
; DI unsigned pk2(float a, float b) { f32x2 v = {a, b}; bf16x2_t r = __builtin_convertvector(v, bf16x2_t); return __builtin_bit_cast(unsigned, r); }
; DI float bflo(unsigned u) { return __uint_as_float(u << 16); }
; DI float bfhi(unsigned u) { return __uint_as_float(u & 0xffff0000u); }
; DI float siluf_(float x) { return x * __builtin_amdgcn_rcpf(1.f + __expf(-x)); }
; DI void dn_conv_phase(const Params& p) {
;     ...
;         for (int tt = 0; tt < SEG; ++tt) {
;             { const u32x4 u = rows[tt + 4]; const int sl = (tt + 4) % 5;
;               ring[sl][0] = (f32x2){bflo(u.x), bfhi(u.x)}; ring[sl][1] = (f32x2){bflo(u.y), bfhi(u.y)}; ring[sl][2] = (f32x2){bflo(u.z), bfhi(u.z)}; ring[sl][3] = (f32x2){bflo(u.w), bfhi(u.w)}; }
;             f32x2 o2[4];
; #pragma unroll
;             for (int e = 0; e < 4; ++e) o2[e] = w[0][e] * ring[tt % 5][e];
; #pragma unroll
;             for (int j = 1; j < 5; ++j)
; #pragma unroll
;                 for (int e = 0; e < 4; ++e) o2[e] += w[j][e] * ring[(tt + j) % 5][e];
;             float o[8];
; #pragma unroll
;             for (int e = 0; e < 4; ++e) { o[2 * e] = siluf_(o2[e].x); o[2 * e + 1] = siluf_(o2[e].y); }
;             if (part < 2) {
;                 float ss = 0.f;
; #pragma unroll
;                 for (int e = 0; e < 8; ++e) ss += o[e] * o[e];
;                 ss += __shfl_xor(ss, 1); ss += __shfl_xor(ss, 2); ss += __shfl_xor(ss, 4); ss += __shfl_xor(ss, 8);
;                 const float sc = rsqrtf(ss + EPS) * (part == 0 ? 0.08838834764831845f : 1.f);
; #pragma unroll
;                 for (int e = 0; e < 8; ++e) o[e] *= sc;
;             }
;             u32x4 ov; ov.x = pk2(o[0], o[1]); ov.y = pk2(o[2], o[3]); ov.z = pk2(o[4], o[5]); ov.w = pk2(o[6], o[7]);
;             *(u32x4*)(QKV + (size_t)(row0 + tt) * 1536 + ch) = ov;
.LBB0_321:
	s_or_b64 exec, exec, s[24:25]
	v_cvt_pk_bf16_f32 v84, v84, v85
	v_cvt_pk_bf16_f32 v85, v86, v87
	v_cvt_pk_bf16_f32 v86, v90, v91
	v_or_b32_e32 v90, 4, v156
	v_cvt_pk_bf16_f32 v87, v94, v95
	v_mad_i64_i32 v[90:91], s[4:5], v90, s45, v[100:101]
	global_store_dwordx4 v[90:91], v[84:87], off
	v_lshlrev_b32_e32 v114, 16, v80
	v_and_b32_e32 v115, 0xffff0000, v80
	v_lshlrev_b32_e32 v112, 16, v81
	v_and_b32_e32 v113, 0xffff0000, v81
	v_lshlrev_b32_e32 v110, 16, v82
	v_and_b32_e32 v111, 0xffff0000, v82
	v_lshlrev_b32_e32 v108, 16, v83
	v_and_b32_e32 v109, 0xffff0000, v83
	v_pk_mul_f32 v[80:81], v[20:21], v[138:139]
	v_pk_mul_f32 v[82:83], v[22:23], v[136:137]
	v_pk_mul_f32 v[84:85], v[12:13], v[96:97]
	v_pk_mul_f32 v[86:87], v[14:15], v[92:93]
	v_pk_fma_f32 v[80:81], v[4:5], v[144:145], v[80:81]
	v_pk_fma_f32 v[82:83], v[6:7], v[142:143], v[82:83]
	v_pk_fma_f32 v[84:85], v[0:1], v[140:141], v[84:85]
	v_pk_fma_f32 v[86:87], v[2:3], v[98:99], v[86:87]
	v_pk_fma_f32 v[80:81], v[24:25], v[134:135], v[80:81]
	v_pk_fma_f32 v[82:83], v[26:27], v[132:133], v[82:83]
	v_pk_fma_f32 v[84:85], v[16:17], v[130:131], v[84:85]
	v_pk_fma_f32 v[86:87], v[18:19], v[88:89], v[86:87]
	v_pk_fma_f32 v[80:81], v[36:37], v[128:129], v[80:81]
	v_pk_fma_f32 v[82:83], v[38:39], v[126:127], v[82:83]
	v_pk_fma_f32 v[84:85], v[28:29], v[118:119], v[84:85]
	v_pk_fma_f32 v[86:87], v[30:31], v[116:117], v[86:87]
	v_pk_fma_f32 v[80:81], v[32:33], v[114:115], v[80:81]
	v_pk_fma_f32 v[82:83], v[34:35], v[112:113], v[82:83]
	v_pk_fma_f32 v[84:85], v[8:9], v[110:111], v[84:85]
	v_pk_fma_f32 v[86:87], v[10:11], v[108:109], v[86:87]
	v_mul_f32_e32 v90, 0xbfb8aa3b, v80
	v_mul_f32_e32 v91, 0xbfb8aa3b, v81
	v_mul_f32_e32 v94, 0xbfb8aa3b, v82
	v_mul_f32_e32 v95, 0xbfb8aa3b, v83
	v_mul_f32_e32 v98, 0xbfb8aa3b, v84
	v_mul_f32_e32 v99, 0xbfb8aa3b, v85
	v_mul_f32_e32 v102, 0xbfb8aa3b, v86
	v_mul_f32_e32 v103, 0xbfb8aa3b, v87
	v_exp_f32_e32 v90, v90
	v_exp_f32_e32 v91, v91
	v_exp_f32_e32 v94, v94
	v_exp_f32_e32 v95, v95
	v_exp_f32_e32 v98, v98
	v_exp_f32_e32 v99, v99
	v_exp_f32_e32 v102, v102
	v_exp_f32_e32 v103, v103
	v_add_f32_e32 v90, 1.0, v90
	v_add_f32_e32 v91, 1.0, v91
	v_add_f32_e32 v94, 1.0, v94
	v_add_f32_e32 v95, 1.0, v95
	v_add_f32_e32 v98, 1.0, v98
	v_add_f32_e32 v99, 1.0, v99
	v_add_f32_e32 v102, 1.0, v102
	v_add_f32_e32 v103, 1.0, v103
	v_rcp_f32_e32 v90, v90
	v_rcp_f32_e32 v91, v91
	v_rcp_f32_e32 v94, v94
	v_rcp_f32_e32 v95, v95
	v_rcp_f32_e32 v98, v98
	v_rcp_f32_e32 v99, v99
	v_rcp_f32_e32 v102, v102
	v_rcp_f32_e32 v103, v103
	v_pk_mul_f32 v[80:81], v[80:81], v[90:91]
	v_pk_mul_f32 v[82:83], v[82:83], v[94:95]
	v_pk_mul_f32 v[84:85], v[84:85], v[98:99]
	v_pk_mul_f32 v[86:87], v[86:87], v[102:103]
	s_and_saveexec_b64 s[24:25], vcc
	s_cbranch_execz .LBB0_323
	v_pk_mul_f32 v[90:91], v[80:81], v[80:81]
	v_pk_mul_f32 v[94:95], v[82:83], v[82:83]
	v_add_f32_e32 v90, v90, v91
	v_add_f32_e32 v90, v94, v90
	v_pk_mul_f32 v[98:99], v[84:85], v[84:85]
	v_add_f32_e32 v90, v95, v90
	v_and_b32_e32 v94, 64, v158
	v_add_f32_e32 v90, v98, v90
	v_xor_b32_e32 v91, 1, v158
	v_add_u32_e32 v94, 64, v94
	v_pk_mul_f32 v[102:103], v[86:87], v[86:87]
	v_add_f32_e32 v90, v99, v90
	v_cmp_lt_i32_e64 s[4:5], v91, v94
	v_add_f32_e32 v90, v102, v90
	v_add_f32_e32 v90, v103, v90
	v_cndmask_b32_e64 v91, v158, v91, s[4:5]
	v_lshlrev_b32_e32 v91, 2, v91
	s_nop 1
	v_mov_b32_dpp v91, v90 quad_perm:[1,0,3,2] row_mask:0xf bank_mask:0xf
	s_waitcnt lgkmcnt(0)
	v_add_f32_e32 v90, v90, v91
	v_xor_b32_e32 v91, 2, v158
	v_cmp_lt_i32_e64 s[4:5], v91, v94
	s_nop 1
	v_cndmask_b32_e64 v91, v158, v91, s[4:5]
	v_lshlrev_b32_e32 v91, 2, v91
	s_nop 1
	v_mov_b32_dpp v91, v90 quad_perm:[2,3,0,1] row_mask:0xf bank_mask:0xf
	s_waitcnt lgkmcnt(0)
	v_add_f32_e32 v90, v90, v91
	v_xor_b32_e32 v91, 4, v158
	v_cmp_lt_i32_e64 s[4:5], v91, v94
	s_nop 1
	v_cndmask_b32_e64 v91, v158, v91, s[4:5]
	v_lshlrev_b32_e32 v91, 2, v91
	s_nop 1
	v_mov_b32_dpp v91, v90 row_half_mirror row_mask:0xf bank_mask:0xf
	s_waitcnt lgkmcnt(0)
	v_add_f32_e32 v90, v90, v91
	v_xor_b32_e32 v91, 8, v158
	v_cmp_lt_i32_e64 s[4:5], v91, v94
	s_nop 1
	v_cndmask_b32_e64 v91, v158, v91, s[4:5]
	v_lshlrev_b32_e32 v91, 2, v91
	s_nop 1
	v_mov_b32_dpp v91, v90 row_ror:8 row_mask:0xf bank_mask:0xf
	s_waitcnt lgkmcnt(0)
	v_add_f32_e32 v90, v90, v91
	v_add_f32_e32 v90, 0x358637bd, v90
	v_mul_f32_e32 v91, 0x4b800000, v90
	v_cmp_gt_f32_e64 s[4:5], s46, v90
	s_nop 1
	v_cndmask_b32_e64 v90, v90, v91, s[4:5]
	v_rsq_f32_e32 v90, v90
	s_nop 0
	v_mul_f32_e32 v91, 0x45800000, v90
	v_cndmask_b32_e64 v90, v90, v91, s[4:5]
	v_mul_f32_e32 v90, v157, v90
	v_pk_mul_f32 v[86:87], v[86:87], v[90:91] op_sel_hi:[1,0]
	v_pk_mul_f32 v[84:85], v[84:85], v[90:91] op_sel_hi:[1,0]
	v_pk_mul_f32 v[82:83], v[82:83], v[90:91] op_sel_hi:[1,0]
	v_pk_mul_f32 v[80:81], v[80:81], v[90:91] op_sel_hi:[1,0]
; DI unsigned pk2(float a, float b) { f32x2 v = {a, b}; bf16x2_t r = __builtin_convertvector(v, bf16x2_t); return __builtin_bit_cast(unsigned, r); }
; DI float bflo(unsigned u) { return __uint_as_float(u << 16); }
; DI float bfhi(unsigned u) { return __uint_as_float(u & 0xffff0000u); }
; DI float siluf_(float x) { return x * __builtin_amdgcn_rcpf(1.f + __expf(-x)); }
; DI void dn_conv_phase(const Params& p) {
;     ...
;         for (int tt = 0; tt < SEG; ++tt) {
;             { const u32x4 u = rows[tt + 4]; const int sl = (tt + 4) % 5;
;               ring[sl][0] = (f32x2){bflo(u.x), bfhi(u.x)}; ring[sl][1] = (f32x2){bflo(u.y), bfhi(u.y)}; ring[sl][2] = (f32x2){bflo(u.z), bfhi(u.z)}; ring[sl][3] = (f32x2){bflo(u.w), bfhi(u.w)}; }
;             f32x2 o2[4];
; #pragma unroll
;             for (int e = 0; e < 4; ++e) o2[e] = w[0][e] * ring[tt % 5][e];
; #pragma unroll
;             for (int j = 1; j < 5; ++j)
; #pragma unroll
;                 for (int e = 0; e < 4; ++e) o2[e] += w[j][e] * ring[(tt + j) % 5][e];
;             float o[8];
; #pragma unroll
;             for (int e = 0; e < 4; ++e) { o[2 * e] = siluf_(o2[e].x); o[2 * e + 1] = siluf_(o2[e].y); }
;             if (part < 2) {
;                 float ss = 0.f;
; #pragma unroll
;                 for (int e = 0; e < 8; ++e) ss += o[e] * o[e];
;                 ss += __shfl_xor(ss, 1); ss += __shfl_xor(ss, 2); ss += __shfl_xor(ss, 4); ss += __shfl_xor(ss, 8);
;                 const float sc = rsqrtf(ss + EPS) * (part == 0 ? 0.08838834764831845f : 1.f);
; #pragma unroll
;                 for (int e = 0; e < 8; ++e) o[e] *= sc;
;             }
;             u32x4 ov; ov.x = pk2(o[0], o[1]); ov.y = pk2(o[2], o[3]); ov.z = pk2(o[4], o[5]); ov.w = pk2(o[6], o[7]);
;             *(u32x4*)(QKV + (size_t)(row0 + tt) * 1536 + ch) = ov;
.LBB0_323:
	s_or_b64 exec, exec, s[24:25]
	v_cvt_pk_bf16_f32 v80, v80, v81
	v_cvt_pk_bf16_f32 v81, v82, v83
	v_cvt_pk_bf16_f32 v82, v84, v85
	v_or_b32_e32 v84, 5, v156
	v_cvt_pk_bf16_f32 v83, v86, v87
	v_mad_i64_i32 v[84:85], s[4:5], v84, s45, v[100:101]
	global_store_dwordx4 v[84:85], v[80:83], off
	v_lshlrev_b32_e32 v106, 16, v76
	v_and_b32_e32 v107, 0xffff0000, v76
	v_lshlrev_b32_e32 v104, 16, v77
	v_and_b32_e32 v105, 0xffff0000, v77
	v_lshlrev_b32_e32 v102, 16, v78
	v_and_b32_e32 v103, 0xffff0000, v78
	v_lshlrev_b32_e32 v98, 16, v79
	v_and_b32_e32 v99, 0xffff0000, v79
	v_pk_mul_f32 v[76:77], v[20:21], v[134:135]
	v_pk_mul_f32 v[78:79], v[22:23], v[132:133]
	v_pk_mul_f32 v[80:81], v[12:13], v[130:131]
	v_pk_mul_f32 v[82:83], v[14:15], v[88:89]
	v_pk_fma_f32 v[76:77], v[4:5], v[138:139], v[76:77]
	v_pk_fma_f32 v[78:79], v[6:7], v[136:137], v[78:79]
	v_pk_fma_f32 v[80:81], v[0:1], v[96:97], v[80:81]
	v_pk_fma_f32 v[82:83], v[2:3], v[92:93], v[82:83]
	v_pk_fma_f32 v[76:77], v[24:25], v[128:129], v[76:77]
	v_pk_fma_f32 v[78:79], v[26:27], v[126:127], v[78:79]
	v_pk_fma_f32 v[80:81], v[16:17], v[118:119], v[80:81]
	v_pk_fma_f32 v[82:83], v[18:19], v[116:117], v[82:83]
	v_pk_fma_f32 v[76:77], v[36:37], v[114:115], v[76:77]
	v_pk_fma_f32 v[78:79], v[38:39], v[112:113], v[78:79]
	v_pk_fma_f32 v[80:81], v[28:29], v[110:111], v[80:81]
	v_pk_fma_f32 v[82:83], v[30:31], v[108:109], v[82:83]
	v_pk_fma_f32 v[76:77], v[32:33], v[106:107], v[76:77]
	v_pk_fma_f32 v[78:79], v[34:35], v[104:105], v[78:79]
	v_pk_fma_f32 v[80:81], v[8:9], v[102:103], v[80:81]
	v_pk_fma_f32 v[82:83], v[10:11], v[98:99], v[82:83]
	v_mul_f32_e32 v84, 0xbfb8aa3b, v76
	v_mul_f32_e32 v85, 0xbfb8aa3b, v77
	v_mul_f32_e32 v86, 0xbfb8aa3b, v78
	v_mul_f32_e32 v87, 0xbfb8aa3b, v79
	v_mul_f32_e32 v90, 0xbfb8aa3b, v80
	v_mul_f32_e32 v91, 0xbfb8aa3b, v81
	v_mul_f32_e32 v92, 0xbfb8aa3b, v82
	v_mul_f32_e32 v93, 0xbfb8aa3b, v83
	v_exp_f32_e32 v84, v84
	v_exp_f32_e32 v85, v85
	v_exp_f32_e32 v86, v86
	v_exp_f32_e32 v87, v87
	v_exp_f32_e32 v90, v90
	v_exp_f32_e32 v91, v91
	v_exp_f32_e32 v92, v92
	v_exp_f32_e32 v93, v93
	v_add_f32_e32 v84, 1.0, v84
	v_add_f32_e32 v85, 1.0, v85
	v_add_f32_e32 v86, 1.0, v86
	v_add_f32_e32 v87, 1.0, v87
	v_add_f32_e32 v90, 1.0, v90
	v_add_f32_e32 v91, 1.0, v91
	v_add_f32_e32 v92, 1.0, v92
	v_add_f32_e32 v93, 1.0, v93
	v_rcp_f32_e32 v84, v84
	v_rcp_f32_e32 v85, v85
	v_rcp_f32_e32 v86, v86
	v_rcp_f32_e32 v87, v87
	v_rcp_f32_e32 v90, v90
	v_rcp_f32_e32 v91, v91
	v_rcp_f32_e32 v92, v92
	v_rcp_f32_e32 v93, v93
	v_pk_mul_f32 v[76:77], v[76:77], v[84:85]
	v_pk_mul_f32 v[78:79], v[78:79], v[86:87]
	v_pk_mul_f32 v[80:81], v[80:81], v[90:91]
	v_pk_mul_f32 v[82:83], v[82:83], v[92:93]
	s_and_saveexec_b64 s[24:25], vcc
	s_cbranch_execz .LBB0_325
	v_pk_mul_f32 v[84:85], v[76:77], v[76:77]
	v_pk_mul_f32 v[86:87], v[78:79], v[78:79]
	v_add_f32_e32 v84, v84, v85
	v_add_f32_e32 v84, v86, v84
	v_pk_mul_f32 v[90:91], v[80:81], v[80:81]
	v_add_f32_e32 v84, v87, v84
	v_and_b32_e32 v86, 64, v158
	v_add_f32_e32 v84, v90, v84
	v_xor_b32_e32 v85, 1, v158
	v_add_u32_e32 v86, 64, v86
	v_pk_mul_f32 v[92:93], v[82:83], v[82:83]
	v_add_f32_e32 v84, v91, v84
	v_cmp_lt_i32_e64 s[4:5], v85, v86
	v_add_f32_e32 v84, v92, v84
	v_add_f32_e32 v84, v93, v84
	v_cndmask_b32_e64 v85, v158, v85, s[4:5]
	v_lshlrev_b32_e32 v85, 2, v85
	s_nop 1
	v_mov_b32_dpp v85, v84 quad_perm:[1,0,3,2] row_mask:0xf bank_mask:0xf
	s_waitcnt lgkmcnt(0)
	v_add_f32_e32 v84, v84, v85
	v_xor_b32_e32 v85, 2, v158
	v_cmp_lt_i32_e64 s[4:5], v85, v86
	s_nop 1
	v_cndmask_b32_e64 v85, v158, v85, s[4:5]
	v_lshlrev_b32_e32 v85, 2, v85
	s_nop 1
	v_mov_b32_dpp v85, v84 quad_perm:[2,3,0,1] row_mask:0xf bank_mask:0xf
	s_waitcnt lgkmcnt(0)
	v_add_f32_e32 v84, v84, v85
	v_xor_b32_e32 v85, 4, v158
	v_cmp_lt_i32_e64 s[4:5], v85, v86
	s_nop 1
	v_cndmask_b32_e64 v85, v158, v85, s[4:5]
	v_lshlrev_b32_e32 v85, 2, v85
	s_nop 1
	v_mov_b32_dpp v85, v84 row_half_mirror row_mask:0xf bank_mask:0xf
	s_waitcnt lgkmcnt(0)
	v_add_f32_e32 v84, v84, v85
	v_xor_b32_e32 v85, 8, v158
	v_cmp_lt_i32_e64 s[4:5], v85, v86
	s_nop 1
	v_cndmask_b32_e64 v85, v158, v85, s[4:5]
	v_lshlrev_b32_e32 v85, 2, v85
	s_nop 1
	v_mov_b32_dpp v85, v84 row_ror:8 row_mask:0xf bank_mask:0xf
	s_waitcnt lgkmcnt(0)
	v_add_f32_e32 v84, v84, v85
	v_add_f32_e32 v84, 0x358637bd, v84
	v_mul_f32_e32 v85, 0x4b800000, v84
	v_cmp_gt_f32_e64 s[4:5], s46, v84
	s_nop 1
	v_cndmask_b32_e64 v84, v84, v85, s[4:5]
	v_rsq_f32_e32 v84, v84
	s_nop 0
	v_mul_f32_e32 v85, 0x45800000, v84
	v_cndmask_b32_e64 v84, v84, v85, s[4:5]
	v_mul_f32_e32 v84, v157, v84
	v_pk_mul_f32 v[82:83], v[82:83], v[84:85] op_sel_hi:[1,0]
	v_pk_mul_f32 v[80:81], v[80:81], v[84:85] op_sel_hi:[1,0]
	v_pk_mul_f32 v[78:79], v[78:79], v[84:85] op_sel_hi:[1,0]
	v_pk_mul_f32 v[76:77], v[76:77], v[84:85] op_sel_hi:[1,0]
; DI unsigned pk2(float a, float b) { f32x2 v = {a, b}; bf16x2_t r = __builtin_convertvector(v, bf16x2_t); return __builtin_bit_cast(unsigned, r); }
; DI float bflo(unsigned u) { return __uint_as_float(u << 16); }
; DI float bfhi(unsigned u) { return __uint_as_float(u & 0xffff0000u); }
; DI float siluf_(float x) { return x * __builtin_amdgcn_rcpf(1.f + __expf(-x)); }
; DI void dn_conv_phase(const Params& p) {
;     ...
;         for (int tt = 0; tt < SEG; ++tt) {
;             { const u32x4 u = rows[tt + 4]; const int sl = (tt + 4) % 5;
;               ring[sl][0] = (f32x2){bflo(u.x), bfhi(u.x)}; ring[sl][1] = (f32x2){bflo(u.y), bfhi(u.y)}; ring[sl][2] = (f32x2){bflo(u.z), bfhi(u.z)}; ring[sl][3] = (f32x2){bflo(u.w), bfhi(u.w)}; }
;             f32x2 o2[4];
; #pragma unroll
;             for (int e = 0; e < 4; ++e) o2[e] = w[0][e] * ring[tt % 5][e];
; #pragma unroll
;             for (int j = 1; j < 5; ++j)
; #pragma unroll
;                 for (int e = 0; e < 4; ++e) o2[e] += w[j][e] * ring[(tt + j) % 5][e];
;             float o[8];
; #pragma unroll
;             for (int e = 0; e < 4; ++e) { o[2 * e] = siluf_(o2[e].x); o[2 * e + 1] = siluf_(o2[e].y); }
;             if (part < 2) {
;                 float ss = 0.f;
; #pragma unroll
;                 for (int e = 0; e < 8; ++e) ss += o[e] * o[e];
;                 ss += __shfl_xor(ss, 1); ss += __shfl_xor(ss, 2); ss += __shfl_xor(ss, 4); ss += __shfl_xor(ss, 8);
;                 const float sc = rsqrtf(ss + EPS) * (part == 0 ? 0.08838834764831845f : 1.f);
; #pragma unroll
;                 for (int e = 0; e < 8; ++e) o[e] *= sc;
;             }
;             u32x4 ov; ov.x = pk2(o[0], o[1]); ov.y = pk2(o[2], o[3]); ov.z = pk2(o[4], o[5]); ov.w = pk2(o[6], o[7]);
;             *(u32x4*)(QKV + (size_t)(row0 + tt) * 1536 + ch) = ov;
.LBB0_325:
	s_or_b64 exec, exec, s[24:25]
	v_cvt_pk_bf16_f32 v76, v76, v77
	v_cvt_pk_bf16_f32 v77, v78, v79
	v_cvt_pk_bf16_f32 v78, v80, v81
	v_or_b32_e32 v80, 6, v156
	v_cvt_pk_bf16_f32 v79, v82, v83
	v_mad_i64_i32 v[80:81], s[4:5], v80, s45, v[100:101]
	global_store_dwordx4 v[80:81], v[76:79], off
	v_lshlrev_b32_e32 v96, 16, v72
	v_and_b32_e32 v97, 0xffff0000, v72
	v_lshlrev_b32_e32 v94, 16, v73
	v_and_b32_e32 v95, 0xffff0000, v73
	v_lshlrev_b32_e32 v92, 16, v74
	v_and_b32_e32 v93, 0xffff0000, v74
	v_lshlrev_b32_e32 v90, 16, v75
	v_and_b32_e32 v91, 0xffff0000, v75
	v_pk_mul_f32 v[72:73], v[20:21], v[128:129]
	v_pk_mul_f32 v[74:75], v[22:23], v[126:127]
	v_pk_mul_f32 v[76:77], v[12:13], v[118:119]
	v_pk_mul_f32 v[78:79], v[14:15], v[116:117]
	v_pk_fma_f32 v[72:73], v[4:5], v[134:135], v[72:73]
	v_pk_fma_f32 v[74:75], v[6:7], v[132:133], v[74:75]
	v_pk_fma_f32 v[76:77], v[0:1], v[130:131], v[76:77]
	v_pk_fma_f32 v[78:79], v[2:3], v[88:89], v[78:79]
	v_pk_fma_f32 v[72:73], v[24:25], v[114:115], v[72:73]
	v_pk_fma_f32 v[74:75], v[26:27], v[112:113], v[74:75]
	v_pk_fma_f32 v[76:77], v[16:17], v[110:111], v[76:77]
	v_pk_fma_f32 v[78:79], v[18:19], v[108:109], v[78:79]
	v_pk_fma_f32 v[72:73], v[36:37], v[106:107], v[72:73]
	v_pk_fma_f32 v[74:75], v[38:39], v[104:105], v[74:75]
	v_pk_fma_f32 v[76:77], v[28:29], v[102:103], v[76:77]
	v_pk_fma_f32 v[78:79], v[30:31], v[98:99], v[78:79]
	v_pk_fma_f32 v[72:73], v[32:33], v[96:97], v[72:73]
	v_pk_fma_f32 v[74:75], v[34:35], v[94:95], v[74:75]
	v_pk_fma_f32 v[76:77], v[8:9], v[92:93], v[76:77]
	v_pk_fma_f32 v[78:79], v[10:11], v[90:91], v[78:79]
	v_mul_f32_e32 v80, 0xbfb8aa3b, v72
	v_mul_f32_e32 v81, 0xbfb8aa3b, v73
	v_mul_f32_e32 v82, 0xbfb8aa3b, v74
	v_mul_f32_e32 v83, 0xbfb8aa3b, v75
	v_mul_f32_e32 v84, 0xbfb8aa3b, v76
	v_mul_f32_e32 v85, 0xbfb8aa3b, v77
	v_mul_f32_e32 v86, 0xbfb8aa3b, v78
	v_mul_f32_e32 v87, 0xbfb8aa3b, v79
	v_exp_f32_e32 v80, v80
	v_exp_f32_e32 v81, v81
	v_exp_f32_e32 v82, v82
	v_exp_f32_e32 v83, v83
	v_exp_f32_e32 v84, v84
	v_exp_f32_e32 v85, v85
	v_exp_f32_e32 v86, v86
	v_exp_f32_e32 v87, v87
	v_add_f32_e32 v80, 1.0, v80
	v_add_f32_e32 v81, 1.0, v81
	v_add_f32_e32 v82, 1.0, v82
	v_add_f32_e32 v83, 1.0, v83
	v_add_f32_e32 v84, 1.0, v84
	v_add_f32_e32 v85, 1.0, v85
	v_add_f32_e32 v86, 1.0, v86
	v_add_f32_e32 v87, 1.0, v87
	v_rcp_f32_e32 v80, v80
	v_rcp_f32_e32 v81, v81
	v_rcp_f32_e32 v82, v82
	v_rcp_f32_e32 v83, v83
	v_rcp_f32_e32 v84, v84
	v_rcp_f32_e32 v85, v85
	v_rcp_f32_e32 v86, v86
	v_rcp_f32_e32 v87, v87
	v_pk_mul_f32 v[72:73], v[72:73], v[80:81]
	v_pk_mul_f32 v[74:75], v[74:75], v[82:83]
	v_pk_mul_f32 v[76:77], v[76:77], v[84:85]
	v_pk_mul_f32 v[78:79], v[78:79], v[86:87]
	s_and_saveexec_b64 s[24:25], vcc
	s_cbranch_execz .LBB0_327
	v_pk_mul_f32 v[80:81], v[72:73], v[72:73]
	v_pk_mul_f32 v[82:83], v[74:75], v[74:75]
	v_add_f32_e32 v80, v80, v81
	v_add_f32_e32 v80, v82, v80
	v_pk_mul_f32 v[84:85], v[76:77], v[76:77]
	v_add_f32_e32 v80, v83, v80
	v_and_b32_e32 v82, 64, v158
	v_add_f32_e32 v80, v84, v80
	v_xor_b32_e32 v81, 1, v158
	v_add_u32_e32 v82, 64, v82
	v_pk_mul_f32 v[86:87], v[78:79], v[78:79]
	v_add_f32_e32 v80, v85, v80
	v_cmp_lt_i32_e64 s[4:5], v81, v82
	v_add_f32_e32 v80, v86, v80
	v_add_f32_e32 v80, v87, v80
	v_cndmask_b32_e64 v81, v158, v81, s[4:5]
	v_lshlrev_b32_e32 v81, 2, v81
	s_nop 1
	v_mov_b32_dpp v81, v80 quad_perm:[1,0,3,2] row_mask:0xf bank_mask:0xf
	s_waitcnt lgkmcnt(0)
	v_add_f32_e32 v80, v80, v81
	v_xor_b32_e32 v81, 2, v158
	v_cmp_lt_i32_e64 s[4:5], v81, v82
	s_nop 1
	v_cndmask_b32_e64 v81, v158, v81, s[4:5]
	v_lshlrev_b32_e32 v81, 2, v81
	s_nop 1
	v_mov_b32_dpp v81, v80 quad_perm:[2,3,0,1] row_mask:0xf bank_mask:0xf
	s_waitcnt lgkmcnt(0)
	v_add_f32_e32 v80, v80, v81
	v_xor_b32_e32 v81, 4, v158
	v_cmp_lt_i32_e64 s[4:5], v81, v82
	s_nop 1
	v_cndmask_b32_e64 v81, v158, v81, s[4:5]
	v_lshlrev_b32_e32 v81, 2, v81
	s_nop 1
	v_mov_b32_dpp v81, v80 row_half_mirror row_mask:0xf bank_mask:0xf
	s_waitcnt lgkmcnt(0)
	v_add_f32_e32 v80, v80, v81
	v_xor_b32_e32 v81, 8, v158
	v_cmp_lt_i32_e64 s[4:5], v81, v82
	s_nop 1
	v_cndmask_b32_e64 v81, v158, v81, s[4:5]
	v_lshlrev_b32_e32 v81, 2, v81
	s_nop 1
	v_mov_b32_dpp v81, v80 row_ror:8 row_mask:0xf bank_mask:0xf
	s_waitcnt lgkmcnt(0)
	v_add_f32_e32 v80, v80, v81
	v_add_f32_e32 v80, 0x358637bd, v80
	v_mul_f32_e32 v81, 0x4b800000, v80
	v_cmp_gt_f32_e64 s[4:5], s46, v80
	s_nop 1
	v_cndmask_b32_e64 v80, v80, v81, s[4:5]
	v_rsq_f32_e32 v80, v80
	s_nop 0
	v_mul_f32_e32 v81, 0x45800000, v80
	v_cndmask_b32_e64 v80, v80, v81, s[4:5]
	v_mul_f32_e32 v80, v157, v80
	v_pk_mul_f32 v[78:79], v[78:79], v[80:81] op_sel_hi:[1,0]
	v_pk_mul_f32 v[76:77], v[76:77], v[80:81] op_sel_hi:[1,0]
	v_pk_mul_f32 v[74:75], v[74:75], v[80:81] op_sel_hi:[1,0]
	v_pk_mul_f32 v[72:73], v[72:73], v[80:81] op_sel_hi:[1,0]
; DI unsigned pk2(float a, float b) { f32x2 v = {a, b}; bf16x2_t r = __builtin_convertvector(v, bf16x2_t); return __builtin_bit_cast(unsigned, r); }
; DI float bflo(unsigned u) { return __uint_as_float(u << 16); }
; DI float bfhi(unsigned u) { return __uint_as_float(u & 0xffff0000u); }
; DI float siluf_(float x) { return x * __builtin_amdgcn_rcpf(1.f + __expf(-x)); }
; DI void dn_conv_phase(const Params& p) {
;     ...
;         for (int tt = 0; tt < SEG; ++tt) {
;             { const u32x4 u = rows[tt + 4]; const int sl = (tt + 4) % 5;
;               ring[sl][0] = (f32x2){bflo(u.x), bfhi(u.x)}; ring[sl][1] = (f32x2){bflo(u.y), bfhi(u.y)}; ring[sl][2] = (f32x2){bflo(u.z), bfhi(u.z)}; ring[sl][3] = (f32x2){bflo(u.w), bfhi(u.w)}; }
;             f32x2 o2[4];
; #pragma unroll
;             for (int e = 0; e < 4; ++e) o2[e] = w[0][e] * ring[tt % 5][e];
; #pragma unroll
;             for (int j = 1; j < 5; ++j)
; #pragma unroll
;                 for (int e = 0; e < 4; ++e) o2[e] += w[j][e] * ring[(tt + j) % 5][e];
;             float o[8];
; #pragma unroll
;             for (int e = 0; e < 4; ++e) { o[2 * e] = siluf_(o2[e].x); o[2 * e + 1] = siluf_(o2[e].y); }
;             if (part < 2) {
;                 float ss = 0.f;
; #pragma unroll
;                 for (int e = 0; e < 8; ++e) ss += o[e] * o[e];
;                 ss += __shfl_xor(ss, 1); ss += __shfl_xor(ss, 2); ss += __shfl_xor(ss, 4); ss += __shfl_xor(ss, 8);
;                 const float sc = rsqrtf(ss + EPS) * (part == 0 ? 0.08838834764831845f : 1.f);
; #pragma unroll
;                 for (int e = 0; e < 8; ++e) o[e] *= sc;
;             }
;             u32x4 ov; ov.x = pk2(o[0], o[1]); ov.y = pk2(o[2], o[3]); ov.z = pk2(o[4], o[5]); ov.w = pk2(o[6], o[7]);
;             *(u32x4*)(QKV + (size_t)(row0 + tt) * 1536 + ch) = ov;
.LBB0_327:
	s_or_b64 exec, exec, s[24:25]
	v_cvt_pk_bf16_f32 v72, v72, v73
	v_cvt_pk_bf16_f32 v73, v74, v75
	v_cvt_pk_bf16_f32 v74, v76, v77
	v_or_b32_e32 v76, 7, v156
	v_cvt_pk_bf16_f32 v75, v78, v79
	v_mad_i64_i32 v[76:77], s[4:5], v76, s45, v[100:101]
	global_store_dwordx4 v[76:77], v[72:75], off
	v_lshlrev_b32_e32 v88, 16, v68
	v_and_b32_e32 v89, 0xffff0000, v68
	v_lshlrev_b32_e32 v86, 16, v69
	v_and_b32_e32 v87, 0xffff0000, v69
	v_lshlrev_b32_e32 v84, 16, v70
	v_and_b32_e32 v85, 0xffff0000, v70
	v_lshlrev_b32_e32 v82, 16, v71
	v_and_b32_e32 v83, 0xffff0000, v71
	v_pk_mul_f32 v[68:69], v[20:21], v[114:115]
	v_pk_mul_f32 v[70:71], v[22:23], v[112:113]
	v_pk_mul_f32 v[72:73], v[12:13], v[110:111]
	v_pk_mul_f32 v[74:75], v[14:15], v[108:109]
	v_pk_fma_f32 v[68:69], v[4:5], v[128:129], v[68:69]
	v_pk_fma_f32 v[70:71], v[6:7], v[126:127], v[70:71]
	v_pk_fma_f32 v[72:73], v[0:1], v[118:119], v[72:73]
	v_pk_fma_f32 v[74:75], v[2:3], v[116:117], v[74:75]
	v_pk_fma_f32 v[68:69], v[24:25], v[106:107], v[68:69]
	v_pk_fma_f32 v[70:71], v[26:27], v[104:105], v[70:71]
	v_pk_fma_f32 v[72:73], v[16:17], v[102:103], v[72:73]
	v_pk_fma_f32 v[74:75], v[18:19], v[98:99], v[74:75]
	v_pk_fma_f32 v[68:69], v[36:37], v[96:97], v[68:69]
	v_pk_fma_f32 v[70:71], v[38:39], v[94:95], v[70:71]
	v_pk_fma_f32 v[72:73], v[28:29], v[92:93], v[72:73]
	v_pk_fma_f32 v[74:75], v[30:31], v[90:91], v[74:75]
	v_pk_fma_f32 v[68:69], v[32:33], v[88:89], v[68:69]
	v_pk_fma_f32 v[70:71], v[34:35], v[86:87], v[70:71]
	v_pk_fma_f32 v[72:73], v[8:9], v[84:85], v[72:73]
	v_pk_fma_f32 v[74:75], v[10:11], v[82:83], v[74:75]
	v_mul_f32_e32 v76, 0xbfb8aa3b, v68
	v_mul_f32_e32 v77, 0xbfb8aa3b, v69
	v_mul_f32_e32 v78, 0xbfb8aa3b, v70
	v_mul_f32_e32 v79, 0xbfb8aa3b, v71
	v_mul_f32_e32 v80, 0xbfb8aa3b, v72
	v_mul_f32_e32 v81, 0xbfb8aa3b, v73
	v_mul_f32_e32 v116, 0xbfb8aa3b, v74
	v_mul_f32_e32 v117, 0xbfb8aa3b, v75
	v_exp_f32_e32 v76, v76
	v_exp_f32_e32 v77, v77
	v_exp_f32_e32 v78, v78
	v_exp_f32_e32 v79, v79
	v_exp_f32_e32 v80, v80
	v_exp_f32_e32 v81, v81
	v_exp_f32_e32 v116, v116
	v_exp_f32_e32 v117, v117
	v_add_f32_e32 v76, 1.0, v76
	v_add_f32_e32 v77, 1.0, v77
	v_add_f32_e32 v78, 1.0, v78
	v_add_f32_e32 v79, 1.0, v79
	v_add_f32_e32 v80, 1.0, v80
	v_add_f32_e32 v81, 1.0, v81
	v_add_f32_e32 v116, 1.0, v116
	v_add_f32_e32 v117, 1.0, v117
	v_rcp_f32_e32 v76, v76
	v_rcp_f32_e32 v77, v77
	v_rcp_f32_e32 v78, v78
	v_rcp_f32_e32 v79, v79
	v_rcp_f32_e32 v80, v80
	v_rcp_f32_e32 v81, v81
	v_rcp_f32_e32 v116, v116
	v_rcp_f32_e32 v117, v117
	v_pk_mul_f32 v[68:69], v[68:69], v[76:77]
	v_pk_mul_f32 v[70:71], v[70:71], v[78:79]
	v_pk_mul_f32 v[72:73], v[72:73], v[80:81]
	v_pk_mul_f32 v[74:75], v[74:75], v[116:117]
	s_and_saveexec_b64 s[24:25], vcc
	s_cbranch_execz .LBB0_329
	v_pk_mul_f32 v[76:77], v[68:69], v[68:69]
	v_pk_mul_f32 v[78:79], v[70:71], v[70:71]
	v_add_f32_e32 v76, v76, v77
	v_add_f32_e32 v76, v78, v76
	v_pk_mul_f32 v[80:81], v[72:73], v[72:73]
	v_add_f32_e32 v76, v79, v76
	v_and_b32_e32 v78, 64, v158
	v_add_f32_e32 v76, v80, v76
	v_xor_b32_e32 v77, 1, v158
	v_add_u32_e32 v78, 64, v78
	v_pk_mul_f32 v[116:117], v[74:75], v[74:75]
	v_add_f32_e32 v76, v81, v76
	v_cmp_lt_i32_e64 s[4:5], v77, v78
	v_add_f32_e32 v76, v116, v76
	v_add_f32_e32 v76, v117, v76
	v_cndmask_b32_e64 v77, v158, v77, s[4:5]
	v_lshlrev_b32_e32 v77, 2, v77
	s_nop 1
	v_mov_b32_dpp v77, v76 quad_perm:[1,0,3,2] row_mask:0xf bank_mask:0xf
	s_waitcnt lgkmcnt(0)
	v_add_f32_e32 v76, v76, v77
	v_xor_b32_e32 v77, 2, v158
	v_cmp_lt_i32_e64 s[4:5], v77, v78
	s_nop 1
	v_cndmask_b32_e64 v77, v158, v77, s[4:5]
	v_lshlrev_b32_e32 v77, 2, v77
	s_nop 1
	v_mov_b32_dpp v77, v76 quad_perm:[2,3,0,1] row_mask:0xf bank_mask:0xf
	s_waitcnt lgkmcnt(0)
	v_add_f32_e32 v76, v76, v77
	v_xor_b32_e32 v77, 4, v158
	v_cmp_lt_i32_e64 s[4:5], v77, v78
	s_nop 1
	v_cndmask_b32_e64 v77, v158, v77, s[4:5]
	v_lshlrev_b32_e32 v77, 2, v77
	s_nop 1
	v_mov_b32_dpp v77, v76 row_half_mirror row_mask:0xf bank_mask:0xf
	s_waitcnt lgkmcnt(0)
	v_add_f32_e32 v76, v76, v77
	v_xor_b32_e32 v77, 8, v158
	v_cmp_lt_i32_e64 s[4:5], v77, v78
	s_nop 1
	v_cndmask_b32_e64 v77, v158, v77, s[4:5]
	v_lshlrev_b32_e32 v77, 2, v77
	s_nop 1
	v_mov_b32_dpp v77, v76 row_ror:8 row_mask:0xf bank_mask:0xf
	s_waitcnt lgkmcnt(0)
	v_add_f32_e32 v76, v76, v77
	v_add_f32_e32 v76, 0x358637bd, v76
	v_mul_f32_e32 v77, 0x4b800000, v76
	v_cmp_gt_f32_e64 s[4:5], s46, v76
	s_nop 1
	v_cndmask_b32_e64 v76, v76, v77, s[4:5]
	v_rsq_f32_e32 v76, v76
	s_nop 0
	v_mul_f32_e32 v77, 0x45800000, v76
	v_cndmask_b32_e64 v76, v76, v77, s[4:5]
	v_mul_f32_e32 v76, v157, v76
	v_pk_mul_f32 v[74:75], v[74:75], v[76:77] op_sel_hi:[1,0]
	v_pk_mul_f32 v[72:73], v[72:73], v[76:77] op_sel_hi:[1,0]
	v_pk_mul_f32 v[70:71], v[70:71], v[76:77] op_sel_hi:[1,0]
	v_pk_mul_f32 v[68:69], v[68:69], v[76:77] op_sel_hi:[1,0]
; DI unsigned pk2(float a, float b) { f32x2 v = {a, b}; bf16x2_t r = __builtin_convertvector(v, bf16x2_t); return __builtin_bit_cast(unsigned, r); }
; DI float bflo(unsigned u) { return __uint_as_float(u << 16); }
; DI float bfhi(unsigned u) { return __uint_as_float(u & 0xffff0000u); }
; DI float siluf_(float x) { return x * __builtin_amdgcn_rcpf(1.f + __expf(-x)); }
; DI void dn_conv_phase(const Params& p) {
;     ...
;         for (int tt = 0; tt < SEG; ++tt) {
;             { const u32x4 u = rows[tt + 4]; const int sl = (tt + 4) % 5;
;               ring[sl][0] = (f32x2){bflo(u.x), bfhi(u.x)}; ring[sl][1] = (f32x2){bflo(u.y), bfhi(u.y)}; ring[sl][2] = (f32x2){bflo(u.z), bfhi(u.z)}; ring[sl][3] = (f32x2){bflo(u.w), bfhi(u.w)}; }
;             f32x2 o2[4];
; #pragma unroll
;             for (int e = 0; e < 4; ++e) o2[e] = w[0][e] * ring[tt % 5][e];
; #pragma unroll
;             for (int j = 1; j < 5; ++j)
; #pragma unroll
;                 for (int e = 0; e < 4; ++e) o2[e] += w[j][e] * ring[(tt + j) % 5][e];
;             float o[8];
; #pragma unroll
;             for (int e = 0; e < 4; ++e) { o[2 * e] = siluf_(o2[e].x); o[2 * e + 1] = siluf_(o2[e].y); }
;             if (part < 2) {
;                 float ss = 0.f;
; #pragma unroll
;                 for (int e = 0; e < 8; ++e) ss += o[e] * o[e];
;                 ss += __shfl_xor(ss, 1); ss += __shfl_xor(ss, 2); ss += __shfl_xor(ss, 4); ss += __shfl_xor(ss, 8);
;                 const float sc = rsqrtf(ss + EPS) * (part == 0 ? 0.08838834764831845f : 1.f);
; #pragma unroll
;                 for (int e = 0; e < 8; ++e) o[e] *= sc;
;             }
;             u32x4 ov; ov.x = pk2(o[0], o[1]); ov.y = pk2(o[2], o[3]); ov.z = pk2(o[4], o[5]); ov.w = pk2(o[6], o[7]);
;             *(u32x4*)(QKV + (size_t)(row0 + tt) * 1536 + ch) = ov;
.LBB0_329:
	s_or_b64 exec, exec, s[24:25]
	v_cvt_pk_bf16_f32 v68, v68, v69
	v_cvt_pk_bf16_f32 v69, v70, v71
	v_cvt_pk_bf16_f32 v70, v72, v73
	v_or_b32_e32 v72, 8, v156
	v_cvt_pk_bf16_f32 v71, v74, v75
	v_mad_i64_i32 v[72:73], s[4:5], v72, s45, v[100:101]
	global_store_dwordx4 v[72:73], v[68:71], off
	v_lshlrev_b32_e32 v80, 16, v64
	v_and_b32_e32 v81, 0xffff0000, v64
	v_lshlrev_b32_e32 v78, 16, v65
	v_and_b32_e32 v79, 0xffff0000, v65
	v_lshlrev_b32_e32 v76, 16, v66
	v_and_b32_e32 v77, 0xffff0000, v66
	v_lshlrev_b32_e32 v74, 16, v67
	v_and_b32_e32 v75, 0xffff0000, v67
	v_pk_mul_f32 v[64:65], v[20:21], v[106:107]
	v_pk_mul_f32 v[66:67], v[22:23], v[104:105]
	v_pk_mul_f32 v[68:69], v[12:13], v[102:103]
	v_pk_mul_f32 v[70:71], v[14:15], v[98:99]
	v_pk_fma_f32 v[64:65], v[4:5], v[114:115], v[64:65]
	v_pk_fma_f32 v[66:67], v[6:7], v[112:113], v[66:67]
	v_pk_fma_f32 v[68:69], v[0:1], v[110:111], v[68:69]
	v_pk_fma_f32 v[70:71], v[2:3], v[108:109], v[70:71]
	v_pk_fma_f32 v[64:65], v[24:25], v[96:97], v[64:65]
	v_pk_fma_f32 v[66:67], v[26:27], v[94:95], v[66:67]
	v_pk_fma_f32 v[68:69], v[16:17], v[92:93], v[68:69]
	v_pk_fma_f32 v[70:71], v[18:19], v[90:91], v[70:71]
	v_pk_fma_f32 v[64:65], v[36:37], v[88:89], v[64:65]
	v_pk_fma_f32 v[66:67], v[38:39], v[86:87], v[66:67]
	v_pk_fma_f32 v[68:69], v[28:29], v[84:85], v[68:69]
	v_pk_fma_f32 v[70:71], v[30:31], v[82:83], v[70:71]
	v_pk_fma_f32 v[64:65], v[32:33], v[80:81], v[64:65]
	v_pk_fma_f32 v[66:67], v[34:35], v[78:79], v[66:67]
	v_pk_fma_f32 v[68:69], v[8:9], v[76:77], v[68:69]
	v_pk_fma_f32 v[70:71], v[10:11], v[74:75], v[70:71]
	v_mul_f32_e32 v72, 0xbfb8aa3b, v64
	v_mul_f32_e32 v73, 0xbfb8aa3b, v65
	v_mul_f32_e32 v108, 0xbfb8aa3b, v66
	v_mul_f32_e32 v109, 0xbfb8aa3b, v67
	v_mul_f32_e32 v110, 0xbfb8aa3b, v68
	v_mul_f32_e32 v111, 0xbfb8aa3b, v69
	v_mul_f32_e32 v112, 0xbfb8aa3b, v70
	v_mul_f32_e32 v113, 0xbfb8aa3b, v71
	v_exp_f32_e32 v72, v72
	v_exp_f32_e32 v73, v73
	v_exp_f32_e32 v108, v108
	v_exp_f32_e32 v109, v109
	v_exp_f32_e32 v110, v110
	v_exp_f32_e32 v111, v111
	v_exp_f32_e32 v112, v112
	v_exp_f32_e32 v113, v113
	v_add_f32_e32 v72, 1.0, v72
	v_add_f32_e32 v73, 1.0, v73
	v_add_f32_e32 v108, 1.0, v108
	v_add_f32_e32 v109, 1.0, v109
	v_add_f32_e32 v110, 1.0, v110
	v_add_f32_e32 v111, 1.0, v111
	v_add_f32_e32 v112, 1.0, v112
	v_add_f32_e32 v113, 1.0, v113
	v_rcp_f32_e32 v72, v72
	v_rcp_f32_e32 v73, v73
	v_rcp_f32_e32 v108, v108
	v_rcp_f32_e32 v109, v109
	v_rcp_f32_e32 v110, v110
	v_rcp_f32_e32 v111, v111
	v_rcp_f32_e32 v112, v112
	v_rcp_f32_e32 v113, v113
	v_pk_mul_f32 v[64:65], v[64:65], v[72:73]
	v_pk_mul_f32 v[66:67], v[66:67], v[108:109]
	v_pk_mul_f32 v[68:69], v[68:69], v[110:111]
	v_pk_mul_f32 v[70:71], v[70:71], v[112:113]
	s_and_saveexec_b64 s[24:25], vcc
	s_cbranch_execz .LBB0_331
	v_pk_mul_f32 v[72:73], v[64:65], v[64:65]
	v_pk_mul_f32 v[108:109], v[66:67], v[66:67]
	v_add_f32_e32 v72, v72, v73
	v_add_f32_e32 v72, v108, v72
	v_pk_mul_f32 v[110:111], v[68:69], v[68:69]
	v_add_f32_e32 v72, v109, v72
	v_and_b32_e32 v108, 64, v158
	v_add_f32_e32 v72, v110, v72
	v_xor_b32_e32 v73, 1, v158
	v_add_u32_e32 v108, 64, v108
	v_pk_mul_f32 v[112:113], v[70:71], v[70:71]
	v_add_f32_e32 v72, v111, v72
	v_cmp_lt_i32_e64 s[4:5], v73, v108
	v_add_f32_e32 v72, v112, v72
	v_add_f32_e32 v72, v113, v72
	v_cndmask_b32_e64 v73, v158, v73, s[4:5]
	v_lshlrev_b32_e32 v73, 2, v73
	s_nop 1
	v_mov_b32_dpp v73, v72 quad_perm:[1,0,3,2] row_mask:0xf bank_mask:0xf
	s_waitcnt lgkmcnt(0)
	v_add_f32_e32 v72, v72, v73
	v_xor_b32_e32 v73, 2, v158
	v_cmp_lt_i32_e64 s[4:5], v73, v108
	s_nop 1
	v_cndmask_b32_e64 v73, v158, v73, s[4:5]
	v_lshlrev_b32_e32 v73, 2, v73
	s_nop 1
	v_mov_b32_dpp v73, v72 quad_perm:[2,3,0,1] row_mask:0xf bank_mask:0xf
	s_waitcnt lgkmcnt(0)
	v_add_f32_e32 v72, v72, v73
	v_xor_b32_e32 v73, 4, v158
	v_cmp_lt_i32_e64 s[4:5], v73, v108
	s_nop 1
	v_cndmask_b32_e64 v73, v158, v73, s[4:5]
	v_lshlrev_b32_e32 v73, 2, v73
	s_nop 1
	v_mov_b32_dpp v73, v72 row_half_mirror row_mask:0xf bank_mask:0xf
	s_waitcnt lgkmcnt(0)
	v_add_f32_e32 v72, v72, v73
	v_xor_b32_e32 v73, 8, v158
	v_cmp_lt_i32_e64 s[4:5], v73, v108
	s_nop 1
	v_cndmask_b32_e64 v73, v158, v73, s[4:5]
	v_lshlrev_b32_e32 v73, 2, v73
	s_nop 1
	v_mov_b32_dpp v73, v72 row_ror:8 row_mask:0xf bank_mask:0xf
	s_waitcnt lgkmcnt(0)
	v_add_f32_e32 v72, v72, v73
	v_add_f32_e32 v72, 0x358637bd, v72
	v_mul_f32_e32 v73, 0x4b800000, v72
	v_cmp_gt_f32_e64 s[4:5], s46, v72
	s_nop 1
	v_cndmask_b32_e64 v72, v72, v73, s[4:5]
	v_rsq_f32_e32 v72, v72
	s_nop 0
	v_mul_f32_e32 v73, 0x45800000, v72
	v_cndmask_b32_e64 v72, v72, v73, s[4:5]
	v_mul_f32_e32 v72, v157, v72
	v_pk_mul_f32 v[70:71], v[70:71], v[72:73] op_sel_hi:[1,0]
	v_pk_mul_f32 v[68:69], v[68:69], v[72:73] op_sel_hi:[1,0]
	v_pk_mul_f32 v[66:67], v[66:67], v[72:73] op_sel_hi:[1,0]
	v_pk_mul_f32 v[64:65], v[64:65], v[72:73] op_sel_hi:[1,0]
; DI unsigned pk2(float a, float b) { f32x2 v = {a, b}; bf16x2_t r = __builtin_convertvector(v, bf16x2_t); return __builtin_bit_cast(unsigned, r); }
; DI float bflo(unsigned u) { return __uint_as_float(u << 16); }
; DI float bfhi(unsigned u) { return __uint_as_float(u & 0xffff0000u); }
; DI float siluf_(float x) { return x * __builtin_amdgcn_rcpf(1.f + __expf(-x)); }
; DI void dn_conv_phase(const Params& p) {
;     ...
;         for (int tt = 0; tt < SEG; ++tt) {
;             { const u32x4 u = rows[tt + 4]; const int sl = (tt + 4) % 5;
;               ring[sl][0] = (f32x2){bflo(u.x), bfhi(u.x)}; ring[sl][1] = (f32x2){bflo(u.y), bfhi(u.y)}; ring[sl][2] = (f32x2){bflo(u.z), bfhi(u.z)}; ring[sl][3] = (f32x2){bflo(u.w), bfhi(u.w)}; }
;             f32x2 o2[4];
; #pragma unroll
;             for (int e = 0; e < 4; ++e) o2[e] = w[0][e] * ring[tt % 5][e];
; #pragma unroll
;             for (int j = 1; j < 5; ++j)
; #pragma unroll
;                 for (int e = 0; e < 4; ++e) o2[e] += w[j][e] * ring[(tt + j) % 5][e];
;             float o[8];
; #pragma unroll
;             for (int e = 0; e < 4; ++e) { o[2 * e] = siluf_(o2[e].x); o[2 * e + 1] = siluf_(o2[e].y); }
;             if (part < 2) {
;                 float ss = 0.f;
; #pragma unroll
;                 for (int e = 0; e < 8; ++e) ss += o[e] * o[e];
;                 ss += __shfl_xor(ss, 1); ss += __shfl_xor(ss, 2); ss += __shfl_xor(ss, 4); ss += __shfl_xor(ss, 8);
;                 const float sc = rsqrtf(ss + EPS) * (part == 0 ? 0.08838834764831845f : 1.f);
; #pragma unroll
;                 for (int e = 0; e < 8; ++e) o[e] *= sc;
;             }
;             u32x4 ov; ov.x = pk2(o[0], o[1]); ov.y = pk2(o[2], o[3]); ov.z = pk2(o[4], o[5]); ov.w = pk2(o[6], o[7]);
;             *(u32x4*)(QKV + (size_t)(row0 + tt) * 1536 + ch) = ov;
.LBB0_331:
	s_or_b64 exec, exec, s[24:25]
	v_cvt_pk_bf16_f32 v64, v64, v65
	v_cvt_pk_bf16_f32 v65, v66, v67
	v_cvt_pk_bf16_f32 v66, v68, v69
	v_or_b32_e32 v68, 9, v156
	v_cvt_pk_bf16_f32 v67, v70, v71
	v_mad_i64_i32 v[68:69], s[4:5], v68, s45, v[100:101]
	global_store_dwordx4 v[68:69], v[64:67], off
	v_lshlrev_b32_e32 v72, 16, v60
	v_and_b32_e32 v73, 0xffff0000, v60
	v_pk_mul_f32 v[64:65], v[12:13], v[92:93]
	v_lshlrev_b32_e32 v70, 16, v61
	v_and_b32_e32 v71, 0xffff0000, v61
	v_lshlrev_b32_e32 v68, 16, v62
	v_and_b32_e32 v69, 0xffff0000, v62
	v_lshlrev_b32_e32 v66, 16, v63
	v_and_b32_e32 v67, 0xffff0000, v63
	v_pk_mul_f32 v[60:61], v[20:21], v[96:97]
	v_pk_mul_f32 v[62:63], v[22:23], v[94:95]
	v_pk_fma_f32 v[64:65], v[0:1], v[102:103], v[64:65]
	v_pk_mul_f32 v[102:103], v[14:15], v[90:91]
	v_pk_fma_f32 v[60:61], v[4:5], v[106:107], v[60:61]
	v_pk_fma_f32 v[62:63], v[6:7], v[104:105], v[62:63]
	v_pk_fma_f32 v[98:99], v[2:3], v[98:99], v[102:103]
	v_pk_fma_f32 v[60:61], v[24:25], v[88:89], v[60:61]
	v_pk_fma_f32 v[62:63], v[26:27], v[86:87], v[62:63]
	v_pk_fma_f32 v[64:65], v[16:17], v[84:85], v[64:65]
	v_pk_fma_f32 v[98:99], v[18:19], v[82:83], v[98:99]
	v_pk_fma_f32 v[60:61], v[36:37], v[80:81], v[60:61]
	v_pk_fma_f32 v[62:63], v[38:39], v[78:79], v[62:63]
	v_pk_fma_f32 v[64:65], v[28:29], v[76:77], v[64:65]
	v_pk_fma_f32 v[98:99], v[30:31], v[74:75], v[98:99]
	v_pk_fma_f32 v[60:61], v[32:33], v[72:73], v[60:61]
	v_pk_fma_f32 v[62:63], v[34:35], v[70:71], v[62:63]
	v_pk_fma_f32 v[64:65], v[8:9], v[68:69], v[64:65]
	v_pk_fma_f32 v[98:99], v[10:11], v[66:67], v[98:99]
	v_mul_f32_e32 v102, 0xbfb8aa3b, v60
	v_mul_f32_e32 v103, 0xbfb8aa3b, v61
	v_mul_f32_e32 v104, 0xbfb8aa3b, v62
	v_mul_f32_e32 v105, 0xbfb8aa3b, v63
	v_mul_f32_e32 v106, 0xbfb8aa3b, v64
	v_mul_f32_e32 v107, 0xbfb8aa3b, v65
	v_mul_f32_e32 v108, 0xbfb8aa3b, v98
	v_mul_f32_e32 v109, 0xbfb8aa3b, v99
	v_exp_f32_e32 v102, v102
	v_exp_f32_e32 v103, v103
	v_exp_f32_e32 v104, v104
	v_exp_f32_e32 v105, v105
	v_exp_f32_e32 v106, v106
	v_exp_f32_e32 v107, v107
	v_exp_f32_e32 v108, v108
	v_exp_f32_e32 v109, v109
	v_add_f32_e32 v102, 1.0, v102
	v_add_f32_e32 v103, 1.0, v103
	v_add_f32_e32 v104, 1.0, v104
	v_add_f32_e32 v105, 1.0, v105
	v_add_f32_e32 v106, 1.0, v106
	v_add_f32_e32 v107, 1.0, v107
	v_add_f32_e32 v108, 1.0, v108
	v_add_f32_e32 v109, 1.0, v109
	v_rcp_f32_e32 v102, v102
	v_rcp_f32_e32 v103, v103
	v_rcp_f32_e32 v104, v104
	v_rcp_f32_e32 v105, v105
	v_rcp_f32_e32 v106, v106
	v_rcp_f32_e32 v107, v107
	v_rcp_f32_e32 v108, v108
	v_rcp_f32_e32 v109, v109
	v_pk_mul_f32 v[60:61], v[60:61], v[102:103]
	v_pk_mul_f32 v[62:63], v[62:63], v[104:105]
	v_pk_mul_f32 v[64:65], v[64:65], v[106:107]
	v_pk_mul_f32 v[98:99], v[98:99], v[108:109]
	s_and_saveexec_b64 s[24:25], vcc
	s_cbranch_execz .LBB0_333
	v_pk_mul_f32 v[102:103], v[60:61], v[60:61]
	v_pk_mul_f32 v[104:105], v[62:63], v[62:63]
	v_add_f32_e32 v102, v102, v103
	v_add_f32_e32 v102, v104, v102
	v_pk_mul_f32 v[106:107], v[64:65], v[64:65]
	v_add_f32_e32 v102, v105, v102
	v_and_b32_e32 v104, 64, v158
	v_add_f32_e32 v102, v106, v102
	v_xor_b32_e32 v103, 1, v158
	v_add_u32_e32 v104, 64, v104
	v_pk_mul_f32 v[108:109], v[98:99], v[98:99]
	v_add_f32_e32 v102, v107, v102
	v_cmp_lt_i32_e64 s[4:5], v103, v104
	v_add_f32_e32 v102, v108, v102
	v_add_f32_e32 v102, v109, v102
	v_cndmask_b32_e64 v103, v158, v103, s[4:5]
	v_lshlrev_b32_e32 v103, 2, v103
	s_nop 1
	v_mov_b32_dpp v103, v102 quad_perm:[1,0,3,2] row_mask:0xf bank_mask:0xf
	s_waitcnt lgkmcnt(0)
	v_add_f32_e32 v102, v102, v103
	v_xor_b32_e32 v103, 2, v158
	v_cmp_lt_i32_e64 s[4:5], v103, v104
	s_nop 1
	v_cndmask_b32_e64 v103, v158, v103, s[4:5]
	v_lshlrev_b32_e32 v103, 2, v103
	s_nop 1
	v_mov_b32_dpp v103, v102 quad_perm:[2,3,0,1] row_mask:0xf bank_mask:0xf
	s_waitcnt lgkmcnt(0)
	v_add_f32_e32 v102, v102, v103
	v_xor_b32_e32 v103, 4, v158
	v_cmp_lt_i32_e64 s[4:5], v103, v104
	s_nop 1
	v_cndmask_b32_e64 v103, v158, v103, s[4:5]
	v_lshlrev_b32_e32 v103, 2, v103
	s_nop 1
	v_mov_b32_dpp v103, v102 row_half_mirror row_mask:0xf bank_mask:0xf
	s_waitcnt lgkmcnt(0)
	v_add_f32_e32 v102, v102, v103
	v_xor_b32_e32 v103, 8, v158
	v_cmp_lt_i32_e64 s[4:5], v103, v104
	s_nop 1
	v_cndmask_b32_e64 v103, v158, v103, s[4:5]
	v_lshlrev_b32_e32 v103, 2, v103
	s_nop 1
	v_mov_b32_dpp v103, v102 row_ror:8 row_mask:0xf bank_mask:0xf
	s_waitcnt lgkmcnt(0)
	v_add_f32_e32 v102, v102, v103
	v_add_f32_e32 v102, 0x358637bd, v102
	v_mul_f32_e32 v103, 0x4b800000, v102
	v_cmp_gt_f32_e64 s[4:5], s46, v102
	s_nop 1
	v_cndmask_b32_e64 v102, v102, v103, s[4:5]
	v_rsq_f32_e32 v102, v102
	s_nop 0
	v_mul_f32_e32 v103, 0x45800000, v102
	v_cndmask_b32_e64 v102, v102, v103, s[4:5]
	v_mul_f32_e32 v102, v157, v102
	v_pk_mul_f32 v[98:99], v[98:99], v[102:103] op_sel_hi:[1,0]
	v_pk_mul_f32 v[64:65], v[64:65], v[102:103] op_sel_hi:[1,0]
	v_pk_mul_f32 v[62:63], v[62:63], v[102:103] op_sel_hi:[1,0]
	v_pk_mul_f32 v[60:61], v[60:61], v[102:103] op_sel_hi:[1,0]
; DI unsigned pk2(float a, float b) { f32x2 v = {a, b}; bf16x2_t r = __builtin_convertvector(v, bf16x2_t); return __builtin_bit_cast(unsigned, r); }
; DI float bflo(unsigned u) { return __uint_as_float(u << 16); }
; DI float bfhi(unsigned u) { return __uint_as_float(u & 0xffff0000u); }
; DI float siluf_(float x) { return x * __builtin_amdgcn_rcpf(1.f + __expf(-x)); }
; DI void dn_conv_phase(const Params& p) {
;     ...
;         for (int tt = 0; tt < SEG; ++tt) {
;             { const u32x4 u = rows[tt + 4]; const int sl = (tt + 4) % 5;
;               ring[sl][0] = (f32x2){bflo(u.x), bfhi(u.x)}; ring[sl][1] = (f32x2){bflo(u.y), bfhi(u.y)}; ring[sl][2] = (f32x2){bflo(u.z), bfhi(u.z)}; ring[sl][3] = (f32x2){bflo(u.w), bfhi(u.w)}; }
;             f32x2 o2[4];
; #pragma unroll
;             for (int e = 0; e < 4; ++e) o2[e] = w[0][e] * ring[tt % 5][e];
; #pragma unroll
;             for (int j = 1; j < 5; ++j)
; #pragma unroll
;                 for (int e = 0; e < 4; ++e) o2[e] += w[j][e] * ring[(tt + j) % 5][e];
;             float o[8];
; #pragma unroll
;             for (int e = 0; e < 4; ++e) { o[2 * e] = siluf_(o2[e].x); o[2 * e + 1] = siluf_(o2[e].y); }
;             if (part < 2) {
;                 float ss = 0.f;
; #pragma unroll
;                 for (int e = 0; e < 8; ++e) ss += o[e] * o[e];
;                 ss += __shfl_xor(ss, 1); ss += __shfl_xor(ss, 2); ss += __shfl_xor(ss, 4); ss += __shfl_xor(ss, 8);
;                 const float sc = rsqrtf(ss + EPS) * (part == 0 ? 0.08838834764831845f : 1.f);
; #pragma unroll
;                 for (int e = 0; e < 8; ++e) o[e] *= sc;
;             }
;             u32x4 ov; ov.x = pk2(o[0], o[1]); ov.y = pk2(o[2], o[3]); ov.z = pk2(o[4], o[5]); ov.w = pk2(o[6], o[7]);
;             *(u32x4*)(QKV + (size_t)(row0 + tt) * 1536 + ch) = ov;
.LBB0_333:
	s_or_b64 exec, exec, s[24:25]
	v_cvt_pk_bf16_f32 v60, v60, v61
	v_cvt_pk_bf16_f32 v61, v62, v63
	v_cvt_pk_bf16_f32 v62, v64, v65
	v_or_b32_e32 v64, 10, v156
	v_cvt_pk_bf16_f32 v63, v98, v99
	v_mad_i64_i32 v[64:65], s[4:5], v64, s45, v[100:101]
	global_store_dwordx4 v[64:65], v[60:63], off
	v_lshlrev_b32_e32 v64, 16, v56
	v_and_b32_e32 v65, 0xffff0000, v56
	v_lshlrev_b32_e32 v62, 16, v57
	v_and_b32_e32 v63, 0xffff0000, v57
	v_lshlrev_b32_e32 v60, 16, v58
	v_and_b32_e32 v61, 0xffff0000, v58
	v_lshlrev_b32_e32 v56, 16, v59
	v_and_b32_e32 v57, 0xffff0000, v59
	v_pk_mul_f32 v[58:59], v[20:21], v[88:89]
	s_nop 0
	v_pk_fma_f32 v[58:59], v[4:5], v[96:97], v[58:59]
	v_pk_mul_f32 v[96:97], v[22:23], v[86:87]
	v_pk_fma_f32 v[58:59], v[24:25], v[80:81], v[58:59]
	v_pk_fma_f32 v[94:95], v[6:7], v[94:95], v[96:97]
	v_pk_mul_f32 v[96:97], v[12:13], v[84:85]
	v_pk_fma_f32 v[58:59], v[36:37], v[72:73], v[58:59]
	v_pk_fma_f32 v[92:93], v[0:1], v[92:93], v[96:97]
	v_pk_mul_f32 v[96:97], v[14:15], v[82:83]
	v_pk_fma_f32 v[58:59], v[32:33], v[64:65], v[58:59]
	v_pk_fma_f32 v[90:91], v[2:3], v[90:91], v[96:97]
	v_mul_f32_e32 v96, 0xbfb8aa3b, v58
	v_exp_f32_e32 v98, v96
	v_mul_f32_e32 v96, 0xbfb8aa3b, v59
	v_exp_f32_e32 v99, v96
	v_pk_fma_f32 v[94:95], v[26:27], v[78:79], v[94:95]
	v_pk_fma_f32 v[92:93], v[16:17], v[76:77], v[92:93]
	v_pk_fma_f32 v[90:91], v[18:19], v[74:75], v[90:91]
	v_pk_fma_f32 v[94:95], v[38:39], v[70:71], v[94:95]
	v_pk_fma_f32 v[92:93], v[28:29], v[68:69], v[92:93]
	v_pk_fma_f32 v[90:91], v[30:31], v[66:67], v[90:91]
	v_pk_fma_f32 v[94:95], v[34:35], v[62:63], v[94:95]
	v_pk_fma_f32 v[92:93], v[8:9], v[60:61], v[92:93]
	v_pk_fma_f32 v[96:97], v[10:11], v[56:57], v[90:91]
	v_add_f32_e32 v90, 1.0, v98
	v_add_f32_e32 v91, 1.0, v99
	v_mul_f32_e32 v98, 0xbfb8aa3b, v94
	v_mul_f32_e32 v99, 0xbfb8aa3b, v95
	v_mul_f32_e32 v102, 0xbfb8aa3b, v92
	v_mul_f32_e32 v103, 0xbfb8aa3b, v93
	v_mul_f32_e32 v104, 0xbfb8aa3b, v96
	v_mul_f32_e32 v105, 0xbfb8aa3b, v97
	v_exp_f32_e32 v98, v98
	v_exp_f32_e32 v99, v99
	v_exp_f32_e32 v102, v102
	v_exp_f32_e32 v103, v103
	v_exp_f32_e32 v104, v104
	v_exp_f32_e32 v105, v105
	v_add_f32_e32 v98, 1.0, v98
	v_add_f32_e32 v99, 1.0, v99
	v_add_f32_e32 v102, 1.0, v102
	v_add_f32_e32 v103, 1.0, v103
	v_add_f32_e32 v104, 1.0, v104
	v_add_f32_e32 v105, 1.0, v105
	v_rcp_f32_e32 v90, v90
	v_rcp_f32_e32 v91, v91
	v_rcp_f32_e32 v98, v98
	v_rcp_f32_e32 v99, v99
	v_rcp_f32_e32 v102, v102
	v_rcp_f32_e32 v103, v103
	v_rcp_f32_e32 v104, v104
	v_rcp_f32_e32 v105, v105
	v_pk_mul_f32 v[58:59], v[58:59], v[90:91]
	v_pk_mul_f32 v[90:91], v[94:95], v[98:99]
	v_pk_mul_f32 v[92:93], v[92:93], v[102:103]
	v_pk_mul_f32 v[94:95], v[96:97], v[104:105]
	s_and_saveexec_b64 s[24:25], vcc
	s_cbranch_execz .LBB0_335
	v_pk_mul_f32 v[96:97], v[58:59], v[58:59]
	v_pk_mul_f32 v[98:99], v[90:91], v[90:91]
	v_add_f32_e32 v96, v96, v97
	v_add_f32_e32 v96, v98, v96
	v_pk_mul_f32 v[102:103], v[92:93], v[92:93]
	v_add_f32_e32 v96, v99, v96
	v_and_b32_e32 v98, 64, v158
	v_add_f32_e32 v96, v102, v96
	v_xor_b32_e32 v97, 1, v158
	v_add_u32_e32 v98, 64, v98
	v_pk_mul_f32 v[104:105], v[94:95], v[94:95]
	v_add_f32_e32 v96, v103, v96
	v_cmp_lt_i32_e64 s[4:5], v97, v98
	v_add_f32_e32 v96, v104, v96
	v_add_f32_e32 v96, v105, v96
	v_cndmask_b32_e64 v97, v158, v97, s[4:5]
	v_lshlrev_b32_e32 v97, 2, v97
	s_nop 1
	v_mov_b32_dpp v97, v96 quad_perm:[1,0,3,2] row_mask:0xf bank_mask:0xf
	s_waitcnt lgkmcnt(0)
	v_add_f32_e32 v96, v96, v97
	v_xor_b32_e32 v97, 2, v158
	v_cmp_lt_i32_e64 s[4:5], v97, v98
	s_nop 1
	v_cndmask_b32_e64 v97, v158, v97, s[4:5]
	v_lshlrev_b32_e32 v97, 2, v97
	s_nop 1
	v_mov_b32_dpp v97, v96 quad_perm:[2,3,0,1] row_mask:0xf bank_mask:0xf
	s_waitcnt lgkmcnt(0)
	v_add_f32_e32 v96, v96, v97
	v_xor_b32_e32 v97, 4, v158
	v_cmp_lt_i32_e64 s[4:5], v97, v98
	s_nop 1
	v_cndmask_b32_e64 v97, v158, v97, s[4:5]
	v_lshlrev_b32_e32 v97, 2, v97
	s_nop 1
	v_mov_b32_dpp v97, v96 row_half_mirror row_mask:0xf bank_mask:0xf
	s_waitcnt lgkmcnt(0)
	v_add_f32_e32 v96, v96, v97
	v_xor_b32_e32 v97, 8, v158
	v_cmp_lt_i32_e64 s[4:5], v97, v98
	s_nop 1
	v_cndmask_b32_e64 v97, v158, v97, s[4:5]
	v_lshlrev_b32_e32 v97, 2, v97
	s_nop 1
	v_mov_b32_dpp v97, v96 row_ror:8 row_mask:0xf bank_mask:0xf
	s_waitcnt lgkmcnt(0)
	v_add_f32_e32 v96, v96, v97
	v_add_f32_e32 v96, 0x358637bd, v96
	v_mul_f32_e32 v97, 0x4b800000, v96
	v_cmp_gt_f32_e64 s[4:5], s46, v96
	s_nop 1
	v_cndmask_b32_e64 v96, v96, v97, s[4:5]
	v_rsq_f32_e32 v96, v96
	s_nop 0
	v_mul_f32_e32 v97, 0x45800000, v96
	v_cndmask_b32_e64 v96, v96, v97, s[4:5]
	v_mul_f32_e32 v96, v157, v96
	v_pk_mul_f32 v[94:95], v[94:95], v[96:97] op_sel_hi:[1,0]
	v_pk_mul_f32 v[92:93], v[92:93], v[96:97] op_sel_hi:[1,0]
	v_pk_mul_f32 v[90:91], v[90:91], v[96:97] op_sel_hi:[1,0]
	v_pk_mul_f32 v[58:59], v[58:59], v[96:97] op_sel_hi:[1,0]
; DI unsigned pk2(float a, float b) { f32x2 v = {a, b}; bf16x2_t r = __builtin_convertvector(v, bf16x2_t); return __builtin_bit_cast(unsigned, r); }
; DI float bflo(unsigned u) { return __uint_as_float(u << 16); }
; DI float bfhi(unsigned u) { return __uint_as_float(u & 0xffff0000u); }
; DI float siluf_(float x) { return x * __builtin_amdgcn_rcpf(1.f + __expf(-x)); }
; DI void dn_conv_phase(const Params& p) {
;     ...
;         for (int tt = 0; tt < SEG; ++tt) {
;             { const u32x4 u = rows[tt + 4]; const int sl = (tt + 4) % 5;
;               ring[sl][0] = (f32x2){bflo(u.x), bfhi(u.x)}; ring[sl][1] = (f32x2){bflo(u.y), bfhi(u.y)}; ring[sl][2] = (f32x2){bflo(u.z), bfhi(u.z)}; ring[sl][3] = (f32x2){bflo(u.w), bfhi(u.w)}; }
;             f32x2 o2[4];
; #pragma unroll
;             for (int e = 0; e < 4; ++e) o2[e] = w[0][e] * ring[tt % 5][e];
; #pragma unroll
;             for (int j = 1; j < 5; ++j)
; #pragma unroll
;                 for (int e = 0; e < 4; ++e) o2[e] += w[j][e] * ring[(tt + j) % 5][e];
;             float o[8];
; #pragma unroll
;             for (int e = 0; e < 4; ++e) { o[2 * e] = siluf_(o2[e].x); o[2 * e + 1] = siluf_(o2[e].y); }
;             if (part < 2) {
;                 float ss = 0.f;
; #pragma unroll
;                 for (int e = 0; e < 8; ++e) ss += o[e] * o[e];
;                 ss += __shfl_xor(ss, 1); ss += __shfl_xor(ss, 2); ss += __shfl_xor(ss, 4); ss += __shfl_xor(ss, 8);
;                 const float sc = rsqrtf(ss + EPS) * (part == 0 ? 0.08838834764831845f : 1.f);
; #pragma unroll
;                 for (int e = 0; e < 8; ++e) o[e] *= sc;
;             }
;             u32x4 ov; ov.x = pk2(o[0], o[1]); ov.y = pk2(o[2], o[3]); ov.z = pk2(o[4], o[5]); ov.w = pk2(o[6], o[7]);
;             *(u32x4*)(QKV + (size_t)(row0 + tt) * 1536 + ch) = ov;
.LBB0_335:
	s_or_b64 exec, exec, s[24:25]
	v_cvt_pk_bf16_f32 v96, v58, v59
	v_or_b32_e32 v58, 11, v156
	v_cvt_pk_bf16_f32 v97, v90, v91
	v_cvt_pk_bf16_f32 v98, v92, v93
	v_cvt_pk_bf16_f32 v99, v94, v95
	v_mad_i64_i32 v[58:59], s[4:5], v58, s45, v[100:101]
	global_store_dwordx4 v[58:59], v[96:99], off
	v_lshlrev_b32_e32 v92, 16, v52
	v_and_b32_e32 v93, 0xffff0000, v52
	v_lshlrev_b32_e32 v90, 16, v53
	v_and_b32_e32 v91, 0xffff0000, v53
	v_lshlrev_b32_e32 v58, 16, v54
	v_and_b32_e32 v59, 0xffff0000, v54
	v_lshlrev_b32_e32 v52, 16, v55
	v_and_b32_e32 v53, 0xffff0000, v55
	v_pk_mul_f32 v[54:55], v[20:21], v[80:81]
	s_nop 0
	v_pk_fma_f32 v[54:55], v[4:5], v[88:89], v[54:55]
	v_pk_mul_f32 v[88:89], v[22:23], v[78:79]
	v_pk_fma_f32 v[54:55], v[24:25], v[72:73], v[54:55]
	v_pk_fma_f32 v[86:87], v[6:7], v[86:87], v[88:89]
	v_pk_mul_f32 v[88:89], v[12:13], v[76:77]
	v_pk_fma_f32 v[54:55], v[36:37], v[64:65], v[54:55]
	v_pk_fma_f32 v[84:85], v[0:1], v[84:85], v[88:89]
	v_pk_mul_f32 v[88:89], v[14:15], v[74:75]
	v_pk_fma_f32 v[54:55], v[32:33], v[92:93], v[54:55]
	v_pk_fma_f32 v[82:83], v[2:3], v[82:83], v[88:89]
	v_mul_f32_e32 v88, 0xbfb8aa3b, v54
	v_exp_f32_e32 v94, v88
	v_mul_f32_e32 v88, 0xbfb8aa3b, v55
	v_exp_f32_e32 v95, v88
	v_pk_fma_f32 v[86:87], v[26:27], v[70:71], v[86:87]
	v_pk_fma_f32 v[84:85], v[16:17], v[68:69], v[84:85]
	v_pk_fma_f32 v[82:83], v[18:19], v[66:67], v[82:83]
	v_pk_fma_f32 v[86:87], v[38:39], v[62:63], v[86:87]
	v_pk_fma_f32 v[84:85], v[28:29], v[60:61], v[84:85]
	v_pk_fma_f32 v[82:83], v[30:31], v[56:57], v[82:83]
	v_pk_fma_f32 v[86:87], v[34:35], v[90:91], v[86:87]
	v_pk_fma_f32 v[84:85], v[8:9], v[58:59], v[84:85]
	v_pk_fma_f32 v[88:89], v[10:11], v[52:53], v[82:83]
	v_add_f32_e32 v82, 1.0, v94
	v_add_f32_e32 v83, 1.0, v95
	v_mul_f32_e32 v94, 0xbfb8aa3b, v86
	v_mul_f32_e32 v95, 0xbfb8aa3b, v87
	v_mul_f32_e32 v96, 0xbfb8aa3b, v84
	v_mul_f32_e32 v97, 0xbfb8aa3b, v85
	v_mul_f32_e32 v98, 0xbfb8aa3b, v88
	v_mul_f32_e32 v99, 0xbfb8aa3b, v89
	v_exp_f32_e32 v94, v94
	v_exp_f32_e32 v95, v95
	v_exp_f32_e32 v96, v96
	v_exp_f32_e32 v97, v97
	v_exp_f32_e32 v98, v98
	v_exp_f32_e32 v99, v99
	v_add_f32_e32 v94, 1.0, v94
	v_add_f32_e32 v95, 1.0, v95
	v_add_f32_e32 v96, 1.0, v96
	v_add_f32_e32 v97, 1.0, v97
	v_add_f32_e32 v98, 1.0, v98
	v_add_f32_e32 v99, 1.0, v99
	v_rcp_f32_e32 v82, v82
	v_rcp_f32_e32 v83, v83
	v_rcp_f32_e32 v94, v94
	v_rcp_f32_e32 v95, v95
	v_rcp_f32_e32 v96, v96
	v_rcp_f32_e32 v97, v97
	v_rcp_f32_e32 v98, v98
	v_rcp_f32_e32 v99, v99
	v_pk_mul_f32 v[54:55], v[54:55], v[82:83]
	v_pk_mul_f32 v[82:83], v[86:87], v[94:95]
	v_pk_mul_f32 v[84:85], v[84:85], v[96:97]
	v_pk_mul_f32 v[86:87], v[88:89], v[98:99]
	s_and_saveexec_b64 s[24:25], vcc
	s_cbranch_execz .LBB0_337
	v_pk_mul_f32 v[88:89], v[54:55], v[54:55]
	v_pk_mul_f32 v[94:95], v[82:83], v[82:83]
	v_add_f32_e32 v88, v88, v89
	v_add_f32_e32 v88, v94, v88
	v_pk_mul_f32 v[96:97], v[84:85], v[84:85]
	v_add_f32_e32 v88, v95, v88
	v_and_b32_e32 v94, 64, v158
	v_add_f32_e32 v88, v96, v88
	v_xor_b32_e32 v89, 1, v158
	v_add_u32_e32 v94, 64, v94
	v_pk_mul_f32 v[98:99], v[86:87], v[86:87]
	v_add_f32_e32 v88, v97, v88
	v_cmp_lt_i32_e64 s[4:5], v89, v94
	v_add_f32_e32 v88, v98, v88
	v_add_f32_e32 v88, v99, v88
	v_cndmask_b32_e64 v89, v158, v89, s[4:5]
	v_lshlrev_b32_e32 v89, 2, v89
	s_nop 1
	v_mov_b32_dpp v89, v88 quad_perm:[1,0,3,2] row_mask:0xf bank_mask:0xf
	s_waitcnt lgkmcnt(0)
	v_add_f32_e32 v88, v88, v89
	v_xor_b32_e32 v89, 2, v158
	v_cmp_lt_i32_e64 s[4:5], v89, v94
	s_nop 1
	v_cndmask_b32_e64 v89, v158, v89, s[4:5]
	v_lshlrev_b32_e32 v89, 2, v89
	s_nop 1
	v_mov_b32_dpp v89, v88 quad_perm:[2,3,0,1] row_mask:0xf bank_mask:0xf
	s_waitcnt lgkmcnt(0)
	v_add_f32_e32 v88, v88, v89
	v_xor_b32_e32 v89, 4, v158
	v_cmp_lt_i32_e64 s[4:5], v89, v94
	s_nop 1
	v_cndmask_b32_e64 v89, v158, v89, s[4:5]
	v_lshlrev_b32_e32 v89, 2, v89
	s_nop 1
	v_mov_b32_dpp v89, v88 row_half_mirror row_mask:0xf bank_mask:0xf
	s_waitcnt lgkmcnt(0)
	v_add_f32_e32 v88, v88, v89
	v_xor_b32_e32 v89, 8, v158
	v_cmp_lt_i32_e64 s[4:5], v89, v94
	s_nop 1
	v_cndmask_b32_e64 v89, v158, v89, s[4:5]
	v_lshlrev_b32_e32 v89, 2, v89
	s_nop 1
	v_mov_b32_dpp v89, v88 row_ror:8 row_mask:0xf bank_mask:0xf
	s_waitcnt lgkmcnt(0)
	v_add_f32_e32 v88, v88, v89
	v_add_f32_e32 v88, 0x358637bd, v88
	v_mul_f32_e32 v89, 0x4b800000, v88
	v_cmp_gt_f32_e64 s[4:5], s46, v88
	s_nop 1
	v_cndmask_b32_e64 v88, v88, v89, s[4:5]
	v_rsq_f32_e32 v88, v88
	s_nop 0
	v_mul_f32_e32 v89, 0x45800000, v88
	v_cndmask_b32_e64 v88, v88, v89, s[4:5]
	v_mul_f32_e32 v88, v157, v88
	v_pk_mul_f32 v[86:87], v[86:87], v[88:89] op_sel_hi:[1,0]
	v_pk_mul_f32 v[84:85], v[84:85], v[88:89] op_sel_hi:[1,0]
	v_pk_mul_f32 v[82:83], v[82:83], v[88:89] op_sel_hi:[1,0]
	v_pk_mul_f32 v[54:55], v[54:55], v[88:89] op_sel_hi:[1,0]
; DI unsigned pk2(float a, float b) { f32x2 v = {a, b}; bf16x2_t r = __builtin_convertvector(v, bf16x2_t); return __builtin_bit_cast(unsigned, r); }
; DI float bflo(unsigned u) { return __uint_as_float(u << 16); }
; DI float bfhi(unsigned u) { return __uint_as_float(u & 0xffff0000u); }
; DI float siluf_(float x) { return x * __builtin_amdgcn_rcpf(1.f + __expf(-x)); }
; DI void dn_conv_phase(const Params& p) {
;     ...
;         for (int tt = 0; tt < SEG; ++tt) {
;             { const u32x4 u = rows[tt + 4]; const int sl = (tt + 4) % 5;
;               ring[sl][0] = (f32x2){bflo(u.x), bfhi(u.x)}; ring[sl][1] = (f32x2){bflo(u.y), bfhi(u.y)}; ring[sl][2] = (f32x2){bflo(u.z), bfhi(u.z)}; ring[sl][3] = (f32x2){bflo(u.w), bfhi(u.w)}; }
;             f32x2 o2[4];
; #pragma unroll
;             for (int e = 0; e < 4; ++e) o2[e] = w[0][e] * ring[tt % 5][e];
; #pragma unroll
;             for (int j = 1; j < 5; ++j)
; #pragma unroll
;                 for (int e = 0; e < 4; ++e) o2[e] += w[j][e] * ring[(tt + j) % 5][e];
;             float o[8];
; #pragma unroll
;             for (int e = 0; e < 4; ++e) { o[2 * e] = siluf_(o2[e].x); o[2 * e + 1] = siluf_(o2[e].y); }
;             if (part < 2) {
;                 float ss = 0.f;
; #pragma unroll
;                 for (int e = 0; e < 8; ++e) ss += o[e] * o[e];
;                 ss += __shfl_xor(ss, 1); ss += __shfl_xor(ss, 2); ss += __shfl_xor(ss, 4); ss += __shfl_xor(ss, 8);
;                 const float sc = rsqrtf(ss + EPS) * (part == 0 ? 0.08838834764831845f : 1.f);
; #pragma unroll
;                 for (int e = 0; e < 8; ++e) o[e] *= sc;
;             }
;             u32x4 ov; ov.x = pk2(o[0], o[1]); ov.y = pk2(o[2], o[3]); ov.z = pk2(o[4], o[5]); ov.w = pk2(o[6], o[7]);
;             *(u32x4*)(QKV + (size_t)(row0 + tt) * 1536 + ch) = ov;
.LBB0_337:
	s_or_b64 exec, exec, s[24:25]
	v_cvt_pk_bf16_f32 v96, v84, v85
	v_pk_mul_f32 v[84:85], v[20:21], v[72:73]
	v_cvt_pk_bf16_f32 v94, v54, v55
	v_pk_fma_f32 v[80:81], v[4:5], v[80:81], v[84:85]
	v_pk_mul_f32 v[84:85], v[22:23], v[70:71]
	v_or_b32_e32 v54, 12, v156
	v_pk_fma_f32 v[78:79], v[6:7], v[78:79], v[84:85]
	v_pk_mul_f32 v[84:85], v[12:13], v[68:69]
	v_cvt_pk_bf16_f32 v95, v82, v83
	v_cvt_pk_bf16_f32 v97, v86, v87
	v_mad_i64_i32 v[54:55], s[4:5], v54, s45, v[100:101]
	v_pk_fma_f32 v[76:77], v[0:1], v[76:77], v[84:85]
	v_pk_fma_f32 v[80:81], v[24:25], v[64:65], v[80:81]
	global_store_dwordx4 v[54:55], v[94:97], off
	v_lshlrev_b32_e32 v54, 16, v48
	v_and_b32_e32 v55, 0xffff0000, v48
	v_pk_fma_f32 v[76:77], v[16:17], v[60:61], v[76:77]
	v_pk_fma_f32 v[80:81], v[36:37], v[92:93], v[80:81]
	v_lshlrev_b32_e32 v82, 16, v50
	v_and_b32_e32 v83, 0xffff0000, v50
	v_pk_mul_f32 v[84:85], v[14:15], v[66:67]
	v_pk_fma_f32 v[76:77], v[28:29], v[58:59], v[76:77]
	v_pk_fma_f32 v[80:81], v[32:33], v[54:55], v[80:81]
	v_pk_fma_f32 v[74:75], v[2:3], v[74:75], v[84:85]
	v_pk_fma_f32 v[84:85], v[8:9], v[82:83], v[76:77]
	v_mul_f32_e32 v76, 0xbfb8aa3b, v80
	v_mul_f32_e32 v77, 0xbfb8aa3b, v81
	v_exp_f32_e32 v76, v76
	v_exp_f32_e32 v77, v77
	v_pk_fma_f32 v[78:79], v[26:27], v[62:63], v[78:79]
	v_pk_fma_f32 v[74:75], v[18:19], v[56:57], v[74:75]
	v_lshlrev_b32_e32 v48, 16, v49
	v_and_b32_e32 v49, 0xffff0000, v49
	v_lshlrev_b32_e32 v50, 16, v51
	v_and_b32_e32 v51, 0xffff0000, v51
	v_pk_fma_f32 v[78:79], v[38:39], v[90:91], v[78:79]
	v_pk_fma_f32 v[74:75], v[30:31], v[52:53], v[74:75]
	v_pk_fma_f32 v[78:79], v[34:35], v[48:49], v[78:79]
	v_pk_fma_f32 v[86:87], v[10:11], v[50:51], v[74:75]
	v_add_f32_e32 v74, 1.0, v76
	v_add_f32_e32 v75, 1.0, v77
	v_mul_f32_e32 v76, 0xbfb8aa3b, v78
	v_mul_f32_e32 v77, 0xbfb8aa3b, v79
	v_mul_f32_e32 v88, 0xbfb8aa3b, v84
	v_mul_f32_e32 v89, 0xbfb8aa3b, v85
	v_mul_f32_e32 v94, 0xbfb8aa3b, v86
	v_mul_f32_e32 v95, 0xbfb8aa3b, v87
	v_exp_f32_e32 v76, v76
	v_exp_f32_e32 v77, v77
	v_exp_f32_e32 v88, v88
	v_exp_f32_e32 v89, v89
	v_exp_f32_e32 v94, v94
	v_exp_f32_e32 v95, v95
	v_add_f32_e32 v76, 1.0, v76
	v_add_f32_e32 v77, 1.0, v77
	v_add_f32_e32 v88, 1.0, v88
	v_add_f32_e32 v89, 1.0, v89
	v_add_f32_e32 v94, 1.0, v94
	v_add_f32_e32 v95, 1.0, v95
	v_rcp_f32_e32 v74, v74
	v_rcp_f32_e32 v75, v75
	v_rcp_f32_e32 v76, v76
	v_rcp_f32_e32 v77, v77
	v_rcp_f32_e32 v88, v88
	v_rcp_f32_e32 v89, v89
	v_rcp_f32_e32 v94, v94
	v_rcp_f32_e32 v95, v95
	v_pk_mul_f32 v[74:75], v[80:81], v[74:75]
	v_pk_mul_f32 v[76:77], v[78:79], v[76:77]
	v_pk_mul_f32 v[78:79], v[84:85], v[88:89]
	v_pk_mul_f32 v[80:81], v[86:87], v[94:95]
	s_and_saveexec_b64 s[24:25], vcc
	s_cbranch_execz .LBB0_339
	v_pk_mul_f32 v[84:85], v[74:75], v[74:75]
	v_pk_mul_f32 v[86:87], v[76:77], v[76:77]
	v_add_f32_e32 v84, v84, v85
	v_add_f32_e32 v84, v86, v84
	v_pk_mul_f32 v[88:89], v[78:79], v[78:79]
	v_add_f32_e32 v84, v87, v84
	v_and_b32_e32 v86, 64, v158
	v_add_f32_e32 v84, v88, v84
	v_xor_b32_e32 v85, 1, v158
	v_add_u32_e32 v86, 64, v86
	v_pk_mul_f32 v[94:95], v[80:81], v[80:81]
	v_add_f32_e32 v84, v89, v84
	v_cmp_lt_i32_e64 s[4:5], v85, v86
	v_add_f32_e32 v84, v94, v84
	v_add_f32_e32 v84, v95, v84
	v_cndmask_b32_e64 v85, v158, v85, s[4:5]
	v_lshlrev_b32_e32 v85, 2, v85
	s_nop 1
	v_mov_b32_dpp v85, v84 quad_perm:[1,0,3,2] row_mask:0xf bank_mask:0xf
	s_waitcnt lgkmcnt(0)
	v_add_f32_e32 v84, v84, v85
	v_xor_b32_e32 v85, 2, v158
	v_cmp_lt_i32_e64 s[4:5], v85, v86
	s_nop 1
	v_cndmask_b32_e64 v85, v158, v85, s[4:5]
	v_lshlrev_b32_e32 v85, 2, v85
	s_nop 1
	v_mov_b32_dpp v85, v84 quad_perm:[2,3,0,1] row_mask:0xf bank_mask:0xf
	s_waitcnt lgkmcnt(0)
	v_add_f32_e32 v84, v84, v85
	v_xor_b32_e32 v85, 4, v158
	v_cmp_lt_i32_e64 s[4:5], v85, v86
	s_nop 1
	v_cndmask_b32_e64 v85, v158, v85, s[4:5]
	v_lshlrev_b32_e32 v85, 2, v85
	s_nop 1
	v_mov_b32_dpp v85, v84 row_half_mirror row_mask:0xf bank_mask:0xf
	s_waitcnt lgkmcnt(0)
	v_add_f32_e32 v84, v84, v85
	v_xor_b32_e32 v85, 8, v158
	v_cmp_lt_i32_e64 s[4:5], v85, v86
	s_nop 1
	v_cndmask_b32_e64 v85, v158, v85, s[4:5]
	v_lshlrev_b32_e32 v85, 2, v85
	s_nop 1
	v_mov_b32_dpp v85, v84 row_ror:8 row_mask:0xf bank_mask:0xf
	s_waitcnt lgkmcnt(0)
	v_add_f32_e32 v84, v84, v85
	v_add_f32_e32 v84, 0x358637bd, v84
	v_mul_f32_e32 v85, 0x4b800000, v84
	v_cmp_gt_f32_e64 s[4:5], s46, v84
	s_nop 1
	v_cndmask_b32_e64 v84, v84, v85, s[4:5]
	v_rsq_f32_e32 v84, v84
	s_nop 0
	v_mul_f32_e32 v85, 0x45800000, v84
	v_cndmask_b32_e64 v84, v84, v85, s[4:5]
	v_mul_f32_e32 v84, v157, v84
	v_pk_mul_f32 v[80:81], v[80:81], v[84:85] op_sel_hi:[1,0]
	v_pk_mul_f32 v[78:79], v[78:79], v[84:85] op_sel_hi:[1,0]
	v_pk_mul_f32 v[76:77], v[76:77], v[84:85] op_sel_hi:[1,0]
	v_pk_mul_f32 v[74:75], v[74:75], v[84:85] op_sel_hi:[1,0]
; DI unsigned pk2(float a, float b) { f32x2 v = {a, b}; bf16x2_t r = __builtin_convertvector(v, bf16x2_t); return __builtin_bit_cast(unsigned, r); }
; DI float bflo(unsigned u) { return __uint_as_float(u << 16); }
; DI float bfhi(unsigned u) { return __uint_as_float(u & 0xffff0000u); }
; DI float siluf_(float x) { return x * __builtin_amdgcn_rcpf(1.f + __expf(-x)); }
; DI void dn_conv_phase(const Params& p) {
;     ...
;         for (int tt = 0; tt < SEG; ++tt) {
;             { const u32x4 u = rows[tt + 4]; const int sl = (tt + 4) % 5;
;               ring[sl][0] = (f32x2){bflo(u.x), bfhi(u.x)}; ring[sl][1] = (f32x2){bflo(u.y), bfhi(u.y)}; ring[sl][2] = (f32x2){bflo(u.z), bfhi(u.z)}; ring[sl][3] = (f32x2){bflo(u.w), bfhi(u.w)}; }
;             f32x2 o2[4];
; #pragma unroll
;             for (int e = 0; e < 4; ++e) o2[e] = w[0][e] * ring[tt % 5][e];
; #pragma unroll
;             for (int j = 1; j < 5; ++j)
; #pragma unroll
;                 for (int e = 0; e < 4; ++e) o2[e] += w[j][e] * ring[(tt + j) % 5][e];
;             float o[8];
; #pragma unroll
;             for (int e = 0; e < 4; ++e) { o[2 * e] = siluf_(o2[e].x); o[2 * e + 1] = siluf_(o2[e].y); }
;             if (part < 2) {
;                 float ss = 0.f;
; #pragma unroll
;                 for (int e = 0; e < 8; ++e) ss += o[e] * o[e];
;                 ss += __shfl_xor(ss, 1); ss += __shfl_xor(ss, 2); ss += __shfl_xor(ss, 4); ss += __shfl_xor(ss, 8);
;                 const float sc = rsqrtf(ss + EPS) * (part == 0 ? 0.08838834764831845f : 1.f);
; #pragma unroll
;                 for (int e = 0; e < 8; ++e) o[e] *= sc;
;             }
;             u32x4 ov; ov.x = pk2(o[0], o[1]); ov.y = pk2(o[2], o[3]); ov.z = pk2(o[4], o[5]); ov.w = pk2(o[6], o[7]);
;             *(u32x4*)(QKV + (size_t)(row0 + tt) * 1536 + ch) = ov;
.LBB0_339:
	s_or_b64 exec, exec, s[24:25]
	v_cvt_pk_bf16_f32 v74, v74, v75
	v_cvt_pk_bf16_f32 v75, v76, v77
	v_cvt_pk_bf16_f32 v76, v78, v79
	v_or_b32_e32 v78, 13, v156
	v_cvt_pk_bf16_f32 v77, v80, v81
	v_mad_i64_i32 v[78:79], s[4:5], v78, s45, v[100:101]
	global_store_dwordx4 v[78:79], v[74:77], off
	v_pk_mul_f32 v[78:79], v[20:21], v[64:65]
	s_nop 0
	v_pk_fma_f32 v[72:73], v[4:5], v[72:73], v[78:79]
	v_pk_mul_f32 v[78:79], v[22:23], v[62:63]
	v_pk_fma_f32 v[72:73], v[24:25], v[92:93], v[72:73]
	v_pk_fma_f32 v[70:71], v[6:7], v[70:71], v[78:79]
	v_pk_mul_f32 v[78:79], v[12:13], v[60:61]
	v_lshlrev_b32_e32 v74, 16, v44
	v_pk_fma_f32 v[68:69], v[0:1], v[68:69], v[78:79]
	v_and_b32_e32 v75, 0xffff0000, v44
	v_pk_fma_f32 v[68:69], v[16:17], v[58:59], v[68:69]
	v_pk_fma_f32 v[72:73], v[36:37], v[54:55], v[72:73]
	v_lshlrev_b32_e32 v76, 16, v46
	v_and_b32_e32 v77, 0xffff0000, v46
	v_pk_mul_f32 v[78:79], v[14:15], v[56:57]
	v_pk_fma_f32 v[68:69], v[28:29], v[82:83], v[68:69]
	v_pk_fma_f32 v[72:73], v[32:33], v[74:75], v[72:73]
	v_pk_fma_f32 v[66:67], v[2:3], v[66:67], v[78:79]
	v_pk_fma_f32 v[78:79], v[8:9], v[76:77], v[68:69]
	v_mul_f32_e32 v68, 0xbfb8aa3b, v72
	v_mul_f32_e32 v69, 0xbfb8aa3b, v73
	v_exp_f32_e32 v68, v68
	v_exp_f32_e32 v69, v69
	v_pk_fma_f32 v[70:71], v[26:27], v[90:91], v[70:71]
	v_pk_fma_f32 v[66:67], v[18:19], v[52:53], v[66:67]
	v_lshlrev_b32_e32 v44, 16, v45
	v_and_b32_e32 v45, 0xffff0000, v45
	v_lshlrev_b32_e32 v46, 16, v47
	v_and_b32_e32 v47, 0xffff0000, v47
	v_pk_fma_f32 v[70:71], v[38:39], v[48:49], v[70:71]
	v_pk_fma_f32 v[66:67], v[30:31], v[50:51], v[66:67]
	v_pk_fma_f32 v[70:71], v[34:35], v[44:45], v[70:71]
	v_pk_fma_f32 v[80:81], v[10:11], v[46:47], v[66:67]
	v_add_f32_e32 v66, 1.0, v68
	v_add_f32_e32 v67, 1.0, v69
	v_mul_f32_e32 v68, 0xbfb8aa3b, v70
	v_mul_f32_e32 v69, 0xbfb8aa3b, v71
	v_mul_f32_e32 v84, 0xbfb8aa3b, v78
	v_mul_f32_e32 v85, 0xbfb8aa3b, v79
	v_mul_f32_e32 v86, 0xbfb8aa3b, v80
	v_mul_f32_e32 v87, 0xbfb8aa3b, v81
	v_exp_f32_e32 v68, v68
	v_exp_f32_e32 v69, v69
	v_exp_f32_e32 v84, v84
	v_exp_f32_e32 v85, v85
	v_exp_f32_e32 v86, v86
	v_exp_f32_e32 v87, v87
	v_add_f32_e32 v68, 1.0, v68
	v_add_f32_e32 v69, 1.0, v69
	v_add_f32_e32 v84, 1.0, v84
	v_add_f32_e32 v85, 1.0, v85
	v_add_f32_e32 v86, 1.0, v86
	v_add_f32_e32 v87, 1.0, v87
	v_rcp_f32_e32 v66, v66
	v_rcp_f32_e32 v67, v67
	v_rcp_f32_e32 v68, v68
	v_rcp_f32_e32 v69, v69
	v_rcp_f32_e32 v84, v84
	v_rcp_f32_e32 v85, v85
	v_rcp_f32_e32 v86, v86
	v_rcp_f32_e32 v87, v87
	v_pk_mul_f32 v[66:67], v[72:73], v[66:67]
	v_pk_mul_f32 v[68:69], v[70:71], v[68:69]
	v_pk_mul_f32 v[70:71], v[78:79], v[84:85]
	v_pk_mul_f32 v[72:73], v[80:81], v[86:87]
	s_and_saveexec_b64 s[24:25], vcc
	s_cbranch_execz .LBB0_341
	v_pk_mul_f32 v[78:79], v[66:67], v[66:67]
	v_pk_mul_f32 v[80:81], v[68:69], v[68:69]
	v_add_f32_e32 v78, v78, v79
	v_add_f32_e32 v78, v80, v78
	v_pk_mul_f32 v[84:85], v[70:71], v[70:71]
	v_add_f32_e32 v78, v81, v78
	v_and_b32_e32 v80, 64, v158
	v_add_f32_e32 v78, v84, v78
	v_xor_b32_e32 v79, 1, v158
	v_add_u32_e32 v80, 64, v80
	v_pk_mul_f32 v[86:87], v[72:73], v[72:73]
	v_add_f32_e32 v78, v85, v78
	v_cmp_lt_i32_e64 s[4:5], v79, v80
	v_add_f32_e32 v78, v86, v78
	v_add_f32_e32 v78, v87, v78
	v_cndmask_b32_e64 v79, v158, v79, s[4:5]
	v_lshlrev_b32_e32 v79, 2, v79
	s_nop 1
	v_mov_b32_dpp v79, v78 quad_perm:[1,0,3,2] row_mask:0xf bank_mask:0xf
	s_waitcnt lgkmcnt(0)
	v_add_f32_e32 v78, v78, v79
	v_xor_b32_e32 v79, 2, v158
	v_cmp_lt_i32_e64 s[4:5], v79, v80
	s_nop 1
	v_cndmask_b32_e64 v79, v158, v79, s[4:5]
	v_lshlrev_b32_e32 v79, 2, v79
	s_nop 1
	v_mov_b32_dpp v79, v78 quad_perm:[2,3,0,1] row_mask:0xf bank_mask:0xf
	s_waitcnt lgkmcnt(0)
	v_add_f32_e32 v78, v78, v79
	v_xor_b32_e32 v79, 4, v158
	v_cmp_lt_i32_e64 s[4:5], v79, v80
	s_nop 1
	v_cndmask_b32_e64 v79, v158, v79, s[4:5]
	v_lshlrev_b32_e32 v79, 2, v79
	s_nop 1
	v_mov_b32_dpp v79, v78 row_half_mirror row_mask:0xf bank_mask:0xf
	s_waitcnt lgkmcnt(0)
	v_add_f32_e32 v78, v78, v79
	v_xor_b32_e32 v79, 8, v158
	v_cmp_lt_i32_e64 s[4:5], v79, v80
	s_nop 1
	v_cndmask_b32_e64 v79, v158, v79, s[4:5]
	v_lshlrev_b32_e32 v79, 2, v79
	s_nop 1
	v_mov_b32_dpp v79, v78 row_ror:8 row_mask:0xf bank_mask:0xf
	s_waitcnt lgkmcnt(0)
	v_add_f32_e32 v78, v78, v79
	v_add_f32_e32 v78, 0x358637bd, v78
	v_mul_f32_e32 v79, 0x4b800000, v78
	v_cmp_gt_f32_e64 s[4:5], s46, v78
	s_nop 1
	v_cndmask_b32_e64 v78, v78, v79, s[4:5]
	v_rsq_f32_e32 v78, v78
	s_nop 0
	v_mul_f32_e32 v79, 0x45800000, v78
	v_cndmask_b32_e64 v78, v78, v79, s[4:5]
	v_mul_f32_e32 v78, v157, v78
	v_pk_mul_f32 v[72:73], v[72:73], v[78:79] op_sel_hi:[1,0]
	v_pk_mul_f32 v[70:71], v[70:71], v[78:79] op_sel_hi:[1,0]
	v_pk_mul_f32 v[68:69], v[68:69], v[78:79] op_sel_hi:[1,0]
	v_pk_mul_f32 v[66:67], v[66:67], v[78:79] op_sel_hi:[1,0]
; DI float siluf_(float x) { return x * __builtin_amdgcn_rcpf(1.f + __expf(-x)); }
; DI void dn_conv_phase(const Params& p) {
;     ...
;             for (int e = 0; e < 4; ++e) o2[e] = w[0][e] * ring[tt % 5][e];
; #pragma unroll
;             for (int j = 1; j < 5; ++j)
; #pragma unroll
;                 for (int e = 0; e < 4; ++e) o2[e] += w[j][e] * ring[(tt + j) % 5][e];
;             float o[8];
; #pragma unroll
;             for (int e = 0; e < 4; ++e) { o[2 * e] = siluf_(o2[e].x); o[2 * e + 1] = siluf_(o2[e].y); }
;             if (part < 2) {
;                 float ss = 0.f;
; #pragma unroll
;                 for (int e = 0; e < 8; ++e) ss += o[e] * o[e];
;                 ss += __shfl_xor(ss, 1); ss += __shfl_xor(ss, 2); ss += __shfl_xor(ss, 4); ss += __shfl_xor(ss, 8);
;                 const float sc = rsqrtf(ss + EPS) * (part == 0 ? 0.08838834764831845f : 1.f);
; #pragma unroll
;                 for (int e = 0; e < 8; ++e) o[e] *= sc;
.LBB0_341:
	s_or_b64 exec, exec, s[24:25]
	v_pk_mul_f32 v[20:21], v[20:21], v[92:93]
	v_pk_mul_f32 v[12:13], v[12:13], v[58:59]
	v_pk_fma_f32 v[4:5], v[4:5], v[64:65], v[20:21]
	v_pk_mul_f32 v[20:21], v[22:23], v[90:91]
	v_pk_fma_f32 v[0:1], v[0:1], v[60:61], v[12:13]
	v_pk_mul_f32 v[12:13], v[14:15], v[52:53]
	v_cvt_pk_bf16_f32 v66, v66, v67
	v_cvt_pk_bf16_f32 v67, v68, v69
	v_cvt_pk_bf16_f32 v68, v70, v71
	v_or_b32_e32 v70, 14, v156
	v_pk_fma_f32 v[6:7], v[6:7], v[62:63], v[20:21]
	v_pk_fma_f32 v[2:3], v[2:3], v[56:57], v[12:13]
	v_cvt_pk_bf16_f32 v69, v72, v73
	v_mad_i64_i32 v[70:71], s[4:5], v70, s45, v[100:101]
	v_pk_fma_f32 v[4:5], v[24:25], v[54:55], v[4:5]
	v_pk_fma_f32 v[6:7], v[26:27], v[48:49], v[6:7]
	v_pk_fma_f32 v[0:1], v[16:17], v[82:83], v[0:1]
	v_pk_fma_f32 v[2:3], v[18:19], v[50:51], v[2:3]
	global_store_dwordx4 v[70:71], v[66:69], off
	v_pk_fma_f32 v[4:5], v[36:37], v[74:75], v[4:5]
	v_pk_fma_f32 v[6:7], v[38:39], v[44:45], v[6:7]
	v_lshlrev_b32_e32 v66, 16, v40
	v_and_b32_e32 v67, 0xffff0000, v40
	v_lshlrev_b32_e32 v40, 16, v41
	v_and_b32_e32 v41, 0xffff0000, v41
	v_lshlrev_b32_e32 v68, 16, v42
	v_and_b32_e32 v69, 0xffff0000, v42
	v_lshlrev_b32_e32 v42, 16, v43
	v_and_b32_e32 v43, 0xffff0000, v43
	v_pk_fma_f32 v[0:1], v[28:29], v[76:77], v[0:1]
	v_pk_fma_f32 v[2:3], v[30:31], v[46:47], v[2:3]
	v_pk_fma_f32 v[4:5], v[32:33], v[66:67], v[4:5]
	v_pk_fma_f32 v[6:7], v[34:35], v[40:41], v[6:7]
	v_pk_fma_f32 v[8:9], v[8:9], v[68:69], v[0:1]
	v_pk_fma_f32 v[10:11], v[10:11], v[42:43], v[2:3]
	v_mul_f32_e32 v0, 0xbfb8aa3b, v4
	v_mul_f32_e32 v1, 0xbfb8aa3b, v5
	v_mul_f32_e32 v2, 0xbfb8aa3b, v6
	v_mul_f32_e32 v3, 0xbfb8aa3b, v7
	v_mul_f32_e32 v12, 0xbfb8aa3b, v8
	v_mul_f32_e32 v13, 0xbfb8aa3b, v9
	v_mul_f32_e32 v14, 0xbfb8aa3b, v10
	v_mul_f32_e32 v15, 0xbfb8aa3b, v11
	v_exp_f32_e32 v0, v0
	v_exp_f32_e32 v1, v1
	v_exp_f32_e32 v2, v2
	v_exp_f32_e32 v3, v3
	v_exp_f32_e32 v12, v12
	v_exp_f32_e32 v13, v13
	v_exp_f32_e32 v14, v14
	v_exp_f32_e32 v15, v15
	v_add_f32_e32 v0, 1.0, v0
	v_add_f32_e32 v1, 1.0, v1
	v_add_f32_e32 v2, 1.0, v2
	v_add_f32_e32 v3, 1.0, v3
	v_add_f32_e32 v12, 1.0, v12
	v_add_f32_e32 v13, 1.0, v13
	v_add_f32_e32 v14, 1.0, v14
	v_add_f32_e32 v15, 1.0, v15
	v_rcp_f32_e32 v0, v0
	v_rcp_f32_e32 v1, v1
	v_rcp_f32_e32 v2, v2
	v_rcp_f32_e32 v3, v3
	v_rcp_f32_e32 v12, v12
	v_rcp_f32_e32 v13, v13
	v_rcp_f32_e32 v14, v14
	v_rcp_f32_e32 v15, v15
	v_pk_mul_f32 v[0:1], v[4:5], v[0:1]
	v_pk_mul_f32 v[2:3], v[6:7], v[2:3]
	v_pk_mul_f32 v[4:5], v[8:9], v[12:13]
	v_pk_mul_f32 v[6:7], v[10:11], v[14:15]
	s_and_saveexec_b64 s[4:5], vcc
	s_cbranch_execz .LBB0_278
	v_pk_mul_f32 v[8:9], v[0:1], v[0:1]
	v_pk_mul_f32 v[10:11], v[2:3], v[2:3]
	v_add_f32_e32 v8, v8, v9
	v_add_f32_e32 v8, v10, v8
	v_pk_mul_f32 v[12:13], v[4:5], v[4:5]
	v_add_f32_e32 v8, v11, v8
	v_and_b32_e32 v10, 64, v158
	v_add_f32_e32 v8, v12, v8
	v_xor_b32_e32 v9, 1, v158
	v_add_u32_e32 v10, 64, v10
	v_pk_mul_f32 v[14:15], v[6:7], v[6:7]
	v_add_f32_e32 v8, v13, v8
	v_cmp_lt_i32_e32 vcc, v9, v10
	v_add_f32_e32 v8, v14, v8
	v_add_f32_e32 v8, v15, v8
	v_cndmask_b32_e32 v9, v158, v9, vcc
	v_lshlrev_b32_e32 v9, 2, v9
	s_nop 1
	v_mov_b32_dpp v9, v8 quad_perm:[1,0,3,2] row_mask:0xf bank_mask:0xf
	s_waitcnt lgkmcnt(0)
	v_add_f32_e32 v8, v8, v9
	v_xor_b32_e32 v9, 2, v158
	v_cmp_lt_i32_e32 vcc, v9, v10
	s_nop 1
	v_cndmask_b32_e32 v9, v158, v9, vcc
	v_lshlrev_b32_e32 v9, 2, v9
	s_nop 1
	v_mov_b32_dpp v9, v8 quad_perm:[2,3,0,1] row_mask:0xf bank_mask:0xf
	s_waitcnt lgkmcnt(0)
	v_add_f32_e32 v8, v8, v9
	v_xor_b32_e32 v9, 4, v158
	v_cmp_lt_i32_e32 vcc, v9, v10
	s_nop 1
	v_cndmask_b32_e32 v9, v158, v9, vcc
	v_lshlrev_b32_e32 v9, 2, v9
	s_nop 1
	v_mov_b32_dpp v9, v8 row_half_mirror row_mask:0xf bank_mask:0xf
	s_waitcnt lgkmcnt(0)
	v_add_f32_e32 v8, v8, v9
	v_xor_b32_e32 v9, 8, v158
	v_cmp_lt_i32_e32 vcc, v9, v10
	s_nop 1
	v_cndmask_b32_e32 v9, v158, v9, vcc
	v_lshlrev_b32_e32 v9, 2, v9
	s_nop 1
	v_mov_b32_dpp v9, v8 row_ror:8 row_mask:0xf bank_mask:0xf
	s_waitcnt lgkmcnt(0)
	v_add_f32_e32 v8, v8, v9
	v_add_f32_e32 v8, 0x358637bd, v8
	v_mul_f32_e32 v9, 0x4b800000, v8
	v_cmp_gt_f32_e32 vcc, s46, v8
	s_nop 1
	v_cndmask_b32_e32 v8, v8, v9, vcc
	v_rsq_f32_e32 v8, v8
	s_nop 0
	v_mul_f32_e32 v9, 0x45800000, v8
	v_cndmask_b32_e32 v8, v8, v9, vcc
	v_mul_f32_e32 v8, v157, v8
	v_pk_mul_f32 v[6:7], v[6:7], v[8:9] op_sel_hi:[1,0]
	v_pk_mul_f32 v[4:5], v[4:5], v[8:9] op_sel_hi:[1,0]
	v_pk_mul_f32 v[2:3], v[2:3], v[8:9] op_sel_hi:[1,0]
	v_pk_mul_f32 v[0:1], v[0:1], v[8:9] op_sel_hi:[1,0]
	s_branch .LBB0_278

; DI float bflo(unsigned u) { return __uint_as_float(u << 16); }
; DI float bfhi(unsigned u) { return __uint_as_float(u & 0xffff0000u); }
; DI void finalize_phase(const Params& p) {
;     ...
;             const int col = 512 * part + 8 * lane;
;             const u32x4 a = *(const u32x4*)(O0 + (size_t)row * 1024 + col), bq = *(const u32x4*)(O1 + (size_t)row * 1024 + col);
;             const u32x4 gt = *(const u32x4*)(P + (size_t)row * P2W + (part ? 2048 : 0) + 8 * lane);
;             float o[8], g[8];
;             o[0] = bflo(a.x) + bflo(bq.x); o[1] = bfhi(a.x) + bfhi(bq.x); o[2] = bflo(a.y) + bflo(bq.y); o[3] = bfhi(a.y) + bfhi(bq.y);
;             o[4] = bflo(a.z) + bflo(bq.z); o[5] = bfhi(a.z) + bfhi(bq.z); o[6] = bflo(a.w) + bflo(bq.w); o[7] = bfhi(a.w) + bfhi(bq.w);
;             g[0] = bflo(gt.x); g[1] = bfhi(gt.x); g[2] = bflo(gt.y); g[3] = bfhi(gt.y); g[4] = bflo(gt.z); g[5] = bfhi(gt.z); g[6] = bflo(gt.w); g[7] = bfhi(gt.w);
;             float ss = 0.f;
; #pragma unroll
;             for (int e = 0; e < 8; ++e) ss += o[e] * o[e];
;             ss += __shfl_xor(ss, 1); ss += __shfl_xor(ss, 2); ss += __shfl_xor(ss, 4); ss += __shfl_xor(ss, 8);
;             const float rstd = rsqrtf(ss * (1.f / 128.f) + EPS);
.LBB0_653:
	v_lshl_add_u64 v[38:39], v[18:19], 0, v[10:11]
	v_add_co_u32_e32 v22, vcc, 0x2376000, v38
	v_lshl_add_u64 v[24:25], v[16:17], 0, v[10:11]
	s_nop 0
	v_addc_co_u32_e32 v23, vcc, 0, v39, vcc
	v_add_co_u32_e32 v46, vcc, 0xa376000, v38
	v_add_co_u32_e64 v50, s[4:5], s23, v24
	s_nop 0
	v_addc_co_u32_e32 v47, vcc, 0, v39, vcc
	v_add_co_u32_e32 v24, vcc, 0x1ef76000, v24
	global_load_dwordx4 v[0:3], v[12:13], off offset:16
	global_load_dwordx4 v[4:7], v[12:13], off
	v_addc_co_u32_e64 v51, s[4:5], 0, v25, s[4:5]
	global_load_dwordx4 v[30:33], v[22:23], off
	global_load_dwordx4 v[34:37], v[22:23], off offset:1024
	global_load_dwordx4 v[38:41], v[46:47], off
	global_load_dwordx4 v[42:45], v[46:47], off offset:1024
	v_addc_co_u32_e32 v25, vcc, 0, v25, vcc
	global_load_dwordx4 v[46:49], v[24:25], off
	v_add_u32_e32 v8, s12, v8
	v_lshl_add_u64 v[16:17], v[16:17], 0, s[14:15]
	v_lshl_add_u64 v[18:19], v[18:19], 0, s[16:17]
	s_waitcnt vmcnt(0)
	v_lshlrev_b32_e32 v24, 16, v33
	v_and_b32_e32 v25, 0xffff0000, v33
	v_lshlrev_b32_e32 v52, 16, v32
	v_and_b32_e32 v53, 0xffff0000, v32
	v_lshlrev_b32_e32 v32, 16, v31
	v_and_b32_e32 v33, 0xffff0000, v31
	v_lshlrev_b32_e32 v54, 16, v30
	v_and_b32_e32 v55, 0xffff0000, v30
	v_lshlrev_b32_e32 v30, 16, v37
	v_and_b32_e32 v31, 0xffff0000, v37
	v_lshlrev_b32_e32 v56, 16, v36
	v_and_b32_e32 v57, 0xffff0000, v36
	v_lshlrev_b32_e32 v36, 16, v35
	v_and_b32_e32 v37, 0xffff0000, v35
	v_lshlrev_b32_e32 v58, 16, v34
	v_and_b32_e32 v59, 0xffff0000, v34
	v_lshlrev_b32_e32 v34, 16, v41
	v_and_b32_e32 v35, 0xffff0000, v41
	v_lshlrev_b32_e32 v60, 16, v40
	v_and_b32_e32 v61, 0xffff0000, v40
	v_lshlrev_b32_e32 v40, 16, v39
	v_and_b32_e32 v41, 0xffff0000, v39
	v_lshlrev_b32_e32 v62, 16, v38
	v_and_b32_e32 v63, 0xffff0000, v38
	v_lshlrev_b32_e32 v38, 16, v45
	v_and_b32_e32 v39, 0xffff0000, v45
	v_lshlrev_b32_e32 v64, 16, v44
	v_and_b32_e32 v65, 0xffff0000, v44
	v_lshlrev_b32_e32 v44, 16, v43
	v_and_b32_e32 v45, 0xffff0000, v43
	v_lshlrev_b32_e32 v66, 16, v42
	v_and_b32_e32 v67, 0xffff0000, v42
	v_pk_add_f32 v[24:25], v[24:25], v[34:35]
	v_lshlrev_b32_e32 v34, 16, v49
	v_and_b32_e32 v35, 0xffff0000, v49
	v_pk_add_f32 v[42:43], v[52:53], v[60:61]
	v_lshlrev_b32_e32 v52, 16, v48
	v_and_b32_e32 v53, 0xffff0000, v48
	v_pk_add_f32 v[48:49], v[54:55], v[62:63]
	v_pk_add_f32 v[36:37], v[36:37], v[44:45]
	v_pk_add_f32 v[44:45], v[58:59], v[66:67]
	v_pk_add_f32 v[32:33], v[32:33], v[40:41]
	v_lshlrev_b32_e32 v40, 16, v47
	v_and_b32_e32 v41, 0xffff0000, v47
	v_lshlrev_b32_e32 v54, 16, v46
	v_and_b32_e32 v55, 0xffff0000, v46
	v_pk_add_f32 v[38:39], v[30:31], v[38:39]
	v_pk_add_f32 v[46:47], v[56:57], v[64:65]
	v_mov_b32_e32 v68, v45
	v_mov_b32_e32 v69, v49
	v_pk_mul_f32 v[30:31], v[24:25], v[24:25]
	v_pk_mul_f32 v[56:57], v[42:43], v[42:43]
	v_pk_mul_f32 v[58:59], v[32:33], v[32:33]
	v_mul_f32_e32 v70, 0xbfb8aa3b, v40
	v_mul_f32_e32 v71, 0xbfb8aa3b, v41
	v_pk_mul_f32 v[60:61], v[38:39], v[38:39]
	v_pk_mul_f32 v[62:63], v[46:47], v[46:47]
	v_pk_mul_f32 v[64:65], v[36:37], v[36:37]
	v_mov_b32_e32 v66, v44
	v_mov_b32_e32 v67, v48
	v_pk_mul_f32 v[68:69], v[68:69], v[68:69]
	v_exp_f32_e32 v76, v70
	v_exp_f32_e32 v77, v71
	v_mov_b32_e32 v70, v64
	v_mov_b32_e32 v71, v58
	v_mov_b32_e32 v58, v65
	v_mov_b32_e32 v64, v62
	v_mov_b32_e32 v65, v56
	v_mov_b32_e32 v56, v63
	v_mov_b32_e32 v62, v60
	v_mov_b32_e32 v63, v30
	v_mov_b32_e32 v30, v61
	v_pk_fma_f32 v[60:61], v[66:67], v[66:67], v[68:69]
	v_mul_f32_e32 v9, 0xbfb8aa3b, v52
	v_pk_add_f32 v[60:61], v[70:71], v[60:61]
	v_exp_f32_e32 v9, v9
	v_pk_add_f32 v[58:59], v[58:59], v[60:61]
	v_mul_f32_e32 v29, 0xbfb8aa3b, v53
	v_pk_add_f32 v[58:59], v[64:65], v[58:59]
	v_mul_f32_e32 v72, 0xbfb8aa3b, v54
	v_pk_add_f32 v[56:57], v[56:57], v[58:59]
	v_mul_f32_e32 v73, 0xbfb8aa3b, v55
	v_pk_add_f32 v[56:57], v[62:63], v[56:57]
	v_mul_f32_e32 v74, 0xbfb8aa3b, v34
	v_pk_add_f32 v[30:31], v[30:31], v[56:57]
	s_nop 1
	v_mov_b32_dpp v57, v31 quad_perm:[1,0,3,2] row_mask:0xf bank_mask:0xf
	s_nop 1
	v_mov_b32_dpp v56, v30 quad_perm:[1,0,3,2] row_mask:0xf bank_mask:0xf
	v_mul_f32_e32 v75, 0xbfb8aa3b, v35
	v_add_f32_e32 v9, 1.0, v9
	v_exp_f32_e32 v29, v29
	v_exp_f32_e32 v72, v72
	s_waitcnt lgkmcnt(0)
	v_pk_add_f32 v[30:31], v[30:31], v[56:57]
	s_nop 1
	v_mov_b32_dpp v57, v31 quad_perm:[2,3,0,1] row_mask:0xf bank_mask:0xf
	s_nop 1
	v_mov_b32_dpp v56, v30 quad_perm:[2,3,0,1] row_mask:0xf bank_mask:0xf
	v_exp_f32_e32 v73, v73
	v_exp_f32_e32 v74, v74
	v_exp_f32_e32 v75, v75
	v_rcp_f32_e32 v60, v9
	s_waitcnt lgkmcnt(0)
; DI unsigned pk2(float a, float b) { f32x2 v = {a, b}; bf16x2_t r = __builtin_convertvector(v, bf16x2_t); return __builtin_bit_cast(unsigned, r); }
; DI float sigmoidf_(float x) { return __builtin_amdgcn_rcpf(1.f + __expf(-x)); }
; DI float siluf_(float x) { return x * __builtin_amdgcn_rcpf(1.f + __expf(-x)); }
; DI void finalize_phase(const Params& p) {
;     ...
;             const float rstd = rsqrtf(ss * (1.f / 128.f) + EPS);
;             const float* nw = part ? p.ml_norm + 8 * lane : p.dn_norm + ((8 * lane) & 127);
;             const f32x4 n0 = *(const f32x4*)nw, n1 = *(const f32x4*)(nw + 4);
;             const float nn[8] = {n0.x, n0.y, n0.z, n0.w, n1.x, n1.y, n1.z, n1.w};
;             float y[8];
; #pragma unroll
;             for (int e = 0; e < 8; ++e) y[e] = o[e] * rstd * nn[e] * (part ? sigmoidf_(g[e]) : siluf_(g[e]));
;             u32x4 ov; ov.x = pk2(y[0], y[1]); ov.y = pk2(y[2], y[3]); ov.z = pk2(y[4], y[5]); ov.w = pk2(y[6], y[7]);
;             *(u32x4*)(O0 + (size_t)row * 1024 + col) = ov;
	v_pk_add_f32 v[30:31], v[30:31], v[56:57]
	s_nop 1
	v_mov_b32_dpp v57, v31 row_half_mirror row_mask:0xf bank_mask:0xf
	s_nop 1
	v_mov_b32_dpp v56, v30 row_half_mirror row_mask:0xf bank_mask:0xf
	v_add_f32_e32 v29, 1.0, v29
	v_add_f32_e32 v66, 1.0, v76
	v_add_f32_e32 v67, 1.0, v77
	v_add_f32_e32 v68, 1.0, v72
	s_waitcnt lgkmcnt(0)
	v_pk_add_f32 v[30:31], v[30:31], v[56:57]
	s_nop 1
	v_mov_b32_dpp v57, v31 row_ror:8 row_mask:0xf bank_mask:0xf
	s_nop 1
	v_mov_b32_dpp v56, v30 row_ror:8 row_mask:0xf bank_mask:0xf
	v_add_f32_e32 v69, 1.0, v73
	v_add_f32_e32 v70, 1.0, v74
	v_add_f32_e32 v71, 1.0, v75
	v_rcp_f32_e32 v61, v29
	s_waitcnt lgkmcnt(0)
	v_pk_add_f32 v[30:31], v[30:31], v[56:57]
	v_rcp_f32_e32 v64, v66
	v_pk_fma_f32 v[56:57], v[30:31], s[22:23], v[20:21] op_sel_hi:[1,0,0]
	v_rcp_f32_e32 v65, v67
	v_mul_f32_e32 v9, 0x4b800000, v57
	v_cmp_gt_f32_e32 vcc, s13, v57
	v_rcp_f32_e32 v66, v68
	v_rcp_f32_e32 v67, v69
	v_cndmask_b32_e32 v9, v57, v9, vcc
	v_rsq_f32_e32 v9, v9
	v_rcp_f32_e32 v68, v70
	v_rcp_f32_e32 v69, v71
	v_pk_mul_f32 v[52:53], v[60:61], v[52:53]
	v_mul_f32_e32 v29, 0x45800000, v9
	v_cndmask_b32_e32 v30, v9, v29, vcc
	v_pk_mul_f32 v[48:49], v[48:49], v[30:31] op_sel_hi:[1,0]
	v_pk_mul_f32 v[32:33], v[32:33], v[30:31] op_sel_hi:[1,0]
	v_pk_mul_f32 v[42:43], v[42:43], v[30:31] op_sel_hi:[1,0]
	v_pk_mul_f32 v[24:25], v[24:25], v[30:31] op_sel_hi:[1,0]
	v_pk_mul_f32 v[40:41], v[64:65], v[40:41]
	v_pk_mul_f32 v[54:55], v[66:67], v[54:55]
	v_pk_mul_f32 v[34:35], v[68:69], v[34:35]
	v_pk_mul_f32 v[4:5], v[4:5], v[48:49]
	v_pk_mul_f32 v[6:7], v[6:7], v[32:33]
	v_pk_mul_f32 v[0:1], v[0:1], v[42:43]
	v_pk_mul_f32 v[2:3], v[2:3], v[24:25]
	v_pk_mul_f32 v[4:5], v[54:55], v[4:5]
	v_pk_mul_f32 v[6:7], v[40:41], v[6:7]
	v_pk_mul_f32 v[24:25], v[52:53], v[0:1]
	v_pk_mul_f32 v[30:31], v[34:35], v[2:3]
	v_cvt_pk_bf16_f32 v0, v4, v5
	v_cvt_pk_bf16_f32 v1, v6, v7
	v_cvt_pk_bf16_f32 v2, v24, v25
	v_cvt_pk_bf16_f32 v3, v30, v31
	global_store_dwordx4 v[22:23], v[0:3], off
	global_load_dwordx4 v[0:3], v[50:51], off
	s_nop 0
	global_load_dwordx4 v[4:7], v[14:15], off
	global_load_dwordx4 v[30:33], v[14:15], off offset:16
	v_cmp_lt_i32_e32 vcc, s24, v8
	s_or_b64 s[18:19], vcc, s[18:19]
	v_mul_f32_e32 v9, 0x4b800000, v56
	v_cmp_gt_f32_e32 vcc, s13, v56
	s_waitcnt vmcnt(2)
	v_and_b32_e32 v29, 0xffff0000, v0
	v_cndmask_b32_e32 v9, v56, v9, vcc
	v_rsq_f32_e32 v9, v9
	v_lshlrev_b32_e32 v42, 16, v2
	v_and_b32_e32 v43, 0xffff0000, v2
	v_mul_f32_e32 v24, 0x45800000, v9
	v_cndmask_b32_e32 v24, v9, v24, vcc
	v_pk_mul_f32 v[34:35], v[44:45], v[24:25] op_sel_hi:[1,0]
	v_pk_mul_f32 v[36:37], v[36:37], v[24:25] op_sel_hi:[1,0]
	v_pk_mul_f32 v[40:41], v[46:47], v[24:25] op_sel_hi:[1,0]
	v_pk_mul_f32 v[24:25], v[38:39], v[24:25] op_sel_hi:[1,0]
	v_lshlrev_b32_e32 v9, 16, v0
	v_lshlrev_b32_e32 v38, 16, v1
	v_and_b32_e32 v39, 0xffff0000, v1
	v_lshlrev_b32_e32 v44, 16, v3
	v_and_b32_e32 v45, 0xffff0000, v3
	s_waitcnt vmcnt(1)
	v_pk_mul_f32 v[0:1], v[4:5], v[34:35]
	v_pk_mul_f32 v[2:3], v[6:7], v[36:37]
	s_waitcnt vmcnt(0)
	v_pk_mul_f32 v[4:5], v[30:31], v[40:41]
	v_pk_mul_f32 v[6:7], v[32:33], v[24:25]
	v_mul_f32_e32 v9, 0xbfb8aa3b, v9
	v_mul_f32_e32 v24, 0xbfb8aa3b, v29
	v_mul_f32_e32 v25, 0xbfb8aa3b, v38
	v_mul_f32_e32 v29, 0xbfb8aa3b, v39
	v_mul_f32_e32 v30, 0xbfb8aa3b, v42
	v_mul_f32_e32 v31, 0xbfb8aa3b, v43
	v_mul_f32_e32 v32, 0xbfb8aa3b, v44
	v_mul_f32_e32 v33, 0xbfb8aa3b, v45
	v_exp_f32_e32 v9, v9
	v_exp_f32_e32 v24, v24
	v_exp_f32_e32 v25, v25
	v_exp_f32_e32 v29, v29
	v_exp_f32_e32 v30, v30
	v_exp_f32_e32 v31, v31
	v_exp_f32_e32 v32, v32
	v_exp_f32_e32 v33, v33
	v_add_f32_e32 v9, 1.0, v9
	v_add_f32_e32 v34, 1.0, v24
	v_add_f32_e32 v35, 1.0, v25
	v_add_f32_e32 v29, 1.0, v29
	v_add_f32_e32 v36, 1.0, v30
	v_add_f32_e32 v37, 1.0, v31
	v_add_f32_e32 v38, 1.0, v32
	v_add_f32_e32 v39, 1.0, v33
	v_rcp_f32_e32 v24, v9
	v_rcp_f32_e32 v25, v34
	v_rcp_f32_e32 v30, v35
	v_rcp_f32_e32 v31, v29
	v_rcp_f32_e32 v32, v36
	v_rcp_f32_e32 v33, v37
	v_rcp_f32_e32 v34, v38
	v_rcp_f32_e32 v35, v39
	v_pk_mul_f32 v[0:1], v[24:25], v[0:1]
	v_pk_mul_f32 v[2:3], v[30:31], v[2:3]
	v_pk_mul_f32 v[4:5], v[32:33], v[4:5]
	v_pk_mul_f32 v[6:7], v[34:35], v[6:7]
	v_cvt_pk_bf16_f32 v0, v0, v1
	v_cvt_pk_bf16_f32 v1, v2, v3
	v_cvt_pk_bf16_f32 v2, v4, v5
	v_cvt_pk_bf16_f32 v3, v6, v7
	global_store_dwordx4 v[22:23], v[0:3], off offset:1024
	s_andn2_b64 exec, exec, s[18:19]
	s_cbranch_execnz .LBB0_653

; DI float bflo(unsigned u) { return __uint_as_float(u << 16); }
; DI float bfhi(unsigned u) { return __uint_as_float(u & 0xffff0000u); }
; DI void norm_rows_b(const Params& p) {
;     ...
;     for (int row0 = gw; row0 < NLAT; row0 += 4 * NGW) {
;         u32x4 v[4][2];
; #pragma unroll
;         for (int u = 0; u < 4; ++u)
; #pragma unroll
;             for (int j = 0; j < 2; ++j) v[u][j] = *(const u32x4*)(X1 + (size_t)(row0 + u * NGW) * DM + 8 * lane + 512 * j);
; #pragma unroll
;         for (int u = 0; u < 4; ++u) {
;             const int row = row0 + u * NGW;
;             float f[2][8]; float s = 0.f;
; #pragma unroll
;             for (int j = 0; j < 2; ++j) { const u32x4 q = v[u][j];
;                 f[j][0] = bflo(q.x); f[j][1] = bfhi(q.x); f[j][2] = bflo(q.y); f[j][3] = bfhi(q.y); f[j][4] = bflo(q.z); f[j][5] = bfhi(q.z); f[j][6] = bflo(q.w); f[j][7] = bfhi(q.w);
; #pragma unroll
;                 for (int e = 0; e < 8; ++e) s += f[j][e] * f[j][e]; }
;             const float rstd = rsqrtf(wave_sum(s) * (1.f / DM) + EPS);
.LBB0_786:
	v_lshl_add_u64 v[20:21], v[42:43], 0, v[38:39]
	v_add_u32_e32 v22, s23, v18
	v_add_u32_e32 v24, s24, v18
	v_ashrrev_i32_e32 v19, 12, v18
	v_add_u32_e32 v28, s21, v18
	v_add_co_u32_e32 v18, vcc, 0x3437a000, v20
	v_mul_hi_i32_i24_e32 v27, 0x6000, v19
	v_mul_i32_i24_e32 v26, 0x6000, v19
	v_addc_co_u32_e32 v19, vcc, 0, v21, vcc
	v_lshl_add_u64 v[16:17], v[40:41], 0, v[38:39]
	v_add_co_u32_e64 v72, s[4:5], s38, v20
	global_load_dwordx4 v[54:57], v[18:19], off
	global_load_dwordx4 v[62:65], v[18:19], off offset:1024
	v_ashrrev_i32_e32 v23, 31, v22
	v_ashrrev_i32_e32 v25, 31, v24
	v_addc_co_u32_e64 v73, s[4:5], 0, v21, s[4:5]
	v_ashrrev_i32_e32 v29, 12, v28
	v_add_u32_e32 v85, s21, v28
	v_add_co_u32_e32 v28, vcc, s25, v16
	v_mov_b32_e32 v45, v33
	v_add_co_u32_e64 v66, s[4:5], s38, v16
	v_lshlrev_b64 v[20:21], 11, v[22:23]
	v_lshlrev_b64 v[48:49], 11, v[24:25]
	v_lshl_add_u64 v[22:23], s[30:31], 0, v[26:27]
	v_mul_hi_i32_i24_e32 v25, 0x6000, v29
	v_mul_i32_i24_e32 v24, 0x6000, v29
	v_ashrrev_i32_e32 v16, 12, v85
	v_addc_co_u32_e32 v29, vcc, 0, v17, vcc
	v_addc_co_u32_e64 v67, s[4:5], 0, v17, s[4:5]
	v_lshl_add_u64 v[26:27], v[34:35], 0, v[20:21]
	v_lshl_add_u64 v[30:31], v[34:35], 0, v[48:49]
	v_lshl_add_u64 v[50:51], v[22:23], 0, v[44:45]
	v_mul_hi_i32_i24_e32 v59, 0x6000, v16
	v_mul_i32_i24_e32 v58, 0x6000, v16
	v_lshl_add_u64 v[52:53], v[36:37], 0, v[20:21]
	global_load_dwordx4 v[68:71], v[28:29], off
	global_load_dwordx4 v[74:77], v[28:29], off offset:1024
	global_load_dwordx4 v[80:83], v[26:27], off
	global_load_dwordx4 v[20:23], v[26:27], off offset:1024
	global_load_dwordx4 v[136:139], v[30:31], off
	global_load_dwordx4 v[16:19], v[30:31], off offset:1024
	v_lshl_add_u64 v[122:123], v[50:51], 0, s[16:17]
	v_lshl_add_u64 v[124:125], v[50:51], 0, s[18:19]
	v_add_co_u32_e32 v50, vcc, s36, v50
	v_lshl_add_u64 v[24:25], s[30:31], 0, v[24:25]
	s_nop 0
	v_addc_co_u32_e32 v51, vcc, 0, v51, vcc
	v_lshl_add_u64 v[78:79], v[24:25], 0, v[44:45]
	global_load_dwordx4 v[24:27], v[50:51], off offset:-4096
	global_load_dwordx4 v[140:143], v[50:51], off
	global_load_dwordx4 v[28:31], v[122:123], off offset:16
	global_load_dwordx4 v[144:147], v[124:125], off offset:16
	v_add_co_u32_e32 v116, vcc, s36, v78
	v_lshl_add_u64 v[96:97], v[78:79], 0, s[16:17]
	v_lshl_add_u64 v[98:99], v[78:79], 0, s[18:19]
	v_addc_co_u32_e32 v117, vcc, 0, v79, vcc
	v_lshl_add_u64 v[58:59], s[30:31], 0, v[58:59]
	v_lshl_add_u64 v[50:51], v[58:59], 0, v[44:45]
	v_mov_b64_e32 v[46:47], s[22:23]
	v_add_co_u32_e32 v94, vcc, s36, v50
	v_lshl_add_u64 v[90:91], v[50:51], 0, s[16:17]
	s_nop 0
	v_addc_co_u32_e32 v95, vcc, 0, v51, vcc
	v_lshl_add_u64 v[92:93], v[50:51], 0, s[18:19]
	v_mov_b32_e32 v61, v33
	v_lshl_add_u64 v[40:41], v[40:41], 0, s[12:13]
	v_lshl_add_u64 v[42:43], v[42:43], 0, s[12:13]
	s_waitcnt vmcnt(0)
	v_and_b32_e32 v157, 0xffff0000, v54
	v_and_b32_e32 v148, 0xffff0000, v64
	v_and_b32_e32 v32, 0xffff0000, v65
	v_lshlrev_b32_e32 v111, 16, v54
	v_lshlrev_b32_e32 v151, 16, v64
	v_lshlrev_b32_e32 v153, 16, v65
	v_lshlrev_b32_e32 v115, 16, v55
	v_mov_b32_e32 v150, v148
	v_mov_b32_e32 v152, v32
	v_and_b32_e32 v155, 0xffff0000, v55
	v_lshlrev_b32_e32 v101, 16, v62
	v_and_b32_e32 v107, 0xffff0000, v62
	v_lshlrev_b32_e32 v103, 16, v63
	v_and_b32_e32 v105, 0xffff0000, v63
	v_lshlrev_b32_e32 v109, 16, v56
	v_mov_b32_e32 v166, v111
	v_mov_b32_e32 v167, v157
	v_and_b32_e32 v121, 0xffff0000, v56
	v_lshlrev_b32_e32 v113, 16, v57
	v_and_b32_e32 v119, 0xffff0000, v57
	v_mov_b32_e32 v164, v115
	v_mov_b32_e32 v165, v155
	v_mov_b32_e32 v168, v113
	v_mov_b32_e32 v169, v119
	v_and_b32_e32 v156, 0xffff0000, v68
	v_lshlrev_b32_e32 v110, 16, v68
	v_and_b32_e32 v158, 0xffff0000, v76
	v_and_b32_e32 v60, 0xffff0000, v77
	v_pk_mul_f32 v[172:173], v[156:157], v[156:157]
	v_lshlrev_b32_e32 v114, 16, v69
	v_lshlrev_b32_e32 v161, 16, v76
	v_lshlrev_b32_e32 v163, 16, v77
	v_mov_b32_e32 v160, v158
	v_mov_b32_e32 v162, v60
	v_pk_fma_f32 v[172:173], v[110:111], v[110:111], v[172:173]
	v_and_b32_e32 v154, 0xffff0000, v69
	v_lshlrev_b32_e32 v108, 16, v70
	v_and_b32_e32 v120, 0xffff0000, v70
	v_lshlrev_b32_e32 v112, 16, v71
	v_and_b32_e32 v118, 0xffff0000, v71
	v_lshlrev_b32_e32 v100, 16, v74
	v_and_b32_e32 v106, 0xffff0000, v74
	v_lshlrev_b32_e32 v102, 16, v75
	v_and_b32_e32 v104, 0xffff0000, v75
	v_lshlrev_b32_e32 v63, 16, v82
	v_and_b32_e32 v75, 0xffff0000, v81
	v_and_b32_e32 v74, 0xffff0000, v137
	v_lshlrev_b32_e32 v62, 16, v138
	v_lshlrev_b32_e32 v69, 16, v80
	v_lshlrev_b32_e32 v68, 16, v136
	v_and_b32_e32 v79, 0xffff0000, v80
	v_and_b32_e32 v78, 0xffff0000, v136
	v_lshlrev_b32_e32 v71, 16, v81
	v_lshlrev_b32_e32 v70, 16, v137
	v_and_b32_e32 v81, 0xffff0000, v82
	v_and_b32_e32 v80, 0xffff0000, v138
	v_lshlrev_b32_e32 v76, 16, v139
	v_and_b32_e32 v82, 0xffff0000, v139
	v_pk_mul_f32 v[136:137], v[150:151], v[150:151]
	v_pk_mul_f32 v[138:139], v[152:153], v[152:153]
	v_pk_mul_f32 v[184:185], v[160:161], v[160:161]
	v_pk_mul_f32 v[186:187], v[162:163], v[162:163]
	v_pk_fma_f32 v[172:173], v[114:115], v[114:115], v[172:173]
	v_mov_b32_e32 v157, v137
	v_mov_b32_e32 v137, v139
	v_mov_b32_e32 v111, v156
	v_mov_b32_e32 v156, v185
	v_mov_b32_e32 v185, v136
	v_mov_b32_e32 v136, v187
	v_mov_b32_e32 v187, v138
	v_pk_fma_f32 v[138:139], v[154:155], v[154:155], v[172:173]
	v_mov_b32_e32 v115, v154
	v_pk_fma_f32 v[138:139], v[108:109], v[108:109], v[138:139]
	v_lshlrev_b32_e32 v55, 16, v20
	v_pk_fma_f32 v[138:139], v[120:121], v[120:121], v[138:139]
	v_and_b32_e32 v57, 0xffff0000, v20
	v_pk_fma_f32 v[138:139], v[112:113], v[112:113], v[138:139]
	v_lshlrev_b32_e32 v58, 16, v17
	v_pk_fma_f32 v[138:139], v[118:119], v[118:119], v[138:139]
	v_and_b32_e32 v20, 0xffff0000, v17
	v_pk_fma_f32 v[138:139], v[100:101], v[100:101], v[138:139]
	v_and_b32_e32 v84, 0xffff0000, v22
	v_pk_fma_f32 v[138:139], v[106:107], v[106:107], v[138:139]
	v_lshlrev_b32_e32 v89, 16, v22
	v_pk_fma_f32 v[138:139], v[102:103], v[102:103], v[138:139]
	v_and_b32_e32 v22, 0xffff0000, v18
	v_pk_fma_f32 v[138:139], v[104:105], v[104:105], v[138:139]
	v_lshlrev_b32_e32 v51, 16, v18
	v_pk_add_f32 v[138:139], v[156:157], v[138:139]
	v_mov_b32_e32 v170, v109
	v_pk_add_f32 v[138:139], v[184:185], v[138:139]
	v_mov_b32_e32 v171, v121
	v_pk_add_f32 v[136:137], v[136:137], v[138:139]
	v_pk_add_f32 v[142:143], v[142:143], 1.0 op_sel_hi:[1,0]
	v_pk_add_f32 v[136:137], v[186:187], v[136:137]
	s_nop 1
	v_mov_b32_dpp v139, v137 quad_perm:[1,0,3,2] row_mask:0xf bank_mask:0xf
	s_nop 1
	v_mov_b32_dpp v138, v136 quad_perm:[1,0,3,2] row_mask:0xf bank_mask:0xf
	v_pk_add_f32 v[140:141], v[140:141], 1.0 op_sel_hi:[1,0]
	v_pk_add_f32 v[146:147], v[146:147], 1.0 op_sel_hi:[1,0]
	v_pk_add_f32 v[144:145], v[144:145], 1.0 op_sel_hi:[1,0]
	v_and_b32_e32 v149, s0, v65
	s_waitcnt lgkmcnt(0)
; DI unsigned pk2(float a, float b) { f32x2 v = {a, b}; bf16x2_t r = __builtin_convertvector(v, bf16x2_t); return __builtin_bit_cast(unsigned, r); }
; DI float bflo(unsigned u) { return __uint_as_float(u << 16); }
; DI float bfhi(unsigned u) { return __uint_as_float(u & 0xffff0000u); }
; DI void norm_rows_b(const Params& p) {
;     ...
;         for (int u = 0; u < 4; ++u) {
;             const int row = row0 + u * NGW;
;             float f[2][8]; float s = 0.f;
; #pragma unroll
;             for (int j = 0; j < 2; ++j) { const u32x4 q = v[u][j];
;                 f[j][0] = bflo(q.x); f[j][1] = bfhi(q.x); f[j][2] = bflo(q.y); f[j][3] = bfhi(q.y); f[j][4] = bflo(q.z); f[j][5] = bfhi(q.z); f[j][6] = bflo(q.w); f[j][7] = bfhi(q.w);
; #pragma unroll
;                 for (int e = 0; e < 8; ++e) s += f[j][e] * f[j][e]; }
;             const float rstd = rsqrtf(wave_sum(s) * (1.f / DM) + EPS);
;             const float* mrow = modp + (size_t)(row >> 12) * NMODC + 3072;
; #pragma unroll
;             for (int j = 0; j < 2; ++j) {
;                 const f32x4 sh0 = *(const f32x4*)(mrow + 8 * lane + 512 * j), sh1 = *(const f32x4*)(mrow + 8 * lane + 512 * j + 4);
;                 const f32x4 sc0 = *(const f32x4*)(mrow + 1024 + 8 * lane + 512 * j), sc1 = *(const f32x4*)(mrow + 1024 + 8 * lane + 512 * j + 4);
;                 const f32x4 x0 = {f[j][0], f[j][1], f[j][2], f[j][3]}, x1 = {f[j][4], f[j][5], f[j][6], f[j][7]};
;                 const f32x4 y0 = (x0 * rstd * gn[j][0]) * (sc0 + 1.f) + sh0, y1 = (x1 * rstd * gn[j][1]) * (sc1 + 1.f) + sh1;
;                 u32x4 o; o.x = pk2(y0.x, y0.y); o.y = pk2(y0.z, y0.w); o.z = pk2(y1.x, y1.y); o.w = pk2(y1.z, y1.w);
;                 *(u32x4*)(H2 + (size_t)row * DM + 8 * lane + 512 * j) = o;
;             }
	v_pk_add_f32 v[136:137], v[136:137], v[138:139]
	s_nop 1
	v_mov_b32_dpp v139, v137 quad_perm:[2,3,0,1] row_mask:0xf bank_mask:0xf
	s_nop 1
	v_mov_b32_dpp v138, v136 quad_perm:[2,3,0,1] row_mask:0xf bank_mask:0xf
	v_pk_mov_b32 v[148:149], v[150:151], v[148:149] op_sel:[1,0]
	v_pk_mul_f32 v[150:151], v[78:79], v[78:79]
	v_mov_b32_e32 v126, v103
	v_mov_b32_e32 v127, v105
	s_waitcnt lgkmcnt(0)
	v_pk_add_f32 v[136:137], v[136:137], v[138:139]
	s_nop 1
	v_mov_b32_dpp v139, v137 row_half_mirror row_mask:0xf bank_mask:0xf
	s_nop 1
	v_mov_b32_dpp v138, v136 row_half_mirror row_mask:0xf bank_mask:0xf
	v_mov_b32_e32 v128, v101
	v_mov_b32_e32 v129, v107
	v_pk_mov_b32 v[152:153], v[152:153], v[32:33] op_sel:[1,0]
	v_pk_fma_f32 v[150:151], v[68:69], v[68:69], v[150:151]
	s_waitcnt lgkmcnt(0)
	v_pk_add_f32 v[136:137], v[136:137], v[138:139]
	s_nop 1
	v_mov_b32_dpp v139, v137 row_ror:8 row_mask:0xf bank_mask:0xf
	s_nop 1
	v_mov_b32_dpp v138, v136 row_ror:8 row_mask:0xf bank_mask:0xf
	v_mov_b32_e32 v109, v120
	v_mov_b32_e32 v113, v118
	v_and_b32_e32 v159, s0, v77
	v_pk_mov_b32 v[60:61], v[162:163], v[60:61] op_sel:[1,0]
	s_waitcnt lgkmcnt(0)
	v_pk_add_f32 v[136:137], v[136:137], v[138:139]
	ds_bpermute_b32 v139, v134, v137
	ds_bpermute_b32 v138, v134, v136
	v_pk_mov_b32 v[158:159], v[160:161], v[158:159] op_sel:[1,0]
	v_mov_b32_e32 v101, v106
	v_mov_b32_e32 v103, v104
	v_lshlrev_b32_e32 v77, 16, v83
	s_waitcnt lgkmcnt(0)
	v_pk_add_f32 v[136:137], v[136:137], v[138:139]
	ds_bpermute_b32 v139, v135, v137
	ds_bpermute_b32 v138, v135, v136
	v_and_b32_e32 v83, 0xffff0000, v83
	v_lshlrev_b32_e32 v54, 16, v16
	v_and_b32_e32 v56, 0xffff0000, v16
	v_lshlrev_b32_e32 v59, 16, v21
	s_waitcnt lgkmcnt(0)
	v_pk_add_f32 v[136:137], v[136:137], v[138:139]
	v_mov_b32_e32 v88, v84
	v_pk_fma_f32 v[154:155], v[136:137], s[20:21], v[46:47] op_sel_hi:[1,0,0]
	v_mov_b32_e32 v50, v22
	v_mul_f32_e32 v17, 0x4b800000, v155
	v_cmp_gt_f32_e32 vcc, s37, v155
	v_and_b32_e32 v21, 0xffff0000, v21
	v_and_b32_e32 v16, 0xffff0000, v19
	v_cndmask_b32_e32 v17, v155, v17, vcc
	v_rsq_f32_e32 v17, v17
	v_and_b32_e32 v32, 0xffff0000, v23
	v_pk_mul_f32 v[160:161], v[88:89], v[88:89]
	v_pk_mul_f32 v[162:163], v[50:51], v[50:51]
	v_mul_f32_e32 v18, 0x45800000, v17
	v_cndmask_b32_e32 v18, v17, v18, vcc
	v_pk_mul_f32 v[136:137], v[164:165], v[18:19] op_sel_hi:[1,0]
	v_pk_mul_f32 v[138:139], v[166:167], v[18:19] op_sel_hi:[1,0]
	v_pk_mul_f32 v[156:157], v[168:169], v[18:19] op_sel_hi:[1,0]
	v_pk_mul_f32 v[164:165], v[170:171], v[18:19] op_sel_hi:[1,0]
	v_pk_mul_f32 v[138:139], v[4:5], v[138:139]
	v_pk_mul_f32 v[136:137], v[6:7], v[136:137]
	v_pk_mul_f32 v[164:165], v[0:1], v[164:165]
	v_pk_mul_f32 v[156:157], v[2:3], v[156:157]
	v_pk_fma_f32 v[26:27], v[142:143], v[136:137], v[26:27]
	v_pk_fma_f32 v[24:25], v[140:141], v[138:139], v[24:25]
	v_pk_fma_f32 v[30:31], v[146:147], v[156:157], v[30:31]
	v_pk_fma_f32 v[28:29], v[144:145], v[164:165], v[28:29]
	v_cvt_pk_bf16_f32 v24, v24, v25
	v_cvt_pk_bf16_f32 v25, v26, v27
	v_cvt_pk_bf16_f32 v26, v28, v29
	v_cvt_pk_bf16_f32 v27, v30, v31
	global_store_dwordx4 v[72:73], v[24:27], off
	global_load_dwordx4 v[24:27], v[124:125], off offset:2048
	s_nop 0
	global_load_dwordx4 v[28:31], v[124:125], off offset:2064
	global_load_dwordx4 v[136:139], v[122:123], off offset:2048
	s_nop 0
	global_load_dwordx4 v[122:125], v[122:123], off offset:2064
	v_pk_fma_f32 v[142:143], v[70:71], v[70:71], v[150:151]
	v_pk_mul_f32 v[126:127], v[126:127], v[18:19] op_sel_hi:[1,0]
	v_pk_mul_f32 v[128:129], v[128:129], v[18:19] op_sel_hi:[1,0]
	v_pk_mul_f32 v[150:151], v[18:19], v[152:153] op_sel_hi:[0,1]
	v_pk_mul_f32 v[148:149], v[18:19], v[148:149] op_sel_hi:[0,1]
	v_pk_mul_f32 v[128:129], v[12:13], v[128:129]
	v_pk_mul_f32 v[126:127], v[14:15], v[126:127]
	v_pk_mul_f32 v[148:149], v[8:9], v[148:149]
	v_pk_mul_f32 v[150:151], v[10:11], v[150:151]
	v_mul_f32_e32 v17, 0x4b800000, v154
	v_cmp_gt_f32_e32 vcc, s37, v154
	v_pk_fma_f32 v[142:143], v[74:75], v[74:75], v[142:143]
	v_lshlrev_b32_e32 v87, 16, v23
	v_cndmask_b32_e32 v17, v154, v17, vcc
	v_rsq_f32_e32 v17, v17
	v_lshlrev_b32_e32 v65, 16, v19
	v_mov_b32_e32 v64, v16
	v_mov_b32_e32 v86, v32
	v_mul_f32_e32 v18, 0x45800000, v17
	v_cndmask_b32_e32 v18, v17, v18, vcc
	v_pk_mul_f32 v[114:115], v[114:115], v[18:19] op_sel_hi:[1,0]
	v_pk_mul_f32 v[110:111], v[110:111], v[18:19] op_sel_hi:[1,0]
	v_pk_mul_f32 v[112:113], v[112:113], v[18:19] op_sel_hi:[1,0]
	v_pk_mul_f32 v[108:109], v[108:109], v[18:19] op_sel_hi:[1,0]
	v_pk_mul_f32 v[110:111], v[4:5], v[110:111]
	v_pk_mul_f32 v[114:115], v[6:7], v[114:115]
	v_pk_mul_f32 v[108:109], v[0:1], v[108:109]
	v_pk_mul_f32 v[112:113], v[2:3], v[112:113]
	v_pk_mul_f32 v[102:103], v[102:103], v[18:19] op_sel_hi:[1,0]
	v_pk_mul_f32 v[100:101], v[100:101], v[18:19] op_sel_hi:[1,0]
	v_pk_mul_f32 v[60:61], v[18:19], v[60:61] op_sel_hi:[0,1]
	v_pk_mul_f32 v[106:107], v[18:19], v[158:159] op_sel_hi:[0,1]
	v_pk_mul_f32 v[100:101], v[12:13], v[100:101]
	v_pk_mul_f32 v[102:103], v[14:15], v[102:103]
	v_pk_mul_f32 v[106:107], v[8:9], v[106:107]
	v_pk_mul_f32 v[60:61], v[10:11], v[60:61]
	v_mov_b32_e32 v144, v163
	v_mov_b32_e32 v145, v161
	v_pk_mul_f32 v[188:189], v[64:65], v[64:65]
	v_pk_mul_f32 v[140:141], v[86:87], v[86:87]
	v_mov_b32_e32 v163, v160
	v_mov_b32_e32 v146, v189
	v_mov_b32_e32 v147, v141
	v_mov_b32_e32 v189, v140
	v_mov_b32_e32 v174, v71
	v_mov_b32_e32 v175, v75
	v_mov_b32_e32 v176, v69
	v_mov_b32_e32 v177, v79
	v_mov_b32_e32 v178, v77
	v_mov_b32_e32 v179, v83
	v_mov_b32_e32 v182, v63
	v_mov_b32_e32 v183, v81
	v_add_u32_e32 v75, s21, v85
	v_and_b32_e32 v85, s0, v23
	v_pk_mov_b32 v[84:85], v[88:89], v[84:85] op_sel:[1,0]
	v_pk_mov_b32 v[86:87], v[86:87], v[32:33] op_sel:[1,0]
	v_mov_b32_e32 v69, v78
	v_mov_b32_e32 v71, v74
	v_and_b32_e32 v23, s0, v19
	v_pk_mov_b32 v[22:23], v[50:51], v[22:23] op_sel:[1,0]
	s_waitcnt vmcnt(3)
; DI unsigned pk2(float a, float b) { f32x2 v = {a, b}; bf16x2_t r = __builtin_convertvector(v, bf16x2_t); return __builtin_bit_cast(unsigned, r); }
; DI float bflo(unsigned u) { return __uint_as_float(u << 16); }
; DI float bfhi(unsigned u) { return __uint_as_float(u & 0xffff0000u); }
; DI void norm_rows_b(const Params& p) {
;     ...
;         for (int u = 0; u < 4; ++u) {
;             const int row = row0 + u * NGW;
;             float f[2][8]; float s = 0.f;
; #pragma unroll
;             for (int j = 0; j < 2; ++j) { const u32x4 q = v[u][j];
;                 f[j][0] = bflo(q.x); f[j][1] = bfhi(q.x); f[j][2] = bflo(q.y); f[j][3] = bfhi(q.y); f[j][4] = bflo(q.z); f[j][5] = bfhi(q.z); f[j][6] = bflo(q.w); f[j][7] = bfhi(q.w);
; #pragma unroll
;                 for (int e = 0; e < 8; ++e) s += f[j][e] * f[j][e]; }
;             const float rstd = rsqrtf(wave_sum(s) * (1.f / DM) + EPS);
;     ...
; #pragma unroll
;             for (int j = 0; j < 2; ++j) {
;                 const f32x4 sh0 = *(const f32x4*)(mrow + 8 * lane + 512 * j), sh1 = *(const f32x4*)(mrow + 8 * lane + 512 * j + 4);
;                 const f32x4 sc0 = *(const f32x4*)(mrow + 1024 + 8 * lane + 512 * j), sc1 = *(const f32x4*)(mrow + 1024 + 8 * lane + 512 * j + 4);
;                 const f32x4 x0 = {f[j][0], f[j][1], f[j][2], f[j][3]}, x1 = {f[j][4], f[j][5], f[j][6], f[j][7]};
;                 const f32x4 y0 = (x0 * rstd * gn[j][0]) * (sc0 + 1.f) + sh0, y1 = (x1 * rstd * gn[j][1]) * (sc1 + 1.f) + sh1;
;                 u32x4 o; o.x = pk2(y0.x, y0.y); o.y = pk2(y0.z, y0.w); o.z = pk2(y1.x, y1.y); o.w = pk2(y1.z, y1.w);
;                 *(u32x4*)(H2 + (size_t)row * DM + 8 * lane + 512 * j) = o;
;             }
	v_pk_add_f32 v[26:27], v[26:27], 1.0 op_sel_hi:[1,0]
	v_pk_add_f32 v[24:25], v[24:25], 1.0 op_sel_hi:[1,0]
	s_waitcnt vmcnt(2)
	v_pk_add_f32 v[30:31], v[30:31], 1.0 op_sel_hi:[1,0]
	v_pk_add_f32 v[28:29], v[28:29], 1.0 op_sel_hi:[1,0]
	s_waitcnt vmcnt(1)
	v_pk_fma_f32 v[26:27], v[26:27], v[126:127], v[138:139]
	v_pk_fma_f32 v[24:25], v[24:25], v[128:129], v[136:137]
	s_waitcnt vmcnt(0)
	v_pk_fma_f32 v[30:31], v[30:31], v[150:151], v[124:125]
	v_pk_fma_f32 v[28:29], v[28:29], v[148:149], v[122:123]
	v_cvt_pk_bf16_f32 v24, v24, v25
	v_cvt_pk_bf16_f32 v25, v26, v27
	v_cvt_pk_bf16_f32 v26, v28, v29
	v_cvt_pk_bf16_f32 v27, v30, v31
	global_store_dwordx4 v[72:73], v[24:27], off offset:1024
	global_load_dwordx4 v[24:27], v[116:117], off
	s_nop 0
	global_load_dwordx4 v[28:31], v[98:99], off offset:16
	global_load_dwordx4 v[122:125], v[116:117], off offset:-4096
	global_load_dwordx4 v[126:129], v[96:97], off offset:16
	v_pk_fma_f32 v[72:73], v[62:63], v[62:63], v[142:143]
	v_mov_b32_e32 v63, v80
	v_pk_fma_f32 v[72:73], v[80:81], v[80:81], v[72:73]
	s_waitcnt vmcnt(3)
	v_pk_add_f32 v[26:27], v[26:27], 1.0 op_sel_hi:[1,0]
	v_pk_add_f32 v[24:25], v[24:25], 1.0 op_sel_hi:[1,0]
	s_waitcnt vmcnt(2)
	v_pk_add_f32 v[30:31], v[30:31], 1.0 op_sel_hi:[1,0]
	v_pk_add_f32 v[28:29], v[28:29], 1.0 op_sel_hi:[1,0]
	s_waitcnt vmcnt(1)
	v_pk_fma_f32 v[26:27], v[26:27], v[114:115], v[124:125]
	v_pk_fma_f32 v[24:25], v[24:25], v[110:111], v[122:123]
	s_waitcnt vmcnt(0)
	v_pk_fma_f32 v[30:31], v[30:31], v[112:113], v[128:129]
	v_pk_fma_f32 v[28:29], v[28:29], v[108:109], v[126:127]
	v_cvt_pk_bf16_f32 v24, v24, v25
	v_cvt_pk_bf16_f32 v25, v26, v27
	v_cvt_pk_bf16_f32 v26, v28, v29
	v_cvt_pk_bf16_f32 v27, v30, v31
	global_store_dwordx4 v[66:67], v[24:27], off
	global_load_dwordx4 v[24:27], v[98:99], off offset:2048
	s_nop 0
	global_load_dwordx4 v[28:31], v[98:99], off offset:2064
	global_load_dwordx4 v[108:111], v[96:97], off offset:2048
	s_nop 0
	global_load_dwordx4 v[96:99], v[96:97], off offset:2064
	v_pk_fma_f32 v[72:73], v[76:77], v[76:77], v[72:73]
	v_mov_b32_e32 v77, v82
	v_pk_fma_f32 v[72:73], v[82:83], v[82:83], v[72:73]
	s_waitcnt vmcnt(3)
	v_pk_add_f32 v[26:27], v[26:27], 1.0 op_sel_hi:[1,0]
	v_pk_add_f32 v[24:25], v[24:25], 1.0 op_sel_hi:[1,0]
	s_waitcnt vmcnt(2)
	v_pk_add_f32 v[30:31], v[30:31], 1.0 op_sel_hi:[1,0]
	v_pk_add_f32 v[28:29], v[28:29], 1.0 op_sel_hi:[1,0]
	s_waitcnt vmcnt(1)
	v_pk_fma_f32 v[26:27], v[26:27], v[102:103], v[110:111]
	v_pk_fma_f32 v[24:25], v[24:25], v[100:101], v[108:109]
	s_waitcnt vmcnt(0)
	v_pk_fma_f32 v[30:31], v[30:31], v[60:61], v[98:99]
	v_pk_fma_f32 v[28:29], v[28:29], v[106:107], v[96:97]
	v_cvt_pk_bf16_f32 v24, v24, v25
	v_cvt_pk_bf16_f32 v25, v26, v27
	v_cvt_pk_bf16_f32 v26, v28, v29
	v_cvt_pk_bf16_f32 v27, v30, v31
	global_store_dwordx4 v[66:67], v[24:27], off offset:1024
	global_load_dwordx4 v[24:27], v[94:95], off
	s_nop 0
	global_load_dwordx4 v[28:31], v[92:93], off offset:16
	global_load_dwordx4 v[96:99], v[94:95], off offset:-4096
	global_load_dwordx4 v[100:103], v[90:91], off offset:16
	v_pk_fma_f32 v[72:73], v[54:55], v[54:55], v[72:73]
	s_waitcnt vmcnt(3)
	v_pk_add_f32 v[26:27], v[26:27], 1.0 op_sel_hi:[1,0]
	v_pk_fma_f32 v[72:73], v[56:57], v[56:57], v[72:73]
	v_pk_add_f32 v[24:25], v[24:25], 1.0 op_sel_hi:[1,0]
	v_pk_fma_f32 v[72:73], v[58:59], v[58:59], v[72:73]
	s_waitcnt vmcnt(2)
	v_pk_add_f32 v[30:31], v[30:31], 1.0 op_sel_hi:[1,0]
	v_pk_fma_f32 v[72:73], v[20:21], v[20:21], v[72:73]
	v_pk_add_f32 v[28:29], v[28:29], 1.0 op_sel_hi:[1,0]
	v_pk_add_f32 v[72:73], v[144:145], v[72:73]
	s_nop 0
	v_pk_add_f32 v[72:73], v[162:163], v[72:73]
	s_nop 0
	v_pk_add_f32 v[72:73], v[146:147], v[72:73]
	s_nop 0
	v_pk_add_f32 v[72:73], v[188:189], v[72:73]
	s_nop 1
	v_mov_b32_dpp v105, v73 quad_perm:[1,0,3,2] row_mask:0xf bank_mask:0xf
	s_nop 1
	v_mov_b32_dpp v104, v72 quad_perm:[1,0,3,2] row_mask:0xf bank_mask:0xf
	s_waitcnt lgkmcnt(0)
	v_pk_add_f32 v[72:73], v[72:73], v[104:105]
	s_nop 1
	v_mov_b32_dpp v105, v73 quad_perm:[2,3,0,1] row_mask:0xf bank_mask:0xf
	s_nop 1
	v_mov_b32_dpp v104, v72 quad_perm:[2,3,0,1] row_mask:0xf bank_mask:0xf
	s_waitcnt lgkmcnt(0)
	v_pk_add_f32 v[72:73], v[72:73], v[104:105]
	s_nop 1
	v_mov_b32_dpp v105, v73 row_half_mirror row_mask:0xf bank_mask:0xf
	s_nop 1
	v_mov_b32_dpp v104, v72 row_half_mirror row_mask:0xf bank_mask:0xf
	s_waitcnt lgkmcnt(0)
	v_pk_add_f32 v[60:61], v[72:73], v[104:105]
	s_nop 1
	v_mov_b32_dpp v67, v61 row_ror:8 row_mask:0xf bank_mask:0xf
	s_nop 1
	v_mov_b32_dpp v66, v60 row_ror:8 row_mask:0xf bank_mask:0xf
	s_waitcnt lgkmcnt(0)
	v_pk_add_f32 v[60:61], v[60:61], v[66:67]
	ds_bpermute_b32 v67, v134, v61
	ds_bpermute_b32 v66, v134, v60
	s_waitcnt lgkmcnt(0)
	v_pk_add_f32 v[60:61], v[60:61], v[66:67]
	ds_bpermute_b32 v67, v135, v61
	ds_bpermute_b32 v66, v135, v60
	s_waitcnt lgkmcnt(0)
	v_pk_add_f32 v[60:61], v[60:61], v[66:67]
	s_nop 0
	v_pk_fma_f32 v[46:47], v[60:61], s[20:21], v[46:47] op_sel_hi:[1,0,0]
	s_nop 0
	v_mul_f32_e32 v17, 0x4b800000, v47
	v_cmp_gt_f32_e32 vcc, s37, v47
	s_nop 1
	v_cndmask_b32_e32 v17, v47, v17, vcc
	v_rsq_f32_e32 v17, v17
	s_nop 0
	v_mul_f32_e32 v18, 0x45800000, v17
	v_cndmask_b32_e32 v18, v17, v18, vcc
	v_pk_mul_f32 v[60:61], v[174:175], v[18:19] op_sel_hi:[1,0]
	v_pk_mul_f32 v[66:67], v[176:177], v[18:19] op_sel_hi:[1,0]
	v_pk_mul_f32 v[72:73], v[178:179], v[18:19] op_sel_hi:[1,0]
	v_pk_mul_f32 v[94:95], v[182:183], v[18:19] op_sel_hi:[1,0]
	v_pk_mul_f32 v[66:67], v[4:5], v[66:67]
	v_pk_mul_f32 v[60:61], v[6:7], v[60:61]
	v_pk_mul_f32 v[94:95], v[0:1], v[94:95]
	v_pk_mul_f32 v[72:73], v[2:3], v[72:73]
	s_waitcnt vmcnt(1)
; DI unsigned pk2(float a, float b) { f32x2 v = {a, b}; bf16x2_t r = __builtin_convertvector(v, bf16x2_t); return __builtin_bit_cast(unsigned, r); }
; DI void norm_rows_b(const Params& p) {
;     ...
; #pragma unroll
;             for (int j = 0; j < 2; ++j) {
;                 const f32x4 sh0 = *(const f32x4*)(mrow + 8 * lane + 512 * j), sh1 = *(const f32x4*)(mrow + 8 * lane + 512 * j + 4);
;                 const f32x4 sc0 = *(const f32x4*)(mrow + 1024 + 8 * lane + 512 * j), sc1 = *(const f32x4*)(mrow + 1024 + 8 * lane + 512 * j + 4);
;                 const f32x4 x0 = {f[j][0], f[j][1], f[j][2], f[j][3]}, x1 = {f[j][4], f[j][5], f[j][6], f[j][7]};
;                 const f32x4 y0 = (x0 * rstd * gn[j][0]) * (sc0 + 1.f) + sh0, y1 = (x1 * rstd * gn[j][1]) * (sc1 + 1.f) + sh1;
;                 u32x4 o; o.x = pk2(y0.x, y0.y); o.y = pk2(y0.z, y0.w); o.z = pk2(y1.x, y1.y); o.w = pk2(y1.z, y1.w);
;                 *(u32x4*)(H2 + (size_t)row * DM + 8 * lane + 512 * j) = o;
;             }
	v_pk_fma_f32 v[26:27], v[26:27], v[60:61], v[98:99]
	v_pk_fma_f32 v[24:25], v[24:25], v[66:67], v[96:97]
	s_waitcnt vmcnt(0)
	v_pk_fma_f32 v[30:31], v[30:31], v[72:73], v[102:103]
	v_pk_fma_f32 v[28:29], v[28:29], v[94:95], v[100:101]
	v_cvt_pk_bf16_f32 v24, v24, v25
	v_cvt_pk_bf16_f32 v25, v26, v27
	v_cvt_pk_bf16_f32 v26, v28, v29
	v_cvt_pk_bf16_f32 v27, v30, v31
	global_store_dwordx4 v[52:53], v[24:27], off
	global_load_dwordx4 v[24:27], v[92:93], off offset:2048
	s_nop 0
	global_load_dwordx4 v[28:31], v[92:93], off offset:2064
	global_load_dwordx4 v[94:97], v[90:91], off offset:2048
	global_load_dwordx4 v[98:101], v[90:91], off offset:2064
	v_ashrrev_i32_e32 v17, 12, v75
	v_mov_b32_e32 v90, v59
	v_mov_b32_e32 v91, v21
	v_mov_b32_e32 v92, v55
	v_mov_b32_e32 v93, v57
	v_mul_hi_i32_i24_e32 v61, 0x6000, v17
	v_mul_i32_i24_e32 v60, 0x6000, v17
	v_pk_mul_f32 v[88:89], v[90:91], v[18:19] op_sel_hi:[1,0]
	v_pk_mul_f32 v[90:91], v[92:93], v[18:19] op_sel_hi:[1,0]
	v_pk_mul_f32 v[86:87], v[18:19], v[86:87] op_sel_hi:[0,1]
	v_pk_mul_f32 v[84:85], v[18:19], v[84:85] op_sel_hi:[0,1]
	v_lshl_add_u64 v[60:61], s[30:31], 0, v[60:61]
	v_pk_mul_f32 v[90:91], v[12:13], v[90:91]
	v_pk_mul_f32 v[88:89], v[14:15], v[88:89]
	v_pk_mul_f32 v[84:85], v[8:9], v[84:85]
	v_pk_mul_f32 v[86:87], v[10:11], v[86:87]
	v_lshl_add_u64 v[60:61], v[60:61], 0, v[44:45]
	v_lshl_add_u64 v[66:67], v[60:61], 0, s[16:17]
	v_lshl_add_u64 v[72:73], v[60:61], 0, s[18:19]
	v_add_co_u32_e32 v60, vcc, s36, v60
	v_mul_f32_e32 v17, 0x4b800000, v46
	s_nop 0
	v_addc_co_u32_e32 v61, vcc, 0, v61, vcc
	v_cmp_gt_f32_e32 vcc, s37, v46
	v_mov_b32_e32 v55, v56
	v_mov_b32_e32 v59, v20
	v_cndmask_b32_e32 v17, v46, v17, vcc
	v_rsq_f32_e32 v17, v17
	s_waitcnt vmcnt(3)
	v_pk_add_f32 v[26:27], v[26:27], 1.0 op_sel_hi:[1,0]
	v_pk_add_f32 v[24:25], v[24:25], 1.0 op_sel_hi:[1,0]
	s_waitcnt vmcnt(2)
	v_pk_add_f32 v[30:31], v[30:31], 1.0 op_sel_hi:[1,0]
	v_pk_add_f32 v[28:29], v[28:29], 1.0 op_sel_hi:[1,0]
	s_waitcnt vmcnt(1)
	v_pk_fma_f32 v[26:27], v[26:27], v[88:89], v[96:97]
	v_pk_fma_f32 v[24:25], v[24:25], v[90:91], v[94:95]
	s_waitcnt vmcnt(0)
	v_pk_fma_f32 v[30:31], v[30:31], v[86:87], v[100:101]
	v_pk_fma_f32 v[28:29], v[28:29], v[84:85], v[98:99]
	v_cvt_pk_bf16_f32 v24, v24, v25
	v_cvt_pk_bf16_f32 v25, v26, v27
	v_cvt_pk_bf16_f32 v26, v28, v29
	v_cvt_pk_bf16_f32 v27, v30, v31
	global_store_dwordx4 v[52:53], v[24:27], off offset:1024
	global_load_dwordx4 v[24:27], v[60:61], off
	s_nop 0
	global_load_dwordx4 v[28:31], v[72:73], off offset:16
	global_load_dwordx4 v[84:87], v[60:61], off offset:-4096
	global_load_dwordx4 v[88:91], v[66:67], off offset:16
	v_mul_f32_e32 v18, 0x45800000, v17
	v_cndmask_b32_e32 v32, v17, v18, vcc
	v_lshl_add_u64 v[52:53], v[36:37], 0, v[48:49]
	v_pk_mul_f32 v[46:47], v[70:71], v[32:33] op_sel_hi:[1,0]
	v_pk_mul_f32 v[48:49], v[68:69], v[32:33] op_sel_hi:[1,0]
	v_pk_mul_f32 v[60:61], v[76:77], v[32:33] op_sel_hi:[1,0]
	v_pk_mul_f32 v[62:63], v[62:63], v[32:33] op_sel_hi:[1,0]
	v_pk_mul_f32 v[48:49], v[4:5], v[48:49]
	v_pk_mul_f32 v[46:47], v[6:7], v[46:47]
	v_pk_mul_f32 v[62:63], v[0:1], v[62:63]
	v_pk_mul_f32 v[60:61], v[2:3], v[60:61]
	v_mov_b32_e32 v17, v33
	v_pk_mov_b32 v[16:17], v[64:65], v[16:17] op_sel:[1,0]
	v_pk_mul_f32 v[20:21], v[58:59], v[32:33] op_sel_hi:[1,0]
	v_pk_mul_f32 v[50:51], v[54:55], v[32:33] op_sel_hi:[1,0]
	v_pk_mul_f32 v[16:17], v[32:33], v[16:17] op_sel_hi:[0,1]
	v_pk_mul_f32 v[22:23], v[32:33], v[22:23] op_sel_hi:[0,1]
	v_add_u32_e32 v18, s21, v75
	v_pk_mul_f32 v[50:51], v[12:13], v[50:51]
	v_pk_mul_f32 v[20:21], v[14:15], v[20:21]
	v_pk_mul_f32 v[22:23], v[8:9], v[22:23]
	v_pk_mul_f32 v[16:17], v[10:11], v[16:17]
	v_cmp_lt_i32_e32 vcc, s39, v18
	s_or_b64 s[14:15], vcc, s[14:15]
	s_waitcnt vmcnt(3)
	v_pk_add_f32 v[26:27], v[26:27], 1.0 op_sel_hi:[1,0]
	v_pk_add_f32 v[24:25], v[24:25], 1.0 op_sel_hi:[1,0]
	s_waitcnt vmcnt(2)
	v_pk_add_f32 v[30:31], v[30:31], 1.0 op_sel_hi:[1,0]
	v_pk_add_f32 v[28:29], v[28:29], 1.0 op_sel_hi:[1,0]
	s_waitcnt vmcnt(1)
	v_pk_fma_f32 v[26:27], v[26:27], v[46:47], v[86:87]
	v_pk_fma_f32 v[24:25], v[24:25], v[48:49], v[84:85]
	s_waitcnt vmcnt(0)
	v_pk_fma_f32 v[30:31], v[30:31], v[60:61], v[90:91]
	v_pk_fma_f32 v[28:29], v[28:29], v[62:63], v[88:89]
	v_cvt_pk_bf16_f32 v24, v24, v25
	v_cvt_pk_bf16_f32 v25, v26, v27
	v_cvt_pk_bf16_f32 v26, v28, v29
	v_cvt_pk_bf16_f32 v27, v30, v31
	global_store_dwordx4 v[52:53], v[24:27], off
	global_load_dwordx4 v[24:27], v[72:73], off offset:2048
	s_nop 0
	global_load_dwordx4 v[28:31], v[72:73], off offset:2064
	global_load_dwordx4 v[46:49], v[66:67], off offset:2048
	global_load_dwordx4 v[60:63], v[66:67], off offset:2064
	s_waitcnt vmcnt(3)
	v_pk_add_f32 v[26:27], v[26:27], 1.0 op_sel_hi:[1,0]
	v_pk_add_f32 v[24:25], v[24:25], 1.0 op_sel_hi:[1,0]
	s_waitcnt vmcnt(2)
	v_pk_add_f32 v[30:31], v[30:31], 1.0 op_sel_hi:[1,0]
	v_pk_add_f32 v[28:29], v[28:29], 1.0 op_sel_hi:[1,0]
	s_waitcnt vmcnt(1)
	v_pk_fma_f32 v[26:27], v[26:27], v[20:21], v[48:49]
	v_pk_fma_f32 v[20:21], v[24:25], v[50:51], v[46:47]
	s_waitcnt vmcnt(0)
	v_pk_fma_f32 v[16:17], v[30:31], v[16:17], v[62:63]
	v_pk_fma_f32 v[22:23], v[28:29], v[22:23], v[60:61]
	v_cvt_pk_bf16_f32 v20, v20, v21
	v_cvt_pk_bf16_f32 v21, v26, v27
	v_cvt_pk_bf16_f32 v22, v22, v23
	v_cvt_pk_bf16_f32 v23, v16, v17
	global_store_dwordx4 v[52:53], v[20:23], off offset:1024
	s_andn2_b64 exec, exec, s[14:15]
	s_cbranch_execnz .LBB0_786

; DI float bflo(unsigned u) { return __uint_as_float(u << 16); }
; DI float bfhi(unsigned u) { return __uint_as_float(u & 0xffff0000u); }
; DI void final_norm_b(const Params& p) {
;     ...
;     for (int row0 = gw; row0 < NLAT; row0 += 4 * NGW) {
;         u32x4 v[4][2];
; #pragma unroll
;         for (int u = 0; u < 4; ++u)
; #pragma unroll
;             for (int j = 0; j < 2; ++j) v[u][j] = *(const u32x4*)(X2 + (size_t)(row0 + u * NGW) * DM + 8 * lane + 512 * j);
; #pragma unroll
;         for (int u = 0; u < 4; ++u) {
;             const int row = row0 + u * NGW;
;             f32x4 f[2][2]; float s = 0.f;
; #pragma unroll
;             for (int j = 0; j < 2; ++j) { const u32x4 q = v[u][j];
;                 f[j][0] = (f32x4){bflo(q.x), bfhi(q.x), bflo(q.y), bfhi(q.y)}; f[j][1] = (f32x4){bflo(q.z), bfhi(q.z), bflo(q.w), bfhi(q.w)};
;                 s += (f[j][0].x * f[j][0].x + f[j][0].y * f[j][0].y) + (f[j][0].z * f[j][0].z + f[j][0].w * f[j][0].w) + (f[j][1].x * f[j][1].x + f[j][1].y * f[j][1].y) + (f[j][1].z * f[j][1].z + f[j][1].w * f[j][1].w); }
;             const float rstd = rsqrtf(wave_sum(s) * (1.f / DM) + EPS);
.LBB0_990:
	v_ashrrev_i32_e32 v45, 31, v44
	v_lshlrev_b64 v[22:23], 11, v[44:45]
	v_lshl_add_u64 v[22:23], v[16:17], 0, v[22:23]
	global_load_dwordx4 v[26:29], v[22:23], off offset:1024
	global_load_dwordx4 v[30:33], v[22:23], off
	v_add_u32_e32 v22, s12, v44
	v_ashrrev_i32_e32 v23, 31, v22
	v_lshlrev_b64 v[24:25], 11, v[22:23]
	v_lshl_add_u64 v[24:25], v[16:17], 0, v[24:25]
	global_load_dwordx4 v[38:41], v[24:25], off offset:1024
	global_load_dwordx4 v[52:55], v[24:25], off
	v_add_u32_e32 v24, s13, v44
	v_ashrrev_i32_e32 v25, 31, v24
	s_waitcnt vmcnt(0)
	v_and_b32_e32 v71, 0xffff0000, v26
	v_and_b32_e32 v70, 0xffff0000, v30
	v_and_b32_e32 v75, 0xffff0000, v27
	v_and_b32_e32 v74, 0xffff0000, v31
	v_and_b32_e32 v79, 0xffff0000, v28
	v_and_b32_e32 v78, 0xffff0000, v32
	v_and_b32_e32 v83, 0xffff0000, v29
	v_and_b32_e32 v82, 0xffff0000, v33
	v_lshlrev_b32_e32 v69, 16, v26
	v_lshlrev_b32_e32 v68, 16, v30
	v_lshlrev_b32_e32 v73, 16, v27
	v_lshlrev_b32_e32 v72, 16, v31
	v_lshlrev_b32_e32 v77, 16, v28
	v_lshlrev_b32_e32 v76, 16, v32
	v_lshlrev_b32_e32 v81, 16, v29
	v_lshlrev_b32_e32 v80, 16, v33
	v_pk_mul_f32 v[26:27], v[70:71], v[70:71]
	v_pk_mul_f32 v[56:57], v[74:75], v[74:75]
	v_pk_mul_f32 v[58:59], v[78:79], v[78:79]
	v_pk_mul_f32 v[60:61], v[82:83], v[82:83]
	v_and_b32_e32 v29, 0xffff0000, v38
	v_and_b32_e32 v28, 0xffff0000, v52
	v_and_b32_e32 v43, 0xffff0000, v39
	v_and_b32_e32 v42, 0xffff0000, v53
	v_lshlrev_b32_e32 v35, 16, v38
	v_lshlrev_b32_e32 v34, 16, v52
	v_lshlrev_b32_e32 v37, 16, v39
	v_lshlrev_b32_e32 v36, 16, v53
	v_lshlrev_b32_e32 v31, 16, v40
	v_lshlrev_b32_e32 v30, 16, v54
	v_and_b32_e32 v39, 0xffff0000, v40
	v_and_b32_e32 v38, 0xffff0000, v54
	v_lshlrev_b32_e32 v32, 16, v55
	v_and_b32_e32 v40, 0xffff0000, v55
	v_pk_fma_f32 v[26:27], v[68:69], v[68:69], v[26:27]
	v_pk_fma_f32 v[52:53], v[72:73], v[72:73], v[56:57]
	v_pk_fma_f32 v[54:55], v[76:77], v[76:77], v[58:59]
	v_pk_fma_f32 v[56:57], v[80:81], v[80:81], v[60:61]
	v_pk_mul_f32 v[58:59], v[28:29], v[28:29]
	v_pk_mul_f32 v[60:61], v[42:43], v[42:43]
	v_lshlrev_b32_e32 v33, 16, v41
	v_and_b32_e32 v41, 0xffff0000, v41
	v_pk_mul_f32 v[62:63], v[38:39], v[38:39]
	v_pk_add_f32 v[26:27], v[26:27], v[52:53]
	v_pk_fma_f32 v[52:53], v[34:35], v[34:35], v[58:59]
	v_pk_fma_f32 v[58:59], v[36:37], v[36:37], v[60:61]
	v_pk_mul_f32 v[64:65], v[40:41], v[40:41]
	v_pk_fma_f32 v[60:61], v[30:31], v[30:31], v[62:63]
	v_pk_add_f32 v[52:53], v[52:53], v[58:59]
	v_pk_fma_f32 v[62:63], v[32:33], v[32:33], v[64:65]
	v_pk_add_f32 v[26:27], v[54:55], v[26:27]
	v_pk_add_f32 v[52:53], v[60:61], v[52:53]
	v_pk_add_f32 v[26:27], v[56:57], v[26:27]
	v_pk_add_f32 v[52:53], v[62:63], v[52:53]
	v_mov_b32_e32 v55, v26
	v_mov_b32_e32 v54, v52
	v_mov_b32_e32 v26, v53
	v_pk_add_f32 v[26:27], v[54:55], v[26:27]
	s_nop 1
	v_mov_b32_dpp v61, v27 quad_perm:[1,0,3,2] row_mask:0xf bank_mask:0xf
	s_nop 1
	v_mov_b32_dpp v60, v26 quad_perm:[1,0,3,2] row_mask:0xf bank_mask:0xf
	v_lshlrev_b64 v[52:53], 11, v[24:25]
	v_lshl_add_u64 v[62:63], v[16:17], 0, v[52:53]
	global_load_dwordx4 v[52:55], v[62:63], off offset:1024
	global_load_dwordx4 v[56:59], v[62:63], off
	v_mov_b32_e32 v90, v72
	s_waitcnt lgkmcnt(0)
	v_pk_add_f32 v[60:61], v[26:27], v[60:61]
	s_nop 1
	v_mov_b32_dpp v63, v61 quad_perm:[2,3,0,1] row_mask:0xf bank_mask:0xf
	s_nop 1
	v_mov_b32_dpp v62, v60 quad_perm:[2,3,0,1] row_mask:0xf bank_mask:0xf
	v_add_u32_e32 v26, s14, v44
	v_ashrrev_i32_e32 v27, 31, v26
	v_lshlrev_b64 v[64:65], 11, v[26:27]
	v_lshl_add_u64 v[88:89], v[16:17], 0, v[64:65]
	s_waitcnt lgkmcnt(0)
	v_pk_add_f32 v[84:85], v[60:61], v[62:63]
	global_load_dwordx4 v[60:63], v[88:89], off
	global_load_dwordx4 v[64:67], v[88:89], off offset:1024
	s_nop 1
	v_mov_b32_dpp v87, v85 row_half_mirror row_mask:0xf bank_mask:0xf
	s_nop 1
	v_mov_b32_dpp v86, v84 row_half_mirror row_mask:0xf bank_mask:0xf
	v_mov_b32_e32 v88, v68
	v_mov_b32_e32 v89, v70
	v_mov_b32_e32 v70, v69
	v_mov_b32_e32 v91, v74
	s_waitcnt lgkmcnt(0)
	v_pk_add_f32 v[84:85], v[84:85], v[86:87]
	s_nop 1
	v_mov_b32_dpp v87, v85 row_ror:8 row_mask:0xf bank_mask:0xf
	s_nop 1
	v_mov_b32_dpp v86, v84 row_ror:8 row_mask:0xf bank_mask:0xf
	v_lshlrev_b64 v[44:45], 12, v[44:45]
	v_mov_b32_e32 v92, v76
	v_mov_b32_e32 v93, v78
	v_mov_b32_e32 v94, v80
	s_waitcnt lgkmcnt(0)
	v_pk_add_f32 v[84:85], v[84:85], v[86:87]
	ds_bpermute_b32 v87, v50, v85
	ds_bpermute_b32 v86, v50, v84
	v_mov_b32_e32 v95, v82
	v_mov_b32_e32 v74, v73
	v_mov_b32_e32 v78, v77
	v_mov_b32_e32 v82, v81
	s_waitcnt lgkmcnt(0)
	v_pk_add_f32 v[84:85], v[84:85], v[86:87]
	ds_bpermute_b32 v87, v51, v85
	ds_bpermute_b32 v86, v51, v84
	v_lshl_add_u64 v[44:45], v[18:19], 0, v[44:45]
	v_lshlrev_b64 v[24:25], 12, v[24:25]
	v_lshl_add_u64 v[24:25], v[18:19], 0, v[24:25]
	s_waitcnt lgkmcnt(0)
	v_pk_add_f32 v[68:69], v[84:85], v[86:87]
	s_nop 0
	v_pk_fma_f32 v[68:69], v[68:69], s[8:9], v[20:21] op_sel_hi:[1,0,0]
	s_waitcnt vmcnt(0)
; DI float bflo(unsigned u) { return __uint_as_float(u << 16); }
; DI float bfhi(unsigned u) { return __uint_as_float(u & 0xffff0000u); }
; DI void final_norm_b(const Params& p) {
;     ...
;         for (int u = 0; u < 4; ++u) {
;             const int row = row0 + u * NGW;
;             f32x4 f[2][2]; float s = 0.f;
; #pragma unroll
;             for (int j = 0; j < 2; ++j) { const u32x4 q = v[u][j];
;                 f[j][0] = (f32x4){bflo(q.x), bfhi(q.x), bflo(q.y), bfhi(q.y)}; f[j][1] = (f32x4){bflo(q.z), bfhi(q.z), bflo(q.w), bfhi(q.w)};
;                 s += (f[j][0].x * f[j][0].x + f[j][0].y * f[j][0].y) + (f[j][0].z * f[j][0].z + f[j][0].w * f[j][0].w) + (f[j][1].x * f[j][1].x + f[j][1].y * f[j][1].y) + (f[j][1].z * f[j][1].z + f[j][1].w * f[j][1].w); }
;             const float rstd = rsqrtf(wave_sum(s) * (1.f / DM) + EPS);
;             float* dst = p.out + (size_t)row * DM + 8 * lane;
; #pragma unroll
;             for (int j = 0; j < 2; ++j) { *(f32x4*)(dst + 512 * j) = f[j][0] * rstd * gn[j][0]; *(f32x4*)(dst + 512 * j + 4) = f[j][1] * rstd * gn[j][1]; }
	v_and_b32_e32 v97, 0xffff0000, v67
	v_mul_f32_e32 v72, 0x4b800000, v69
	v_cmp_gt_f32_e32 vcc, s15, v69
	v_cmp_gt_f32_e64 s[0:1], s15, v68
	s_nop 0
	v_cndmask_b32_e32 v69, v69, v72, vcc
	v_rsq_f32_e32 v69, v69
	v_mul_f32_e32 v72, 0x4b800000, v68
	v_cndmask_b32_e64 v96, v68, v72, s[0:1]
	v_mul_f32_e32 v68, 0x45800000, v69
	v_cndmask_b32_e32 v68, v69, v68, vcc
	v_pk_mul_f32 v[72:73], v[88:89], v[68:69] op_sel_hi:[1,0]
	v_pk_mul_f32 v[76:77], v[90:91], v[68:69] op_sel_hi:[1,0]
	v_pk_mul_f32 v[86:87], v[70:71], v[68:69] op_sel_hi:[1,0]
	v_pk_mul_f32 v[80:81], v[92:93], v[68:69] op_sel_hi:[1,0]
	v_pk_mul_f32 v[84:85], v[94:95], v[68:69] op_sel_hi:[1,0]
	v_pk_mul_f32 v[88:89], v[74:75], v[68:69] op_sel_hi:[1,0]
	v_pk_mul_f32 v[90:91], v[78:79], v[68:69] op_sel_hi:[1,0]
	v_pk_mul_f32 v[82:83], v[82:83], v[68:69] op_sel_hi:[1,0]
	v_pk_mul_f32 v[70:71], v[6:7], v[76:77]
	v_pk_mul_f32 v[68:69], v[4:5], v[72:73]
	v_pk_mul_f32 v[76:77], v[12:13], v[86:87]
	v_pk_mul_f32 v[74:75], v[2:3], v[84:85]
	v_pk_mul_f32 v[72:73], v[0:1], v[80:81]
	v_pk_mul_f32 v[78:79], v[14:15], v[88:89]
	global_store_dwordx4 v[44:45], v[68:71], off
	global_store_dwordx4 v[44:45], v[72:75], off offset:16
	global_store_dwordx4 v[44:45], v[76:79], off offset:2048
	v_and_b32_e32 v81, 0xffff0000, v53
	v_and_b32_e32 v80, 0xffff0000, v57
	v_and_b32_e32 v77, 0xffff0000, v52
	v_and_b32_e32 v76, 0xffff0000, v56
	v_pk_mul_f32 v[70:71], v[10:11], v[82:83]
	v_lshlrev_b32_e32 v75, 16, v52
	v_lshlrev_b32_e32 v74, 16, v56
	v_lshlrev_b32_e32 v79, 16, v53
	v_lshlrev_b32_e32 v78, 16, v57
	v_lshlrev_b32_e32 v57, 16, v54
	v_and_b32_e32 v83, 0xffff0000, v54
	v_lshlrev_b32_e32 v85, 16, v55
	v_and_b32_e32 v87, 0xffff0000, v55
	v_pk_mul_f32 v[52:53], v[76:77], v[76:77]
	v_pk_mul_f32 v[54:55], v[80:81], v[80:81]
	v_and_b32_e32 v82, 0xffff0000, v58
	v_pk_fma_f32 v[52:53], v[74:75], v[74:75], v[52:53]
	v_pk_fma_f32 v[54:55], v[78:79], v[78:79], v[54:55]
	v_lshlrev_b32_e32 v56, 16, v58
	v_pk_add_f32 v[52:53], v[52:53], v[54:55]
	v_pk_mul_f32 v[54:55], v[82:83], v[82:83]
	v_and_b32_e32 v86, 0xffff0000, v59
	v_pk_fma_f32 v[54:55], v[56:57], v[56:57], v[54:55]
	v_lshlrev_b32_e32 v84, 16, v59
	v_pk_add_f32 v[52:53], v[54:55], v[52:53]
	v_pk_mul_f32 v[54:55], v[86:87], v[86:87]
	v_pk_mul_f32 v[68:69], v[8:9], v[90:91]
	v_pk_fma_f32 v[54:55], v[84:85], v[84:85], v[54:55]
	v_lshlrev_b32_e32 v59, 16, v64
	v_and_b32_e32 v89, 0xffff0000, v64
	v_and_b32_e32 v88, 0xffff0000, v60
	v_lshlrev_b32_e32 v91, 16, v65
	v_and_b32_e32 v65, 0xffff0000, v65
	v_and_b32_e32 v64, 0xffff0000, v61
	v_rsq_f32_e32 v72, v96
	v_pk_add_f32 v[52:53], v[54:55], v[52:53]
	v_lshlrev_b32_e32 v58, 16, v60
	v_lshlrev_b32_e32 v90, 16, v61
	v_lshlrev_b32_e32 v60, 16, v62
	v_and_b32_e32 v92, 0xffff0000, v62
	v_lshlrev_b32_e32 v94, 16, v63
	v_and_b32_e32 v96, 0xffff0000, v63
	v_pk_mul_f32 v[54:55], v[88:89], v[88:89]
	v_pk_mul_f32 v[62:63], v[64:65], v[64:65]
	v_and_b32_e32 v93, 0xffff0000, v66
	v_pk_fma_f32 v[54:55], v[58:59], v[58:59], v[54:55]
	v_pk_fma_f32 v[62:63], v[90:91], v[90:91], v[62:63]
	v_lshlrev_b32_e32 v61, 16, v66
	v_pk_add_f32 v[54:55], v[54:55], v[62:63]
	v_pk_mul_f32 v[62:63], v[92:93], v[92:93]
	v_lshlrev_b32_e32 v95, 16, v67
	v_pk_fma_f32 v[62:63], v[60:61], v[60:61], v[62:63]
	global_store_dwordx4 v[44:45], v[68:71], off offset:2064
	v_pk_add_f32 v[54:55], v[62:63], v[54:55]
	v_pk_mul_f32 v[62:63], v[96:97], v[96:97]
	v_mul_f32_e32 v44, 0x45800000, v72
	v_pk_fma_f32 v[62:63], v[94:95], v[94:95], v[62:63]
	v_lshlrev_b64 v[68:69], 12, v[22:23]
	v_pk_add_f32 v[54:55], v[62:63], v[54:55]
	v_mov_b32_e32 v63, v52
	v_mov_b32_e32 v62, v54
	v_mov_b32_e32 v52, v55
	v_pk_add_f32 v[52:53], v[62:63], v[52:53]
	s_nop 1
	v_mov_b32_dpp v55, v53 quad_perm:[1,0,3,2] row_mask:0xf bank_mask:0xf
	s_nop 1
	v_mov_b32_dpp v54, v52 quad_perm:[1,0,3,2] row_mask:0xf bank_mask:0xf
	v_cndmask_b32_e64 v44, v72, v44, s[0:1]
	v_lshl_add_u64 v[70:71], v[18:19], 0, v[68:69]
	v_mov_b32_e32 v68, v34
	v_mov_b32_e32 v69, v28
	s_waitcnt lgkmcnt(0)
	v_pk_add_f32 v[52:53], v[52:53], v[54:55]
	s_nop 1
	v_mov_b32_dpp v55, v53 quad_perm:[2,3,0,1] row_mask:0xf bank_mask:0xf
	s_nop 1
	v_mov_b32_dpp v54, v52 quad_perm:[2,3,0,1] row_mask:0xf bank_mask:0xf
	v_pk_mul_f32 v[72:73], v[68:69], v[44:45] op_sel_hi:[1,0]
	v_mov_b32_e32 v68, v36
	v_mov_b32_e32 v69, v42
	v_pk_mul_f32 v[68:69], v[68:69], v[44:45] op_sel_hi:[1,0]
	v_pk_mul_f32 v[66:67], v[4:5], v[72:73]
	v_pk_mul_f32 v[68:69], v[6:7], v[68:69]
	global_store_dwordx4 v[70:71], v[66:69], off
	v_mov_b32_e32 v62, v30
	v_mov_b32_e32 v63, v38
	s_waitcnt lgkmcnt(0)
; DI void final_norm_b(const Params& p) {
;     ...
;             const float rstd = rsqrtf(wave_sum(s) * (1.f / DM) + EPS);
;             float* dst = p.out + (size_t)row * DM + 8 * lane;
; #pragma unroll
;             for (int j = 0; j < 2; ++j) { *(f32x4*)(dst + 512 * j) = f[j][0] * rstd * gn[j][0]; *(f32x4*)(dst + 512 * j + 4) = f[j][1] * rstd * gn[j][1]; }
;         }
	v_pk_add_f32 v[68:69], v[52:53], v[54:55]
	s_nop 1
	v_mov_b32_dpp v73, v69 row_half_mirror row_mask:0xf bank_mask:0xf
	s_nop 1
	v_mov_b32_dpp v72, v68 row_half_mirror row_mask:0xf bank_mask:0xf
	v_mov_b32_e32 v66, v32
	v_mov_b32_e32 v67, v40
	v_pk_mul_f32 v[62:63], v[62:63], v[44:45] op_sel_hi:[1,0]
	v_pk_mul_f32 v[66:67], v[66:67], v[44:45] op_sel_hi:[1,0]
	v_pk_mul_f32 v[52:53], v[0:1], v[62:63]
	v_pk_mul_f32 v[54:55], v[2:3], v[66:67]
	v_mov_b32_e32 v28, v35
	s_waitcnt lgkmcnt(0)
	v_pk_add_f32 v[34:35], v[68:69], v[72:73]
	global_store_dwordx4 v[70:71], v[52:55], off offset:16
	s_nop 1
	v_mov_b32_dpp v53, v35 row_ror:8 row_mask:0xf bank_mask:0xf
	s_nop 1
	v_mov_b32_dpp v52, v34 row_ror:8 row_mask:0xf bank_mask:0xf
	v_mov_b32_e32 v42, v37
	v_pk_mul_f32 v[36:37], v[42:43], v[44:45] op_sel_hi:[1,0]
	v_pk_mul_f32 v[28:29], v[28:29], v[44:45] op_sel_hi:[1,0]
	v_pk_mul_f32 v[36:37], v[14:15], v[36:37]
	s_waitcnt lgkmcnt(0)
	v_pk_add_f32 v[42:43], v[34:35], v[52:53]
	ds_bpermute_b32 v53, v50, v43
	ds_bpermute_b32 v52, v50, v42
	v_pk_mul_f32 v[34:35], v[12:13], v[28:29]
	global_store_dwordx4 v[70:71], v[34:37], off offset:2048
	v_mov_b32_e32 v40, v33
	v_mov_b32_e32 v38, v31
	s_waitcnt lgkmcnt(0)
	v_pk_add_f32 v[34:35], v[42:43], v[52:53]
	ds_bpermute_b32 v37, v51, v35
	ds_bpermute_b32 v36, v51, v34
	v_pk_mul_f32 v[28:29], v[38:39], v[44:45] op_sel_hi:[1,0]
	v_pk_mul_f32 v[30:31], v[40:41], v[44:45] op_sel_hi:[1,0]
	v_pk_mul_f32 v[28:29], v[8:9], v[28:29]
	v_pk_mul_f32 v[30:31], v[10:11], v[30:31]
	s_waitcnt lgkmcnt(0)
	v_pk_add_f32 v[32:33], v[34:35], v[36:37]
	global_store_dwordx4 v[70:71], v[28:31], off offset:2064
	v_pk_fma_f32 v[32:33], v[32:33], s[8:9], v[20:21] op_sel_hi:[1,0,0]
	v_add_u32_e32 v44, s16, v22
	v_mul_f32_e32 v23, 0x4b800000, v33
	v_cmp_gt_f32_e32 vcc, s15, v33
	v_mov_b32_e32 v29, v76
	v_mov_b32_e32 v30, v78
	v_cndmask_b32_e32 v23, v33, v23, vcc
	v_rsq_f32_e32 v23, v23
	v_mov_b32_e32 v31, v80
	v_mov_b32_e32 v76, v75
	v_mov_b32_e32 v80, v79
	v_mul_f32_e32 v28, 0x45800000, v23
	v_cndmask_b32_e32 v34, v23, v28, vcc
	v_mov_b32_e32 v28, v74
	v_pk_mul_f32 v[28:29], v[28:29], v[34:35] op_sel_hi:[1,0]
	v_pk_mul_f32 v[30:31], v[30:31], v[34:35] op_sel_hi:[1,0]
	v_pk_mul_f32 v[28:29], v[4:5], v[28:29]
	v_pk_mul_f32 v[30:31], v[6:7], v[30:31]
	global_store_dwordx4 v[24:25], v[28:31], off
	v_mul_f32_e32 v23, 0x4b800000, v32
	v_cmp_gt_f32_e32 vcc, s15, v32
	v_mov_b32_e32 v28, v56
	v_mov_b32_e32 v29, v82
	v_mov_b32_e32 v30, v84
	v_mov_b32_e32 v31, v86
	v_pk_mul_f32 v[28:29], v[28:29], v[34:35] op_sel_hi:[1,0]
	v_pk_mul_f32 v[30:31], v[30:31], v[34:35] op_sel_hi:[1,0]
	v_pk_mul_f32 v[28:29], v[0:1], v[28:29]
	v_pk_mul_f32 v[30:31], v[2:3], v[30:31]
	v_cndmask_b32_e32 v23, v32, v23, vcc
	global_store_dwordx4 v[24:25], v[28:31], off offset:16
	v_rsq_f32_e32 v23, v23
	v_mov_b32_e32 v82, v57
	v_pk_mul_f32 v[28:29], v[76:77], v[34:35] op_sel_hi:[1,0]
	v_pk_mul_f32 v[30:31], v[80:81], v[34:35] op_sel_hi:[1,0]
	v_pk_mul_f32 v[28:29], v[12:13], v[28:29]
	v_pk_mul_f32 v[30:31], v[14:15], v[30:31]
	v_mov_b32_e32 v86, v85
	global_store_dwordx4 v[24:25], v[28:31], off offset:2048
	s_nop 1
	v_pk_mul_f32 v[28:29], v[82:83], v[34:35] op_sel_hi:[1,0]
	v_pk_mul_f32 v[30:31], v[86:87], v[34:35] op_sel_hi:[1,0]
	v_pk_mul_f32 v[28:29], v[8:9], v[28:29]
	v_pk_mul_f32 v[30:31], v[10:11], v[30:31]
	global_store_dwordx4 v[24:25], v[28:31], off offset:2064
	v_mul_f32_e32 v24, 0x45800000, v23
	s_nop 0
	v_cndmask_b32_e32 v28, v23, v24, vcc
	v_lshlrev_b64 v[24:25], 12, v[26:27]
	v_lshl_add_u64 v[30:31], v[18:19], 0, v[24:25]
	v_mov_b32_e32 v24, v58
	v_mov_b32_e32 v25, v88
	v_mov_b32_e32 v26, v90
	v_mov_b32_e32 v27, v64
	v_pk_mul_f32 v[24:25], v[24:25], v[28:29] op_sel_hi:[1,0]
	v_pk_mul_f32 v[26:27], v[26:27], v[28:29] op_sel_hi:[1,0]
	v_pk_mul_f32 v[24:25], v[4:5], v[24:25]
	v_pk_mul_f32 v[26:27], v[6:7], v[26:27]
	global_store_dwordx4 v[30:31], v[24:27], off
	v_mov_b32_e32 v88, v59
	v_mov_b32_e32 v64, v91
	v_mov_b32_e32 v24, v60
	v_mov_b32_e32 v25, v92
	v_mov_b32_e32 v26, v94
	v_mov_b32_e32 v27, v96
	v_pk_mul_f32 v[24:25], v[24:25], v[28:29] op_sel_hi:[1,0]
	v_pk_mul_f32 v[26:27], v[26:27], v[28:29] op_sel_hi:[1,0]
	v_pk_mul_f32 v[24:25], v[0:1], v[24:25]
	v_pk_mul_f32 v[26:27], v[2:3], v[26:27]
	global_store_dwordx4 v[30:31], v[24:27], off offset:16
	v_mov_b32_e32 v92, v61
	v_mov_b32_e32 v96, v95
	v_pk_mul_f32 v[24:25], v[88:89], v[28:29] op_sel_hi:[1,0]
	v_pk_mul_f32 v[26:27], v[64:65], v[28:29] op_sel_hi:[1,0]
	v_pk_mul_f32 v[24:25], v[12:13], v[24:25]
	v_pk_mul_f32 v[26:27], v[14:15], v[26:27]
	global_store_dwordx4 v[30:31], v[24:27], off offset:2048
	v_cmp_lt_i32_e32 vcc, s17, v44
	s_or_b64 s[6:7], vcc, s[6:7]
	v_pk_mul_f32 v[24:25], v[92:93], v[28:29] op_sel_hi:[1,0]
	v_pk_mul_f32 v[26:27], v[96:97], v[28:29] op_sel_hi:[1,0]
	v_pk_mul_f32 v[24:25], v[8:9], v[24:25]
	v_pk_mul_f32 v[26:27], v[10:11], v[26:27]
	global_store_dwordx4 v[30:31], v[24:27], off offset:2064
	s_andn2_b64 exec, exec, s[6:7]
	s_cbranch_execnz .LBB0_990
